# 32 redundant post-barrier lgkmcnt(0) waits removed from the GEMM MFMA segment heads
# speedup vs baseline: 1.0058x; 1.0041x over previous
; #define PG8_STAGE(bufoff, gbase, voff) do { _Pragma("unroll") for (int _i = 0; _i < 2; ++_i) \
;         __builtin_amdgcn_global_load_lds((const unsigned*)((const char*)(gbase) + (voff)[_i]), (PG8_LAS unsigned*)(lds + (bufoff) + ldsw + _i * 8192), 16, 0, 0); } while (0)
; #define PG8_LDA(dst, b, h) do { _Pragma("unroll") for (int m = 0; m < 4; ++m) _Pragma("unroll") for (int k = 0; k < 2; ++k) dst[m][k] = *(const PG8_LAS bf16x8*)(lds + PG8_SA(b, h) + aoff + m * 2048 + k * 1024); } while (0)
; #define PG8_LDB(dst, b, h) do { _Pragma("unroll") for (int n = 0; n < 2; ++n) _Pragma("unroll") for (int k = 0; k < 2; ++k) dst[n][k] = *(const PG8_LAS bf16x8*)(lds + PG8_SB(b, h) + boff + n * 2048 + k * 1024); } while (0)
; #define PG8_MMA(ai, bj, At, Bt) do { __builtin_amdgcn_s_setprio(1); _Pragma("unroll") for (int m = 0; m < 4; ++m) _Pragma("unroll") for (int n = 0; n < 2; ++n) _Pragma("unroll") for (int k = 0; k < 2; ++k) \
;         acc[ai][bj][m][n] = __builtin_amdgcn_mfma_f32_16x16x32_bf16(Bt[n][k], At[m][k], acc[ai][bj][m][n], 0, 0, 0); __builtin_amdgcn_s_setprio(0); } while (0)
; #define PG8_WAIT_V(n) asm volatile("s_waitcnt vmcnt(" #n ")" ::: "memory")
; #define PG8_WAIT_L(n) asm volatile("s_waitcnt lgkmcnt(" #n ")" ::: "memory")
; template <class Epi, class Sched, bool ALIGN_EPI = false, bool SP2 = false>
; __device__ __forceinline__ void gemm_phase(PG8_LAS unsigned char* lds, const Gemm g, const Sched& S, const Epi& E) {
;     ...
;             const bool last = (t == nt - 2);
;             const char* a1 = cA + (size_t)(t + 1) * kstep;
;             const char* a2 = last ? nA : cA + (size_t)(t + 2) * kstep; const char* b2 = last ? nB : cB + (size_t)(t + 2) * kstep;
;             const char* a3 = a2 + kstep; const char* b3 = b2 + kstep;
;             if (last && has_next) S.a_ready(nxt);
;             if constexpr (SP2) {
;             PG8_LDB(B0, 0, 0); PG8_LDB(B1, 0, 1); PG8_SCHED; PG8_LDA(At, 0, 0); PG8_STAGE(PG8_SA(1, 1), a1 + hstep, voffA);
;             PG8_WAIT_V(8); PG8_WAIT_L(0); PG8_BAR; PG8_MMA(0, 0, At, B0); PG8_MMA(0, 1, At, B1); PG8_BAR; PG8_SCHED;
;             PG8_LDA(At, 0, 1); PG8_STAGE(PG8_SB(0, 0), b2, voffB); PG8_STAGE(PG8_SB(0, 1), b2 + hstep, voffB); PG8_STAGE(PG8_SA(0, 0), a2, voffA);
;             PG8_WAIT_V(8); PG8_WAIT_L(0); PG8_BAR; PG8_MMA(1, 0, At, B0); PG8_MMA(1, 1, At, B1); PG8_BAR; PG8_SCHED;
.LBB0_128:
	s_add_u32 s40, vcc_lo, 0xfffc0080
	s_addc_u32 s41, vcc_hi, -1
	s_add_i32 s68, 0, 0x10000
	s_cmp_eq_u32 s60, 12
	s_cselect_b32 s57, s1, s41
	s_cselect_b32 s56, s3, s40
	v_add_u32_e32 v112, s68, v176
	s_cselect_b32 s41, s12, s61
	s_cselect_b32 s40, s13, s55
	s_add_i32 s70, 0, 0x14000
	ds_read_b128 v[130:133], v112
	ds_read_b128 v[134:137], v112 offset:1024
	ds_read_b128 v[152:155], v112 offset:2048
	ds_read_b128 v[156:159], v112 offset:3072
	v_add_u32_e32 v112, s70, v176
	ds_read_b128 v[160:163], v112
	ds_read_b128 v[164:167], v112 offset:1024
	ds_read_b128 v[168:171], v112 offset:2048
	ds_read_b128 v[172:175], v112 offset:3072
	v_lshl_add_u64 v[180:181], vcc, 0, v[148:149]
	s_add_i32 m0, s22, 0xc000
	ds_read_b128 v[200:203], v179
	ds_read_b128 v[204:207], v179 offset:1024
	ds_read_b128 v[208:211], v179 offset:2048
	ds_read_b128 v[222:225], v179 offset:3072
	ds_read_b128 v[226:229], v179 offset:4096
	ds_read_b128 v[230:233], v179 offset:5120
	ds_read_b128 v[234:237], v179 offset:6144
	ds_read_b128 v[238:241], v179 offset:7168
	global_load_lds_dwordx4 v[180:181], off
	v_lshl_add_u64 v[180:181], vcc, 0, v[150:151]
	s_add_i32 m0, s22, 0xe000
	s_nop 0
	global_load_lds_dwordx4 v[180:181], off
	s_waitcnt vmcnt(8)
	s_waitcnt lgkmcnt(0)
	s_barrier
	s_setprio 1
	v_mfma_f32_16x16x32_bf16 v[126:129], v[130:133], v[200:203], v[126:129]
	v_mfma_f32_16x16x32_bf16 v[122:125], v[152:155], v[200:203], v[122:125]
	v_mfma_f32_16x16x32_bf16 v[108:111], v[130:133], v[208:211], v[108:111]
	v_mfma_f32_16x16x32_bf16 v[104:107], v[152:155], v[208:211], v[104:107]
	v_mfma_f32_16x16x32_bf16 v[92:95], v[130:133], v[226:229], v[92:95]
	v_mfma_f32_16x16x32_bf16 v[88:91], v[152:155], v[226:229], v[88:91]
	v_mfma_f32_16x16x32_bf16 v[76:79], v[130:133], v[234:237], v[76:79]
	v_mfma_f32_16x16x32_bf16 v[72:75], v[152:155], v[234:237], v[72:75]
	v_mfma_f32_16x16x32_bf16 v[126:129], v[134:137], v[204:207], v[126:129]
	v_mfma_f32_16x16x32_bf16 v[122:125], v[156:159], v[204:207], v[122:125]
	v_mfma_f32_16x16x32_bf16 v[108:111], v[134:137], v[222:225], v[108:111]
	v_mfma_f32_16x16x32_bf16 v[104:107], v[156:159], v[222:225], v[104:107]
	v_mfma_f32_16x16x32_bf16 v[92:95], v[134:137], v[230:233], v[92:95]
	v_mfma_f32_16x16x32_bf16 v[88:91], v[156:159], v[230:233], v[88:91]
	v_mfma_f32_16x16x32_bf16 v[76:79], v[134:137], v[238:241], v[76:79]
	v_mfma_f32_16x16x32_bf16 v[72:75], v[156:159], v[238:241], v[72:75]
	s_setprio 0
	s_setprio 1
	v_mfma_f32_16x16x32_bf16 v[118:121], v[160:163], v[200:203], v[118:121]
	v_mfma_f32_16x16x32_bf16 v[114:117], v[168:171], v[200:203], v[114:117]
	v_mfma_f32_16x16x32_bf16 v[100:103], v[160:163], v[208:211], v[100:103]
	v_mfma_f32_16x16x32_bf16 v[96:99], v[168:171], v[208:211], v[96:99]
	v_mfma_f32_16x16x32_bf16 v[84:87], v[160:163], v[226:229], v[84:87]
	v_mfma_f32_16x16x32_bf16 v[80:83], v[168:171], v[226:229], v[80:83]
	v_mfma_f32_16x16x32_bf16 v[68:71], v[160:163], v[234:237], v[68:71]
	v_mfma_f32_16x16x32_bf16 v[64:67], v[168:171], v[234:237], v[64:67]
	v_mfma_f32_16x16x32_bf16 v[118:121], v[164:167], v[204:207], v[118:121]
	v_mfma_f32_16x16x32_bf16 v[114:117], v[172:175], v[204:207], v[114:117]
	v_mfma_f32_16x16x32_bf16 v[100:103], v[164:167], v[222:225], v[100:103]
	v_mfma_f32_16x16x32_bf16 v[96:99], v[172:175], v[222:225], v[96:99]
	v_mfma_f32_16x16x32_bf16 v[84:87], v[164:167], v[230:233], v[84:87]
	v_mfma_f32_16x16x32_bf16 v[80:83], v[172:175], v[230:233], v[80:83]
	v_mfma_f32_16x16x32_bf16 v[68:71], v[164:167], v[238:241], v[68:71]
	v_mfma_f32_16x16x32_bf16 v[64:67], v[172:175], v[238:241], v[64:67]
	s_setprio 0
	s_barrier
	s_add_i32 s68, s68, s20
	v_lshl_add_u64 v[180:181], s[40:41], 0, v[142:143]
	s_mov_b32 m0, s68
	ds_read_b128 v[200:203], v179 offset:16384
	ds_read_b128 v[204:207], v179 offset:17408
	ds_read_b128 v[208:211], v179 offset:18432
	ds_read_b128 v[222:225], v179 offset:19456
	ds_read_b128 v[226:229], v179 offset:20480
	ds_read_b128 v[230:233], v179 offset:21504
	ds_read_b128 v[234:237], v179 offset:22528
	ds_read_b128 v[238:241], v179 offset:23552
	global_load_lds_dwordx4 v[180:181], off
	s_add_i32 m0, s68, 0x2000
	s_add_u32 s68, s40, 0x40000
	v_lshl_add_u64 v[184:185], s[40:41], 0, v[138:139]
	s_addc_u32 s69, s41, 0
	s_add_i32 s70, s70, s20
	global_load_lds_dwordx4 v[184:185], off
	v_lshl_add_u64 v[186:187], s[68:69], 0, v[142:143]
	s_mov_b32 m0, s70
	v_lshl_add_u64 v[212:213], s[56:57], 0, v[140:141]
	global_load_lds_dwordx4 v[186:187], off
	v_lshl_add_u64 v[186:187], s[68:69], 0, v[138:139]
	s_add_i32 m0, s70, 0x2000
	s_nop 0
	global_load_lds_dwordx4 v[186:187], off
	v_lshl_add_u64 v[186:187], s[56:57], 0, v[144:145]
	s_mov_b32 m0, s22
	s_nop 0
	global_load_lds_dwordx4 v[186:187], off
	s_mov_b32 m0, s23
	s_nop 0
	global_load_lds_dwordx4 v[212:213], off
	s_waitcnt vmcnt(8)
	s_waitcnt lgkmcnt(0)
	s_barrier
; #define PG8_STAGE(bufoff, gbase, voff) do { _Pragma("unroll") for (int _i = 0; _i < 2; ++_i) \
;         __builtin_amdgcn_global_load_lds((const unsigned*)((const char*)(gbase) + (voff)[_i]), (PG8_LAS unsigned*)(lds + (bufoff) + ldsw + _i * 8192), 16, 0, 0); } while (0)
; #define PG8_LDA(dst, b, h) do { _Pragma("unroll") for (int m = 0; m < 4; ++m) _Pragma("unroll") for (int k = 0; k < 2; ++k) dst[m][k] = *(const PG8_LAS bf16x8*)(lds + PG8_SA(b, h) + aoff + m * 2048 + k * 1024); } while (0)
; #define PG8_LDB(dst, b, h) do { _Pragma("unroll") for (int n = 0; n < 2; ++n) _Pragma("unroll") for (int k = 0; k < 2; ++k) dst[n][k] = *(const PG8_LAS bf16x8*)(lds + PG8_SB(b, h) + boff + n * 2048 + k * 1024); } while (0)
; #define PG8_MMA(ai, bj, At, Bt) do { __builtin_amdgcn_s_setprio(1); _Pragma("unroll") for (int m = 0; m < 4; ++m) _Pragma("unroll") for (int n = 0; n < 2; ++n) _Pragma("unroll") for (int k = 0; k < 2; ++k) \
;         acc[ai][bj][m][n] = __builtin_amdgcn_mfma_f32_16x16x32_bf16(Bt[n][k], At[m][k], acc[ai][bj][m][n], 0, 0, 0); __builtin_amdgcn_s_setprio(0); } while (0)
; #define PG8_WAIT_V(n) asm volatile("s_waitcnt vmcnt(" #n ")" ::: "memory")
; #define PG8_WAIT_L(n) asm volatile("s_waitcnt lgkmcnt(" #n ")" ::: "memory")
; #define PG8_BAR __builtin_amdgcn_s_barrier()
; #define PG8_SCHED __builtin_amdgcn_sched_barrier(0)
; template <class Epi, class Sched, bool ALIGN_EPI = false, bool SP2 = false>
; __device__ __forceinline__ void gemm_phase(PG8_LAS unsigned char* lds, const Gemm g, const Sched& S, const Epi& E) {
;     ...
;             PG8_WAIT_V(8); PG8_WAIT_L(0); PG8_BAR; PG8_MMA(1, 0, At, B0); PG8_MMA(1, 1, At, B1); PG8_BAR; PG8_SCHED;
;             PG8_LDB(B0, 1, 0); PG8_LDB(B1, 1, 1); PG8_SCHED; PG8_LDA(At, 1, 0); PG8_STAGE(PG8_SA(0, 1), a2 + hstep, voffA);
;             PG8_WAIT_V(8); PG8_WAIT_L(0); PG8_BAR; PG8_MMA(0, 0, At, B0); PG8_MMA(0, 1, At, B1); PG8_BAR; PG8_SCHED;
	s_setprio 1
	v_mfma_f32_16x16x32_bf16 v[60:63], v[130:133], v[200:203], v[60:63]
	v_mfma_f32_16x16x32_bf16 v[56:59], v[152:155], v[200:203], v[56:59]
	v_mfma_f32_16x16x32_bf16 v[44:47], v[130:133], v[208:211], v[44:47]
	v_mfma_f32_16x16x32_bf16 v[40:43], v[152:155], v[208:211], v[40:43]
	v_mfma_f32_16x16x32_bf16 v[28:31], v[130:133], v[226:229], v[28:31]
	v_mfma_f32_16x16x32_bf16 v[24:27], v[152:155], v[226:229], v[24:27]
	v_mfma_f32_16x16x32_bf16 v[12:15], v[130:133], v[234:237], v[12:15]
	v_mfma_f32_16x16x32_bf16 v[8:11], v[152:155], v[234:237], v[8:11]
	v_mfma_f32_16x16x32_bf16 v[60:63], v[134:137], v[204:207], v[60:63]
	v_mfma_f32_16x16x32_bf16 v[56:59], v[156:159], v[204:207], v[56:59]
	v_mfma_f32_16x16x32_bf16 v[44:47], v[134:137], v[222:225], v[44:47]
	v_mfma_f32_16x16x32_bf16 v[40:43], v[156:159], v[222:225], v[40:43]
	v_mfma_f32_16x16x32_bf16 v[28:31], v[134:137], v[230:233], v[28:31]
	v_mfma_f32_16x16x32_bf16 v[24:27], v[156:159], v[230:233], v[24:27]
	v_mfma_f32_16x16x32_bf16 v[12:15], v[134:137], v[238:241], v[12:15]
	v_mfma_f32_16x16x32_bf16 v[8:11], v[156:159], v[238:241], v[8:11]
	s_setprio 0
	s_setprio 1
	v_mfma_f32_16x16x32_bf16 v[52:55], v[160:163], v[200:203], v[52:55]
	v_mfma_f32_16x16x32_bf16 v[48:51], v[168:171], v[200:203], v[48:51]
	v_mfma_f32_16x16x32_bf16 v[36:39], v[160:163], v[208:211], v[36:39]
	v_mfma_f32_16x16x32_bf16 v[32:35], v[168:171], v[208:211], v[32:35]
	v_mfma_f32_16x16x32_bf16 v[20:23], v[160:163], v[226:229], v[20:23]
	v_mfma_f32_16x16x32_bf16 v[16:19], v[168:171], v[226:229], v[16:19]
	v_mfma_f32_16x16x32_bf16 v[4:7], v[160:163], v[234:237], v[4:7]
	v_mfma_f32_16x16x32_bf16 v[0:3], v[168:171], v[234:237], v[0:3]
	v_mfma_f32_16x16x32_bf16 v[52:55], v[164:167], v[204:207], v[52:55]
	v_mfma_f32_16x16x32_bf16 v[48:51], v[172:175], v[204:207], v[48:51]
	v_mfma_f32_16x16x32_bf16 v[36:39], v[164:167], v[222:225], v[36:39]
	v_mfma_f32_16x16x32_bf16 v[32:35], v[172:175], v[222:225], v[32:35]
	v_mfma_f32_16x16x32_bf16 v[20:23], v[164:167], v[230:233], v[20:23]
	v_mfma_f32_16x16x32_bf16 v[16:19], v[172:175], v[230:233], v[16:19]
	v_mfma_f32_16x16x32_bf16 v[4:7], v[164:167], v[238:241], v[4:7]
	v_mfma_f32_16x16x32_bf16 v[0:3], v[172:175], v[238:241], v[0:3]
	s_setprio 0
	s_barrier
	s_add_i32 s68, 0, 0x18000
	v_add_u32_e32 v112, s68, v176
	s_add_i32 s69, 0, 0x1c000
	ds_read_b128 v[130:133], v112
	ds_read_b128 v[134:137], v112 offset:1024
	ds_read_b128 v[152:155], v112 offset:2048
	ds_read_b128 v[156:159], v112 offset:3072
	v_add_u32_e32 v112, s69, v176
	ds_read_b128 v[160:163], v112
	ds_read_b128 v[164:167], v112 offset:1024
	ds_read_b128 v[168:171], v112 offset:2048
	ds_read_b128 v[172:175], v112 offset:3072
	s_add_u32 s56, s56, 0x40000
	s_addc_u32 s57, s57, 0
	s_mov_b32 m0, s45
	v_lshl_add_u64 v[242:243], s[56:57], 0, v[144:145]
	ds_read_b128 v[200:203], v179 offset:32768
	ds_read_b128 v[204:207], v179 offset:33792
	ds_read_b128 v[208:211], v179 offset:34816
	ds_read_b128 v[222:225], v179 offset:35840
	ds_read_b128 v[226:229], v179 offset:36864
	ds_read_b128 v[230:233], v179 offset:37888
	ds_read_b128 v[234:237], v179 offset:38912
	ds_read_b128 v[238:241], v179 offset:39936
	global_load_lds_dwordx4 v[242:243], off
	v_lshl_add_u64 v[242:243], s[56:57], 0, v[140:141]
	s_mov_b32 m0, s53
	s_nop 0
	global_load_lds_dwordx4 v[242:243], off
	s_waitcnt vmcnt(8)
	s_waitcnt lgkmcnt(0)
	s_barrier
	s_setprio 1
	v_mfma_f32_16x16x32_bf16 v[126:129], v[130:133], v[200:203], v[126:129]
	v_mfma_f32_16x16x32_bf16 v[122:125], v[152:155], v[200:203], v[122:125]
	v_mfma_f32_16x16x32_bf16 v[108:111], v[130:133], v[208:211], v[108:111]
	v_mfma_f32_16x16x32_bf16 v[104:107], v[152:155], v[208:211], v[104:107]
	v_mfma_f32_16x16x32_bf16 v[92:95], v[130:133], v[226:229], v[92:95]
	v_mfma_f32_16x16x32_bf16 v[88:91], v[152:155], v[226:229], v[88:91]
	v_mfma_f32_16x16x32_bf16 v[76:79], v[130:133], v[234:237], v[76:79]
	v_mfma_f32_16x16x32_bf16 v[72:75], v[152:155], v[234:237], v[72:75]
	v_mfma_f32_16x16x32_bf16 v[126:129], v[134:137], v[204:207], v[126:129]
	v_mfma_f32_16x16x32_bf16 v[122:125], v[156:159], v[204:207], v[122:125]
	v_mfma_f32_16x16x32_bf16 v[108:111], v[134:137], v[222:225], v[108:111]
	v_mfma_f32_16x16x32_bf16 v[104:107], v[156:159], v[222:225], v[104:107]
	v_mfma_f32_16x16x32_bf16 v[92:95], v[134:137], v[230:233], v[92:95]
	v_mfma_f32_16x16x32_bf16 v[88:91], v[156:159], v[230:233], v[88:91]
	v_mfma_f32_16x16x32_bf16 v[76:79], v[134:137], v[238:241], v[76:79]
	v_mfma_f32_16x16x32_bf16 v[72:75], v[156:159], v[238:241], v[72:75]
	s_setprio 0
	s_setprio 1
	v_mfma_f32_16x16x32_bf16 v[118:121], v[160:163], v[200:203], v[118:121]
	v_mfma_f32_16x16x32_bf16 v[114:117], v[168:171], v[200:203], v[114:117]
	v_mfma_f32_16x16x32_bf16 v[100:103], v[160:163], v[208:211], v[100:103]
	v_mfma_f32_16x16x32_bf16 v[96:99], v[168:171], v[208:211], v[96:99]
	v_mfma_f32_16x16x32_bf16 v[84:87], v[160:163], v[226:229], v[84:87]
	v_mfma_f32_16x16x32_bf16 v[80:83], v[168:171], v[226:229], v[80:83]
	v_mfma_f32_16x16x32_bf16 v[68:71], v[160:163], v[234:237], v[68:71]
	v_mfma_f32_16x16x32_bf16 v[64:67], v[168:171], v[234:237], v[64:67]
	v_mfma_f32_16x16x32_bf16 v[118:121], v[164:167], v[204:207], v[118:121]
	v_mfma_f32_16x16x32_bf16 v[114:117], v[172:175], v[204:207], v[114:117]
	v_mfma_f32_16x16x32_bf16 v[100:103], v[164:167], v[222:225], v[100:103]
	v_mfma_f32_16x16x32_bf16 v[96:99], v[172:175], v[222:225], v[96:99]
	v_mfma_f32_16x16x32_bf16 v[84:87], v[164:167], v[230:233], v[84:87]
	v_mfma_f32_16x16x32_bf16 v[80:83], v[172:175], v[230:233], v[80:83]
	v_mfma_f32_16x16x32_bf16 v[68:71], v[164:167], v[238:241], v[68:71]
	v_mfma_f32_16x16x32_bf16 v[64:67], v[172:175], v[238:241], v[64:67]
	s_setprio 0
	s_barrier
; #define PG8_STAGE(bufoff, gbase, voff) do { _Pragma("unroll") for (int _i = 0; _i < 2; ++_i) \
;         __builtin_amdgcn_global_load_lds((const unsigned*)((const char*)(gbase) + (voff)[_i]), (PG8_LAS unsigned*)(lds + (bufoff) + ldsw + _i * 8192), 16, 0, 0); } while (0)
; #define PG8_LDA(dst, b, h) do { _Pragma("unroll") for (int m = 0; m < 4; ++m) _Pragma("unroll") for (int k = 0; k < 2; ++k) dst[m][k] = *(const PG8_LAS bf16x8*)(lds + PG8_SA(b, h) + aoff + m * 2048 + k * 1024); } while (0)
; #define PG8_MMA(ai, bj, At, Bt) do { __builtin_amdgcn_s_setprio(1); _Pragma("unroll") for (int m = 0; m < 4; ++m) _Pragma("unroll") for (int n = 0; n < 2; ++n) _Pragma("unroll") for (int k = 0; k < 2; ++k) \
;         acc[ai][bj][m][n] = __builtin_amdgcn_mfma_f32_16x16x32_bf16(Bt[n][k], At[m][k], acc[ai][bj][m][n], 0, 0, 0); __builtin_amdgcn_s_setprio(0); } while (0)
; #define PG8_WAIT_V(n) asm volatile("s_waitcnt vmcnt(" #n ")" ::: "memory")
; #define PG8_WAIT_L(n) asm volatile("s_waitcnt lgkmcnt(" #n ")" ::: "memory")
; #define PG8_BAR __builtin_amdgcn_s_barrier()
; #define PG8_SCHED __builtin_amdgcn_sched_barrier(0)
; template <class Epi, class Sched, bool ALIGN_EPI = false, bool SP2 = false>
; __device__ __forceinline__ void gemm_phase(PG8_LAS unsigned char* lds, const Gemm g, const Sched& S, const Epi& E) {
;     ...
;         for (int t = 0; t < nt; t += 2) {
;     ...
;             PG8_LDA(At, 1, 1); PG8_STAGE(PG8_SB(1, 0), b3, voffB); PG8_STAGE(PG8_SB(1, 1), b3 + hstep, voffB); PG8_STAGE(PG8_SA(1, 0), a3, voffA);
;             PG8_WAIT_V(8); PG8_WAIT_L(0); PG8_BAR; PG8_MMA(1, 0, At, B0); PG8_MMA(1, 1, At, B1); PG8_BAR; PG8_SCHED;
	s_add_i32 s56, s68, s20
	v_lshl_add_u64 v[180:181], v[180:181], 0, s[36:37]
	s_mov_b32 m0, s56
	ds_read_b128 v[200:203], v179 offset:49152
	ds_read_b128 v[204:207], v179 offset:50176
	ds_read_b128 v[208:211], v179 offset:51200
	ds_read_b128 v[222:225], v179 offset:52224
	ds_read_b128 v[226:229], v179 offset:53248
	ds_read_b128 v[230:233], v179 offset:54272
	ds_read_b128 v[234:237], v179 offset:55296
	ds_read_b128 v[238:241], v179 offset:56320
	global_load_lds_dwordx4 v[180:181], off
	s_add_i32 m0, s56, 0x2000
	s_add_u32 s40, s40, 0x40080
	v_lshl_add_u64 v[180:181], v[184:185], 0, s[36:37]
	s_addc_u32 s41, s41, 0
	s_add_i32 s56, s69, s20
	global_load_lds_dwordx4 v[180:181], off
	v_lshl_add_u64 v[180:181], s[40:41], 0, v[142:143]
	s_mov_b32 m0, s56
	s_nop 0
	global_load_lds_dwordx4 v[180:181], off
	v_lshl_add_u64 v[180:181], s[40:41], 0, v[138:139]
	s_add_i32 m0, s56, 0x2000
	s_nop 0
	global_load_lds_dwordx4 v[180:181], off
	v_lshl_add_u64 v[180:181], v[186:187], 0, s[36:37]
	s_mov_b32 m0, s11
	s_nop 0
	global_load_lds_dwordx4 v[180:181], off
	v_lshl_add_u64 v[180:181], v[212:213], 0, s[36:37]
	s_mov_b32 m0, s44
	s_nop 0
	global_load_lds_dwordx4 v[180:181], off
	s_waitcnt vmcnt(8)
	s_waitcnt lgkmcnt(0)
	s_barrier
	s_setprio 1
	v_mfma_f32_16x16x32_bf16 v[60:63], v[130:133], v[200:203], v[60:63]
	v_mfma_f32_16x16x32_bf16 v[56:59], v[152:155], v[200:203], v[56:59]
	v_mfma_f32_16x16x32_bf16 v[44:47], v[130:133], v[208:211], v[44:47]
	v_mfma_f32_16x16x32_bf16 v[40:43], v[152:155], v[208:211], v[40:43]
	v_mfma_f32_16x16x32_bf16 v[28:31], v[130:133], v[226:229], v[28:31]
	v_mfma_f32_16x16x32_bf16 v[24:27], v[152:155], v[226:229], v[24:27]
	v_mfma_f32_16x16x32_bf16 v[12:15], v[130:133], v[234:237], v[12:15]
	v_mfma_f32_16x16x32_bf16 v[8:11], v[152:155], v[234:237], v[8:11]
	v_mfma_f32_16x16x32_bf16 v[60:63], v[134:137], v[204:207], v[60:63]
	v_mfma_f32_16x16x32_bf16 v[56:59], v[156:159], v[204:207], v[56:59]
	v_mfma_f32_16x16x32_bf16 v[44:47], v[134:137], v[222:225], v[44:47]
	v_mfma_f32_16x16x32_bf16 v[40:43], v[156:159], v[222:225], v[40:43]
	v_mfma_f32_16x16x32_bf16 v[28:31], v[134:137], v[230:233], v[28:31]
	v_mfma_f32_16x16x32_bf16 v[24:27], v[156:159], v[230:233], v[24:27]
	v_mfma_f32_16x16x32_bf16 v[12:15], v[134:137], v[238:241], v[12:15]
	v_mfma_f32_16x16x32_bf16 v[8:11], v[156:159], v[238:241], v[8:11]
	s_setprio 0
	s_setprio 1
	v_mfma_f32_16x16x32_bf16 v[52:55], v[160:163], v[200:203], v[52:55]
	v_mfma_f32_16x16x32_bf16 v[48:51], v[168:171], v[200:203], v[48:51]
	v_mfma_f32_16x16x32_bf16 v[36:39], v[160:163], v[208:211], v[36:39]
	v_mfma_f32_16x16x32_bf16 v[32:35], v[168:171], v[208:211], v[32:35]
	v_mfma_f32_16x16x32_bf16 v[20:23], v[160:163], v[226:229], v[20:23]
	v_mfma_f32_16x16x32_bf16 v[16:19], v[168:171], v[226:229], v[16:19]
	v_mfma_f32_16x16x32_bf16 v[4:7], v[160:163], v[234:237], v[4:7]
	v_mfma_f32_16x16x32_bf16 v[0:3], v[168:171], v[234:237], v[0:3]
	v_mfma_f32_16x16x32_bf16 v[52:55], v[164:167], v[204:207], v[52:55]
	v_mfma_f32_16x16x32_bf16 v[48:51], v[172:175], v[204:207], v[48:51]
	v_mfma_f32_16x16x32_bf16 v[36:39], v[164:167], v[222:225], v[36:39]
	v_mfma_f32_16x16x32_bf16 v[32:35], v[172:175], v[222:225], v[32:35]
	v_mfma_f32_16x16x32_bf16 v[20:23], v[164:167], v[230:233], v[20:23]
	v_mfma_f32_16x16x32_bf16 v[16:19], v[172:175], v[230:233], v[16:19]
	v_mfma_f32_16x16x32_bf16 v[4:7], v[164:167], v[238:241], v[4:7]
	v_mfma_f32_16x16x32_bf16 v[0:3], v[172:175], v[238:241], v[0:3]
	s_setprio 0
	s_barrier
	s_add_i32 s60, s60, 2
	s_add_u32 vcc_lo, vcc_lo, 0x100
	s_addc_u32 vcc_hi, vcc_hi, 0
	s_add_u32 s55, s55, 0x100
	s_addc_u32 s61, s61, 0
	s_cmp_gt_u32 s60, 13
	s_cbranch_scc0 .LBB0_128
	s_and_b64 vcc, exec, s[50:51]
	s_cbranch_vccnz .LBB0_133
	v_lshl_add_u32 v152, s0, 8, v147
	s_cmp_gt_i32 s67, 3
	s_mov_b64 s[0:1], -1
	s_cbranch_scc1 .LBB0_134

; #define PG8_STAGE(bufoff, gbase, voff) do { _Pragma("unroll") for (int _i = 0; _i < 2; ++_i) \
;         __builtin_amdgcn_global_load_lds((const unsigned*)((const char*)(gbase) + (voff)[_i]), (PG8_LAS unsigned*)(lds + (bufoff) + ldsw + _i * 8192), 16, 0, 0); } while (0)
; #define PG8_LDA(dst, b, h) do { _Pragma("unroll") for (int m = 0; m < 4; ++m) _Pragma("unroll") for (int k = 0; k < 2; ++k) dst[m][k] = *(const PG8_LAS bf16x8*)(lds + PG8_SA(b, h) + aoff + m * 2048 + k * 1024); } while (0)
; #define PG8_LDB(dst, b, h) do { _Pragma("unroll") for (int n = 0; n < 2; ++n) _Pragma("unroll") for (int k = 0; k < 2; ++k) dst[n][k] = *(const PG8_LAS bf16x8*)(lds + PG8_SB(b, h) + boff + n * 2048 + k * 1024); } while (0)
; #define PG8_MMA(ai, bj, At, Bt) do { __builtin_amdgcn_s_setprio(1); _Pragma("unroll") for (int m = 0; m < 4; ++m) _Pragma("unroll") for (int n = 0; n < 2; ++n) _Pragma("unroll") for (int k = 0; k < 2; ++k) \
;         acc[ai][bj][m][n] = __builtin_amdgcn_mfma_f32_16x16x32_bf16(Bt[n][k], At[m][k], acc[ai][bj][m][n], 0, 0, 0); __builtin_amdgcn_s_setprio(0); } while (0)
; #define PG8_WAIT_V(n) asm volatile("s_waitcnt vmcnt(" #n ")" ::: "memory")
; #define PG8_WAIT_L(n) asm volatile("s_waitcnt lgkmcnt(" #n ")" ::: "memory")
; template <class Epi, class Sched, bool ALIGN_EPI = false, bool SP2 = false>
; __device__ __forceinline__ void gemm_phase(PG8_LAS unsigned char* lds, const Gemm g, const Sched& S, const Epi& E) {
;     ...
;             const bool last = (t == nt - 2);
;             const char* a1 = cA + (size_t)(t + 1) * kstep;
;             const char* a2 = last ? nA : cA + (size_t)(t + 2) * kstep; const char* b2 = last ? nB : cB + (size_t)(t + 2) * kstep;
;             const char* a3 = a2 + kstep; const char* b3 = b2 + kstep;
;             if (last && has_next) S.a_ready(nxt);
;             if constexpr (SP2) {
;             PG8_LDB(B0, 0, 0); PG8_LDB(B1, 0, 1); PG8_SCHED; PG8_LDA(At, 0, 0); PG8_STAGE(PG8_SA(1, 1), a1 + hstep, voffA);
;             PG8_WAIT_V(8); PG8_WAIT_L(0); PG8_BAR; PG8_MMA(0, 0, At, B0); PG8_MMA(0, 1, At, B1); PG8_BAR; PG8_SCHED;
;             PG8_LDA(At, 0, 1); PG8_STAGE(PG8_SB(0, 0), b2, voffB); PG8_STAGE(PG8_SB(0, 1), b2 + hstep, voffB); PG8_STAGE(PG8_SA(0, 0), a2, voffA);
;             PG8_WAIT_V(8); PG8_WAIT_L(0); PG8_BAR; PG8_MMA(1, 0, At, B0); PG8_MMA(1, 1, At, B1); PG8_BAR; PG8_SCHED;
.LBB0_160:
	s_add_u32 s40, s54, 0xfffc0080
	s_addc_u32 s41, s55, -1
	s_add_i32 s66, 0, 0x10000
	s_cmp_eq_u32 s60, 12
	s_cselect_b32 s57, s12, s41
	s_cselect_b32 s56, s13, s40
	v_add_u32_e32 v139, s66, v150
	s_cselect_b32 s41, s39, s61
	s_cselect_b32 s40, s43, s65
	s_add_i32 s68, 0, 0x14000
	ds_read_b128 v[144:147], v139
	ds_read_b128 v[154:157], v139 offset:1024
	ds_read_b128 v[158:161], v139 offset:2048
	ds_read_b128 v[162:165], v139 offset:3072
	v_add_u32_e32 v139, s68, v150
	ds_read_b128 v[166:169], v139
	ds_read_b128 v[170:173], v139 offset:1024
	ds_read_b128 v[174:177], v139 offset:2048
	ds_read_b128 v[178:181], v139 offset:3072
	v_lshl_add_u64 v[148:149], s[54:55], 0, v[134:135]
	s_add_i32 m0, s21, 0xc000
	ds_read_b128 v[200:203], v152
	ds_read_b128 v[204:207], v152 offset:1024
	ds_read_b128 v[208:211], v152 offset:2048
	ds_read_b128 v[222:225], v152 offset:3072
	ds_read_b128 v[226:229], v152 offset:4096
	ds_read_b128 v[230:233], v152 offset:5120
	ds_read_b128 v[234:237], v152 offset:6144
	ds_read_b128 v[238:241], v152 offset:7168
	global_load_lds_dwordx4 v[148:149], off
	v_lshl_add_u64 v[148:149], s[54:55], 0, v[136:137]
	s_add_i32 m0, s21, 0xe000
	s_nop 0
	global_load_lds_dwordx4 v[148:149], off
	s_waitcnt vmcnt(8)
	s_waitcnt lgkmcnt(0)
	s_barrier
	s_setprio 1
	v_mfma_f32_16x16x32_bf16 v[126:129], v[144:147], v[200:203], v[126:129]
	v_mfma_f32_16x16x32_bf16 v[92:95], v[158:161], v[200:203], v[92:95]
	v_mfma_f32_16x16x32_bf16 v[122:125], v[144:147], v[208:211], v[122:125]
	v_mfma_f32_16x16x32_bf16 v[88:91], v[158:161], v[208:211], v[88:91]
	v_mfma_f32_16x16x32_bf16 v[118:121], v[144:147], v[226:229], v[118:121]
	v_mfma_f32_16x16x32_bf16 v[84:87], v[158:161], v[226:229], v[84:87]
	v_mfma_f32_16x16x32_bf16 v[114:117], v[144:147], v[234:237], v[114:117]
	v_mfma_f32_16x16x32_bf16 v[80:83], v[158:161], v[234:237], v[80:83]
	v_mfma_f32_16x16x32_bf16 v[126:129], v[154:157], v[204:207], v[126:129]
	v_mfma_f32_16x16x32_bf16 v[92:95], v[162:165], v[204:207], v[92:95]
	v_mfma_f32_16x16x32_bf16 v[122:125], v[154:157], v[222:225], v[122:125]
	v_mfma_f32_16x16x32_bf16 v[88:91], v[162:165], v[222:225], v[88:91]
	v_mfma_f32_16x16x32_bf16 v[118:121], v[154:157], v[230:233], v[118:121]
	v_mfma_f32_16x16x32_bf16 v[84:87], v[162:165], v[230:233], v[84:87]
	v_mfma_f32_16x16x32_bf16 v[114:117], v[154:157], v[238:241], v[114:117]
	v_mfma_f32_16x16x32_bf16 v[80:83], v[162:165], v[238:241], v[80:83]
	s_setprio 0
	s_setprio 1
	v_mfma_f32_16x16x32_bf16 v[60:63], v[166:169], v[200:203], v[60:63]
	v_mfma_f32_16x16x32_bf16 v[28:31], v[174:177], v[200:203], v[28:31]
	v_mfma_f32_16x16x32_bf16 v[56:59], v[166:169], v[208:211], v[56:59]
	v_mfma_f32_16x16x32_bf16 v[24:27], v[174:177], v[208:211], v[24:27]
	v_mfma_f32_16x16x32_bf16 v[52:55], v[166:169], v[226:229], v[52:55]
	v_mfma_f32_16x16x32_bf16 v[20:23], v[174:177], v[226:229], v[20:23]
	v_mfma_f32_16x16x32_bf16 v[48:51], v[166:169], v[234:237], v[48:51]
	v_mfma_f32_16x16x32_bf16 v[16:19], v[174:177], v[234:237], v[16:19]
	v_mfma_f32_16x16x32_bf16 v[60:63], v[170:173], v[204:207], v[60:63]
	v_mfma_f32_16x16x32_bf16 v[28:31], v[178:181], v[204:207], v[28:31]
	v_mfma_f32_16x16x32_bf16 v[56:59], v[170:173], v[222:225], v[56:59]
	v_mfma_f32_16x16x32_bf16 v[24:27], v[178:181], v[222:225], v[24:27]
	v_mfma_f32_16x16x32_bf16 v[52:55], v[170:173], v[230:233], v[52:55]
	v_mfma_f32_16x16x32_bf16 v[20:23], v[178:181], v[230:233], v[20:23]
	v_mfma_f32_16x16x32_bf16 v[48:51], v[170:173], v[238:241], v[48:51]
	v_mfma_f32_16x16x32_bf16 v[16:19], v[178:181], v[238:241], v[16:19]
	s_setprio 0
	s_barrier
	s_add_i32 s66, s66, s20
	v_lshl_add_u64 v[148:149], s[40:41], 0, v[130:131]
	s_mov_b32 m0, s66
	ds_read_b128 v[200:203], v152 offset:16384
	ds_read_b128 v[204:207], v152 offset:17408
	ds_read_b128 v[208:211], v152 offset:18432
	ds_read_b128 v[222:225], v152 offset:19456
	ds_read_b128 v[226:229], v152 offset:20480
	ds_read_b128 v[230:233], v152 offset:21504
	ds_read_b128 v[234:237], v152 offset:22528
	ds_read_b128 v[238:241], v152 offset:23552
	global_load_lds_dwordx4 v[148:149], off
	s_add_i32 m0, s66, 0x2000
	s_add_u32 s66, s40, 0x40000
	v_lshl_add_u64 v[184:185], s[40:41], 0, v[132:133]
	s_addc_u32 s67, s41, 0
	s_add_i32 s68, s68, s20
	global_load_lds_dwordx4 v[184:185], off
	v_lshl_add_u64 v[186:187], s[66:67], 0, v[130:131]
	s_mov_b32 m0, s68
	v_lshl_add_u64 v[212:213], s[56:57], 0, v[132:133]
	global_load_lds_dwordx4 v[186:187], off
	v_lshl_add_u64 v[186:187], s[66:67], 0, v[132:133]
	s_add_i32 m0, s68, 0x2000
	s_nop 0
	global_load_lds_dwordx4 v[186:187], off
	v_lshl_add_u64 v[186:187], s[56:57], 0, v[130:131]
	s_mov_b32 m0, s21
	s_nop 0
	global_load_lds_dwordx4 v[186:187], off
	s_mov_b32 m0, s22
	s_nop 0
	global_load_lds_dwordx4 v[212:213], off
	s_waitcnt vmcnt(8)
	s_waitcnt lgkmcnt(0)
	s_barrier
; #define PG8_STAGE(bufoff, gbase, voff) do { _Pragma("unroll") for (int _i = 0; _i < 2; ++_i) \
;         __builtin_amdgcn_global_load_lds((const unsigned*)((const char*)(gbase) + (voff)[_i]), (PG8_LAS unsigned*)(lds + (bufoff) + ldsw + _i * 8192), 16, 0, 0); } while (0)
; #define PG8_LDA(dst, b, h) do { _Pragma("unroll") for (int m = 0; m < 4; ++m) _Pragma("unroll") for (int k = 0; k < 2; ++k) dst[m][k] = *(const PG8_LAS bf16x8*)(lds + PG8_SA(b, h) + aoff + m * 2048 + k * 1024); } while (0)
; #define PG8_LDB(dst, b, h) do { _Pragma("unroll") for (int n = 0; n < 2; ++n) _Pragma("unroll") for (int k = 0; k < 2; ++k) dst[n][k] = *(const PG8_LAS bf16x8*)(lds + PG8_SB(b, h) + boff + n * 2048 + k * 1024); } while (0)
; #define PG8_MMA(ai, bj, At, Bt) do { __builtin_amdgcn_s_setprio(1); _Pragma("unroll") for (int m = 0; m < 4; ++m) _Pragma("unroll") for (int n = 0; n < 2; ++n) _Pragma("unroll") for (int k = 0; k < 2; ++k) \
;         acc[ai][bj][m][n] = __builtin_amdgcn_mfma_f32_16x16x32_bf16(Bt[n][k], At[m][k], acc[ai][bj][m][n], 0, 0, 0); __builtin_amdgcn_s_setprio(0); } while (0)
; #define PG8_WAIT_V(n) asm volatile("s_waitcnt vmcnt(" #n ")" ::: "memory")
; #define PG8_WAIT_L(n) asm volatile("s_waitcnt lgkmcnt(" #n ")" ::: "memory")
; #define PG8_BAR __builtin_amdgcn_s_barrier()
; #define PG8_SCHED __builtin_amdgcn_sched_barrier(0)
; template <class Epi, class Sched, bool ALIGN_EPI = false, bool SP2 = false>
; __device__ __forceinline__ void gemm_phase(PG8_LAS unsigned char* lds, const Gemm g, const Sched& S, const Epi& E) {
;     ...
;             PG8_WAIT_V(8); PG8_WAIT_L(0); PG8_BAR; PG8_MMA(1, 0, At, B0); PG8_MMA(1, 1, At, B1); PG8_BAR; PG8_SCHED;
;             PG8_LDB(B0, 1, 0); PG8_LDB(B1, 1, 1); PG8_SCHED; PG8_LDA(At, 1, 0); PG8_STAGE(PG8_SA(0, 1), a2 + hstep, voffA);
;             PG8_WAIT_V(8); PG8_WAIT_L(0); PG8_BAR; PG8_MMA(0, 0, At, B0); PG8_MMA(0, 1, At, B1); PG8_BAR; PG8_SCHED;
	s_setprio 1
	v_mfma_f32_16x16x32_bf16 v[108:111], v[144:147], v[200:203], v[108:111]
	v_mfma_f32_16x16x32_bf16 v[76:79], v[158:161], v[200:203], v[76:79]
	v_mfma_f32_16x16x32_bf16 v[104:107], v[144:147], v[208:211], v[104:107]
	v_mfma_f32_16x16x32_bf16 v[72:75], v[158:161], v[208:211], v[72:75]
	v_mfma_f32_16x16x32_bf16 v[100:103], v[144:147], v[226:229], v[100:103]
	v_mfma_f32_16x16x32_bf16 v[68:71], v[158:161], v[226:229], v[68:71]
	v_mfma_f32_16x16x32_bf16 v[96:99], v[144:147], v[234:237], v[96:99]
	v_mfma_f32_16x16x32_bf16 v[64:67], v[158:161], v[234:237], v[64:67]
	v_mfma_f32_16x16x32_bf16 v[108:111], v[154:157], v[204:207], v[108:111]
	v_mfma_f32_16x16x32_bf16 v[76:79], v[162:165], v[204:207], v[76:79]
	v_mfma_f32_16x16x32_bf16 v[104:107], v[154:157], v[222:225], v[104:107]
	v_mfma_f32_16x16x32_bf16 v[72:75], v[162:165], v[222:225], v[72:75]
	v_mfma_f32_16x16x32_bf16 v[100:103], v[154:157], v[230:233], v[100:103]
	v_mfma_f32_16x16x32_bf16 v[68:71], v[162:165], v[230:233], v[68:71]
	v_mfma_f32_16x16x32_bf16 v[96:99], v[154:157], v[238:241], v[96:99]
	v_mfma_f32_16x16x32_bf16 v[64:67], v[162:165], v[238:241], v[64:67]
	s_setprio 0
	s_setprio 1
	v_mfma_f32_16x16x32_bf16 v[44:47], v[166:169], v[200:203], v[44:47]
	v_mfma_f32_16x16x32_bf16 v[12:15], v[174:177], v[200:203], v[12:15]
	v_mfma_f32_16x16x32_bf16 v[40:43], v[166:169], v[208:211], v[40:43]
	v_mfma_f32_16x16x32_bf16 v[8:11], v[174:177], v[208:211], v[8:11]
	v_mfma_f32_16x16x32_bf16 v[36:39], v[166:169], v[226:229], v[36:39]
	v_mfma_f32_16x16x32_bf16 v[4:7], v[174:177], v[226:229], v[4:7]
	v_mfma_f32_16x16x32_bf16 v[32:35], v[166:169], v[234:237], v[32:35]
	v_mfma_f32_16x16x32_bf16 v[0:3], v[174:177], v[234:237], v[0:3]
	v_mfma_f32_16x16x32_bf16 v[44:47], v[170:173], v[204:207], v[44:47]
	v_mfma_f32_16x16x32_bf16 v[12:15], v[178:181], v[204:207], v[12:15]
	v_mfma_f32_16x16x32_bf16 v[40:43], v[170:173], v[222:225], v[40:43]
	v_mfma_f32_16x16x32_bf16 v[8:11], v[178:181], v[222:225], v[8:11]
	v_mfma_f32_16x16x32_bf16 v[36:39], v[170:173], v[230:233], v[36:39]
	v_mfma_f32_16x16x32_bf16 v[4:7], v[178:181], v[230:233], v[4:7]
	v_mfma_f32_16x16x32_bf16 v[32:35], v[170:173], v[238:241], v[32:35]
	v_mfma_f32_16x16x32_bf16 v[0:3], v[178:181], v[238:241], v[0:3]
	s_setprio 0
	s_barrier
	s_add_i32 s66, 0, 0x18000
	v_add_u32_e32 v139, s66, v150
	s_add_i32 s67, 0, 0x1c000
	ds_read_b128 v[144:147], v139
	ds_read_b128 v[154:157], v139 offset:1024
	ds_read_b128 v[158:161], v139 offset:2048
	ds_read_b128 v[162:165], v139 offset:3072
	v_add_u32_e32 v139, s67, v150
	ds_read_b128 v[166:169], v139
	ds_read_b128 v[170:173], v139 offset:1024
	ds_read_b128 v[174:177], v139 offset:2048
	ds_read_b128 v[178:181], v139 offset:3072
	s_add_u32 s56, s56, 0x40000
	s_addc_u32 s57, s57, 0
	s_mov_b32 m0, s23
	v_lshl_add_u64 v[242:243], s[56:57], 0, v[130:131]
	ds_read_b128 v[200:203], v152 offset:32768
	ds_read_b128 v[204:207], v152 offset:33792
	ds_read_b128 v[208:211], v152 offset:34816
	ds_read_b128 v[222:225], v152 offset:35840
	ds_read_b128 v[226:229], v152 offset:36864
	ds_read_b128 v[230:233], v152 offset:37888
	ds_read_b128 v[234:237], v152 offset:38912
	ds_read_b128 v[238:241], v152 offset:39936
	global_load_lds_dwordx4 v[242:243], off
	v_lshl_add_u64 v[242:243], s[56:57], 0, v[132:133]
	s_mov_b32 m0, s24
	s_nop 0
	global_load_lds_dwordx4 v[242:243], off
	s_waitcnt vmcnt(8)
	s_waitcnt lgkmcnt(0)
	s_barrier
	s_setprio 1
	v_mfma_f32_16x16x32_bf16 v[126:129], v[144:147], v[200:203], v[126:129]
	v_mfma_f32_16x16x32_bf16 v[92:95], v[158:161], v[200:203], v[92:95]
	v_mfma_f32_16x16x32_bf16 v[122:125], v[144:147], v[208:211], v[122:125]
	v_mfma_f32_16x16x32_bf16 v[88:91], v[158:161], v[208:211], v[88:91]
	v_mfma_f32_16x16x32_bf16 v[118:121], v[144:147], v[226:229], v[118:121]
	v_mfma_f32_16x16x32_bf16 v[84:87], v[158:161], v[226:229], v[84:87]
	v_mfma_f32_16x16x32_bf16 v[114:117], v[144:147], v[234:237], v[114:117]
	v_mfma_f32_16x16x32_bf16 v[80:83], v[158:161], v[234:237], v[80:83]
	v_mfma_f32_16x16x32_bf16 v[126:129], v[154:157], v[204:207], v[126:129]
	v_mfma_f32_16x16x32_bf16 v[92:95], v[162:165], v[204:207], v[92:95]
	v_mfma_f32_16x16x32_bf16 v[122:125], v[154:157], v[222:225], v[122:125]
	v_mfma_f32_16x16x32_bf16 v[88:91], v[162:165], v[222:225], v[88:91]
	v_mfma_f32_16x16x32_bf16 v[118:121], v[154:157], v[230:233], v[118:121]
	v_mfma_f32_16x16x32_bf16 v[84:87], v[162:165], v[230:233], v[84:87]
	v_mfma_f32_16x16x32_bf16 v[114:117], v[154:157], v[238:241], v[114:117]
	v_mfma_f32_16x16x32_bf16 v[80:83], v[162:165], v[238:241], v[80:83]
	s_setprio 0
	s_setprio 1
	v_mfma_f32_16x16x32_bf16 v[60:63], v[166:169], v[200:203], v[60:63]
	v_mfma_f32_16x16x32_bf16 v[28:31], v[174:177], v[200:203], v[28:31]
	v_mfma_f32_16x16x32_bf16 v[56:59], v[166:169], v[208:211], v[56:59]
	v_mfma_f32_16x16x32_bf16 v[24:27], v[174:177], v[208:211], v[24:27]
	v_mfma_f32_16x16x32_bf16 v[52:55], v[166:169], v[226:229], v[52:55]
	v_mfma_f32_16x16x32_bf16 v[20:23], v[174:177], v[226:229], v[20:23]
	v_mfma_f32_16x16x32_bf16 v[48:51], v[166:169], v[234:237], v[48:51]
	v_mfma_f32_16x16x32_bf16 v[16:19], v[174:177], v[234:237], v[16:19]
	v_mfma_f32_16x16x32_bf16 v[60:63], v[170:173], v[204:207], v[60:63]
	v_mfma_f32_16x16x32_bf16 v[28:31], v[178:181], v[204:207], v[28:31]
	v_mfma_f32_16x16x32_bf16 v[56:59], v[170:173], v[222:225], v[56:59]
	v_mfma_f32_16x16x32_bf16 v[24:27], v[178:181], v[222:225], v[24:27]
	v_mfma_f32_16x16x32_bf16 v[52:55], v[170:173], v[230:233], v[52:55]
	v_mfma_f32_16x16x32_bf16 v[20:23], v[178:181], v[230:233], v[20:23]
	v_mfma_f32_16x16x32_bf16 v[48:51], v[170:173], v[238:241], v[48:51]
	v_mfma_f32_16x16x32_bf16 v[16:19], v[178:181], v[238:241], v[16:19]
	s_setprio 0
	s_barrier
; #define PG8_STAGE(bufoff, gbase, voff) do { _Pragma("unroll") for (int _i = 0; _i < 2; ++_i) \
;         __builtin_amdgcn_global_load_lds((const unsigned*)((const char*)(gbase) + (voff)[_i]), (PG8_LAS unsigned*)(lds + (bufoff) + ldsw + _i * 8192), 16, 0, 0); } while (0)
; #define PG8_LDA(dst, b, h) do { _Pragma("unroll") for (int m = 0; m < 4; ++m) _Pragma("unroll") for (int k = 0; k < 2; ++k) dst[m][k] = *(const PG8_LAS bf16x8*)(lds + PG8_SA(b, h) + aoff + m * 2048 + k * 1024); } while (0)
; #define PG8_MMA(ai, bj, At, Bt) do { __builtin_amdgcn_s_setprio(1); _Pragma("unroll") for (int m = 0; m < 4; ++m) _Pragma("unroll") for (int n = 0; n < 2; ++n) _Pragma("unroll") for (int k = 0; k < 2; ++k) \
;         acc[ai][bj][m][n] = __builtin_amdgcn_mfma_f32_16x16x32_bf16(Bt[n][k], At[m][k], acc[ai][bj][m][n], 0, 0, 0); __builtin_amdgcn_s_setprio(0); } while (0)
; #define PG8_WAIT_V(n) asm volatile("s_waitcnt vmcnt(" #n ")" ::: "memory")
; #define PG8_WAIT_L(n) asm volatile("s_waitcnt lgkmcnt(" #n ")" ::: "memory")
; #define PG8_BAR __builtin_amdgcn_s_barrier()
; #define PG8_SCHED __builtin_amdgcn_sched_barrier(0)
; template <class Epi, class Sched, bool ALIGN_EPI = false, bool SP2 = false>
; __device__ __forceinline__ void gemm_phase(PG8_LAS unsigned char* lds, const Gemm g, const Sched& S, const Epi& E) {
;     ...
;         for (int t = 0; t < nt; t += 2) {
;     ...
;             PG8_LDA(At, 1, 1); PG8_STAGE(PG8_SB(1, 0), b3, voffB); PG8_STAGE(PG8_SB(1, 1), b3 + hstep, voffB); PG8_STAGE(PG8_SA(1, 0), a3, voffA);
;             PG8_WAIT_V(8); PG8_WAIT_L(0); PG8_BAR; PG8_MMA(1, 0, At, B0); PG8_MMA(1, 1, At, B1); PG8_BAR; PG8_SCHED;
;     ...
;         if constexpr (ALIGN_EPI) { if (wr == 0) PG8_BAR; }
	s_add_i32 s56, s66, s20
	v_lshl_add_u64 v[148:149], v[148:149], 0, s[36:37]
	s_mov_b32 m0, s56
	ds_read_b128 v[200:203], v152 offset:49152
	ds_read_b128 v[204:207], v152 offset:50176
	ds_read_b128 v[208:211], v152 offset:51200
	ds_read_b128 v[222:225], v152 offset:52224
	ds_read_b128 v[226:229], v152 offset:53248
	ds_read_b128 v[230:233], v152 offset:54272
	ds_read_b128 v[234:237], v152 offset:55296
	ds_read_b128 v[238:241], v152 offset:56320
	global_load_lds_dwordx4 v[148:149], off
	s_add_i32 m0, s56, 0x2000
	s_add_u32 s40, s40, 0x40080
	v_lshl_add_u64 v[148:149], v[184:185], 0, s[36:37]
	s_addc_u32 s41, s41, 0
	s_add_i32 s56, s67, s20
	global_load_lds_dwordx4 v[148:149], off
	v_lshl_add_u64 v[148:149], s[40:41], 0, v[130:131]
	s_mov_b32 m0, s56
	s_nop 0
	global_load_lds_dwordx4 v[148:149], off
	v_lshl_add_u64 v[148:149], s[40:41], 0, v[132:133]
	s_add_i32 m0, s56, 0x2000
	s_nop 0
	global_load_lds_dwordx4 v[148:149], off
	v_lshl_add_u64 v[148:149], v[186:187], 0, s[36:37]
	s_mov_b32 m0, s45
	s_nop 0
	global_load_lds_dwordx4 v[148:149], off
	v_lshl_add_u64 v[148:149], v[212:213], 0, s[36:37]
	s_mov_b32 m0, s53
	s_nop 0
	global_load_lds_dwordx4 v[148:149], off
	s_waitcnt vmcnt(8)
	s_waitcnt lgkmcnt(0)
	s_barrier
	s_setprio 1
	v_mfma_f32_16x16x32_bf16 v[108:111], v[144:147], v[200:203], v[108:111]
	v_mfma_f32_16x16x32_bf16 v[76:79], v[158:161], v[200:203], v[76:79]
	v_mfma_f32_16x16x32_bf16 v[104:107], v[144:147], v[208:211], v[104:107]
	v_mfma_f32_16x16x32_bf16 v[72:75], v[158:161], v[208:211], v[72:75]
	v_mfma_f32_16x16x32_bf16 v[100:103], v[144:147], v[226:229], v[100:103]
	v_mfma_f32_16x16x32_bf16 v[68:71], v[158:161], v[226:229], v[68:71]
	v_mfma_f32_16x16x32_bf16 v[96:99], v[144:147], v[234:237], v[96:99]
	v_mfma_f32_16x16x32_bf16 v[64:67], v[158:161], v[234:237], v[64:67]
	v_mfma_f32_16x16x32_bf16 v[108:111], v[154:157], v[204:207], v[108:111]
	v_mfma_f32_16x16x32_bf16 v[76:79], v[162:165], v[204:207], v[76:79]
	v_mfma_f32_16x16x32_bf16 v[104:107], v[154:157], v[222:225], v[104:107]
	v_mfma_f32_16x16x32_bf16 v[72:75], v[162:165], v[222:225], v[72:75]
	v_mfma_f32_16x16x32_bf16 v[100:103], v[154:157], v[230:233], v[100:103]
	v_mfma_f32_16x16x32_bf16 v[68:71], v[162:165], v[230:233], v[68:71]
	v_mfma_f32_16x16x32_bf16 v[96:99], v[154:157], v[238:241], v[96:99]
	v_mfma_f32_16x16x32_bf16 v[64:67], v[162:165], v[238:241], v[64:67]
	s_setprio 0
	s_setprio 1
	v_mfma_f32_16x16x32_bf16 v[44:47], v[166:169], v[200:203], v[44:47]
	v_mfma_f32_16x16x32_bf16 v[12:15], v[174:177], v[200:203], v[12:15]
	v_mfma_f32_16x16x32_bf16 v[40:43], v[166:169], v[208:211], v[40:43]
	v_mfma_f32_16x16x32_bf16 v[8:11], v[174:177], v[208:211], v[8:11]
	v_mfma_f32_16x16x32_bf16 v[36:39], v[166:169], v[226:229], v[36:39]
	v_mfma_f32_16x16x32_bf16 v[4:7], v[174:177], v[226:229], v[4:7]
	v_mfma_f32_16x16x32_bf16 v[32:35], v[166:169], v[234:237], v[32:35]
	v_mfma_f32_16x16x32_bf16 v[0:3], v[174:177], v[234:237], v[0:3]
	v_mfma_f32_16x16x32_bf16 v[44:47], v[170:173], v[204:207], v[44:47]
	v_mfma_f32_16x16x32_bf16 v[12:15], v[178:181], v[204:207], v[12:15]
	v_mfma_f32_16x16x32_bf16 v[40:43], v[170:173], v[222:225], v[40:43]
	v_mfma_f32_16x16x32_bf16 v[8:11], v[178:181], v[222:225], v[8:11]
	v_mfma_f32_16x16x32_bf16 v[36:39], v[170:173], v[230:233], v[36:39]
	v_mfma_f32_16x16x32_bf16 v[4:7], v[178:181], v[230:233], v[4:7]
	v_mfma_f32_16x16x32_bf16 v[32:35], v[170:173], v[238:241], v[32:35]
	v_mfma_f32_16x16x32_bf16 v[0:3], v[178:181], v[238:241], v[0:3]
	s_setprio 0
	s_barrier
	s_add_i32 s60, s60, 2
	s_add_u32 s54, s54, 0x100
	s_addc_u32 s55, s55, 0
	s_add_u32 s65, s65, 0x100
	s_addc_u32 s61, s61, 0
	s_cmp_gt_u32 s60, 13
	s_cbranch_scc0 .LBB0_160
	s_and_b64 vcc, exec, s[8:9]
	s_cbranch_vccz .LBB0_163
	s_barrier

; #define PG8_STAGE(bufoff, gbase, voff) do { _Pragma("unroll") for (int _i = 0; _i < 2; ++_i) \
;         __builtin_amdgcn_global_load_lds((const unsigned*)((const char*)(gbase) + (voff)[_i]), (PG8_LAS unsigned*)(lds + (bufoff) + ldsw + _i * 8192), 16, 0, 0); } while (0)
; #define PG8_LDA(dst, b, h) do { _Pragma("unroll") for (int m = 0; m < 4; ++m) _Pragma("unroll") for (int k = 0; k < 2; ++k) dst[m][k] = *(const PG8_LAS bf16x8*)(lds + PG8_SA(b, h) + aoff + m * 2048 + k * 1024); } while (0)
; #define PG8_LDB(dst, b, h) do { _Pragma("unroll") for (int n = 0; n < 2; ++n) _Pragma("unroll") for (int k = 0; k < 2; ++k) dst[n][k] = *(const PG8_LAS bf16x8*)(lds + PG8_SB(b, h) + boff + n * 2048 + k * 1024); } while (0)
; #define PG8_MMA(ai, bj, At, Bt) do { __builtin_amdgcn_s_setprio(1); _Pragma("unroll") for (int m = 0; m < 4; ++m) _Pragma("unroll") for (int n = 0; n < 2; ++n) _Pragma("unroll") for (int k = 0; k < 2; ++k) \
;         acc[ai][bj][m][n] = __builtin_amdgcn_mfma_f32_16x16x32_bf16(Bt[n][k], At[m][k], acc[ai][bj][m][n], 0, 0, 0); __builtin_amdgcn_s_setprio(0); } while (0)
; #define PG8_WAIT_V(n) asm volatile("s_waitcnt vmcnt(" #n ")" ::: "memory")
; #define PG8_WAIT_L(n) asm volatile("s_waitcnt lgkmcnt(" #n ")" ::: "memory")
; template <class Epi, class Sched, bool ALIGN_EPI = false, bool SP2 = false>
; __device__ __forceinline__ void gemm_phase(PG8_LAS unsigned char* lds, const Gemm g, const Sched& S, const Epi& E) {
;     ...
;             const bool last = (t == nt - 2);
;             const char* a1 = cA + (size_t)(t + 1) * kstep;
;             const char* a2 = last ? nA : cA + (size_t)(t + 2) * kstep; const char* b2 = last ? nB : cB + (size_t)(t + 2) * kstep;
;             const char* a3 = a2 + kstep; const char* b3 = b2 + kstep;
;             if (last && has_next) S.a_ready(nxt);
;             if constexpr (SP2) {
;             PG8_LDB(B0, 0, 0); PG8_LDB(B1, 0, 1); PG8_SCHED; PG8_LDA(At, 0, 0); PG8_STAGE(PG8_SA(1, 1), a1 + hstep, voffA);
;             PG8_WAIT_V(8); PG8_WAIT_L(0); PG8_BAR; PG8_MMA(0, 0, At, B0); PG8_MMA(0, 1, At, B1); PG8_BAR; PG8_SCHED;
;             PG8_LDA(At, 0, 1); PG8_STAGE(PG8_SB(0, 0), b2, voffB); PG8_STAGE(PG8_SB(0, 1), b2 + hstep, voffB); PG8_STAGE(PG8_SA(0, 0), a2, voffA);
;             PG8_WAIT_V(8); PG8_WAIT_L(0); PG8_BAR; PG8_MMA(1, 0, At, B0); PG8_MMA(1, 1, At, B1); PG8_BAR; PG8_SCHED;
.LBB0_435:
	s_add_u32 s0, s2, s62
	s_addc_u32 s1, s3, s63
	s_add_u32 s0, s0, 0x100
	s_addc_u32 s1, s1, 0
	s_add_u32 s60, s44, s62
	s_addc_u32 s61, s58, s63
	s_add_i32 s65, 0, 0x10000
	s_cmpk_eq_i32 s62, 0x700
	s_cselect_b32 s41, s11, s1
	s_cselect_b32 s40, s24, s0
	v_add_u32_e32 v112, s65, v159
	s_cselect_b32 s1, s39, s61
	s_cselect_b32 s0, s43, s60
	s_add_i32 s66, 0, 0x14000
	ds_read_b128 v[132:135], v112
	ds_read_b128 v[136:139], v112 offset:1024
	ds_read_b128 v[162:165], v112 offset:2048
	ds_read_b128 v[166:169], v112 offset:3072
	v_add_u32_e32 v112, s66, v159
	ds_read_b128 v[170:173], v112
	ds_read_b128 v[174:177], v112 offset:1024
	ds_read_b128 v[178:181], v112 offset:2048
	ds_read_b128 v[184:187], v112 offset:3072
	v_lshl_add_u64 v[114:115], v[152:153], 0, s[62:63]
	s_add_i32 m0, s20, 0xc000
	ds_read_b128 v[200:203], v161
	ds_read_b128 v[204:207], v161 offset:1024
	ds_read_b128 v[208:211], v161 offset:2048
	ds_read_b128 v[224:227], v161 offset:3072
	ds_read_b128 v[228:231], v161 offset:4096
	ds_read_b128 v[232:235], v161 offset:5120
	ds_read_b128 v[236:239], v161 offset:6144
	ds_read_b128 v[240:243], v161 offset:7168
	global_load_lds_dwordx4 v[114:115], off
	v_lshl_add_u64 v[114:115], v[154:155], 0, s[62:63]
	s_add_i32 m0, s20, 0xe000
	s_nop 0
	global_load_lds_dwordx4 v[114:115], off
	s_waitcnt vmcnt(8)
	s_waitcnt lgkmcnt(0)
	s_barrier
	s_setprio 1
	v_mfma_f32_16x16x32_bf16 v[128:131], v[132:135], v[200:203], v[128:131]
	v_mfma_f32_16x16x32_bf16 v[124:127], v[162:165], v[200:203], v[124:127]
	v_mfma_f32_16x16x32_bf16 v[108:111], v[132:135], v[208:211], v[108:111]
	v_mfma_f32_16x16x32_bf16 v[104:107], v[162:165], v[208:211], v[104:107]
	v_mfma_f32_16x16x32_bf16 v[92:95], v[132:135], v[228:231], v[92:95]
	v_mfma_f32_16x16x32_bf16 v[88:91], v[162:165], v[228:231], v[88:91]
	v_mfma_f32_16x16x32_bf16 v[76:79], v[132:135], v[236:239], v[76:79]
	v_mfma_f32_16x16x32_bf16 v[72:75], v[162:165], v[236:239], v[72:75]
	v_mfma_f32_16x16x32_bf16 v[128:131], v[136:139], v[204:207], v[128:131]
	v_mfma_f32_16x16x32_bf16 v[124:127], v[166:169], v[204:207], v[124:127]
	v_mfma_f32_16x16x32_bf16 v[108:111], v[136:139], v[224:227], v[108:111]
	v_mfma_f32_16x16x32_bf16 v[104:107], v[166:169], v[224:227], v[104:107]
	v_mfma_f32_16x16x32_bf16 v[92:95], v[136:139], v[232:235], v[92:95]
	v_mfma_f32_16x16x32_bf16 v[88:91], v[166:169], v[232:235], v[88:91]
	v_mfma_f32_16x16x32_bf16 v[76:79], v[136:139], v[240:243], v[76:79]
	v_mfma_f32_16x16x32_bf16 v[72:75], v[166:169], v[240:243], v[72:75]
	s_setprio 0
	s_setprio 1
	v_mfma_f32_16x16x32_bf16 v[120:123], v[170:173], v[200:203], v[120:123]
	v_mfma_f32_16x16x32_bf16 v[114:117], v[178:181], v[200:203], v[116:119]
	v_mfma_f32_16x16x32_bf16 v[100:103], v[170:173], v[208:211], v[100:103]
	v_mfma_f32_16x16x32_bf16 v[96:99], v[178:181], v[208:211], v[96:99]
	v_mfma_f32_16x16x32_bf16 v[84:87], v[170:173], v[228:231], v[84:87]
	v_mfma_f32_16x16x32_bf16 v[80:83], v[178:181], v[228:231], v[80:83]
	v_mfma_f32_16x16x32_bf16 v[68:71], v[170:173], v[236:239], v[68:71]
	v_mfma_f32_16x16x32_bf16 v[64:67], v[178:181], v[236:239], v[64:67]
	v_mfma_f32_16x16x32_bf16 v[120:123], v[174:177], v[204:207], v[120:123]
	v_mfma_f32_16x16x32_bf16 v[114:117], v[184:187], v[204:207], v[114:117]
	v_mfma_f32_16x16x32_bf16 v[100:103], v[174:177], v[224:227], v[100:103]
	v_mfma_f32_16x16x32_bf16 v[96:99], v[184:187], v[224:227], v[96:99]
	v_mfma_f32_16x16x32_bf16 v[84:87], v[174:177], v[232:235], v[84:87]
	v_mfma_f32_16x16x32_bf16 v[80:83], v[184:187], v[232:235], v[80:83]
	v_mfma_f32_16x16x32_bf16 v[68:71], v[174:177], v[240:243], v[68:71]
	v_mfma_f32_16x16x32_bf16 v[64:67], v[184:187], v[240:243], v[64:67]
	s_setprio 0
	s_barrier
	s_add_i32 s60, s65, s19
	v_lshl_add_u64 v[156:157], s[0:1], 0, v[142:143]
	s_mov_b32 m0, s60
	ds_read_b128 v[200:203], v161 offset:16384
	ds_read_b128 v[204:207], v161 offset:17408
	ds_read_b128 v[208:211], v161 offset:18432
	ds_read_b128 v[224:227], v161 offset:19456
	ds_read_b128 v[228:231], v161 offset:20480
	ds_read_b128 v[232:235], v161 offset:21504
	ds_read_b128 v[236:239], v161 offset:22528
	ds_read_b128 v[240:243], v161 offset:23552
	global_load_lds_dwordx4 v[156:157], off
	s_add_i32 m0, s60, 0x2000
	s_add_u32 s60, s0, 0x40000
	v_lshl_add_u64 v[212:213], s[0:1], 0, v[146:147]
	s_addc_u32 s61, s1, 0
	s_add_i32 s65, s66, s19
	global_load_lds_dwordx4 v[212:213], off
	v_lshl_add_u64 v[118:119], s[60:61], 0, v[142:143]
	s_mov_b32 m0, s65
	v_lshl_add_u64 v[244:245], s[40:41], 0, v[140:141]
	global_load_lds_dwordx4 v[118:119], off
	v_lshl_add_u64 v[118:119], s[60:61], 0, v[146:147]
	s_add_i32 m0, s65, 0x2000
	v_lshl_add_u64 v[246:247], s[40:41], 0, v[144:145]
	global_load_lds_dwordx4 v[118:119], off
	s_mov_b32 m0, s20
	s_nop 0
	global_load_lds_dwordx4 v[244:245], off
	s_mov_b32 m0, s21
	s_nop 0
	global_load_lds_dwordx4 v[246:247], off
	s_waitcnt vmcnt(8)
	s_waitcnt lgkmcnt(0)
	s_barrier
; #define PG8_STAGE(bufoff, gbase, voff) do { _Pragma("unroll") for (int _i = 0; _i < 2; ++_i) \
;         __builtin_amdgcn_global_load_lds((const unsigned*)((const char*)(gbase) + (voff)[_i]), (PG8_LAS unsigned*)(lds + (bufoff) + ldsw + _i * 8192), 16, 0, 0); } while (0)
; #define PG8_LDA(dst, b, h) do { _Pragma("unroll") for (int m = 0; m < 4; ++m) _Pragma("unroll") for (int k = 0; k < 2; ++k) dst[m][k] = *(const PG8_LAS bf16x8*)(lds + PG8_SA(b, h) + aoff + m * 2048 + k * 1024); } while (0)
; #define PG8_LDB(dst, b, h) do { _Pragma("unroll") for (int n = 0; n < 2; ++n) _Pragma("unroll") for (int k = 0; k < 2; ++k) dst[n][k] = *(const PG8_LAS bf16x8*)(lds + PG8_SB(b, h) + boff + n * 2048 + k * 1024); } while (0)
; #define PG8_MMA(ai, bj, At, Bt) do { __builtin_amdgcn_s_setprio(1); _Pragma("unroll") for (int m = 0; m < 4; ++m) _Pragma("unroll") for (int n = 0; n < 2; ++n) _Pragma("unroll") for (int k = 0; k < 2; ++k) \
;         acc[ai][bj][m][n] = __builtin_amdgcn_mfma_f32_16x16x32_bf16(Bt[n][k], At[m][k], acc[ai][bj][m][n], 0, 0, 0); __builtin_amdgcn_s_setprio(0); } while (0)
; #define PG8_WAIT_V(n) asm volatile("s_waitcnt vmcnt(" #n ")" ::: "memory")
; #define PG8_WAIT_L(n) asm volatile("s_waitcnt lgkmcnt(" #n ")" ::: "memory")
; #define PG8_BAR __builtin_amdgcn_s_barrier()
; #define PG8_SCHED __builtin_amdgcn_sched_barrier(0)
; template <class Epi, class Sched, bool ALIGN_EPI = false, bool SP2 = false>
; __device__ __forceinline__ void gemm_phase(PG8_LAS unsigned char* lds, const Gemm g, const Sched& S, const Epi& E) {
;     ...
;             PG8_WAIT_V(8); PG8_WAIT_L(0); PG8_BAR; PG8_MMA(1, 0, At, B0); PG8_MMA(1, 1, At, B1); PG8_BAR; PG8_SCHED;
;             PG8_LDB(B0, 1, 0); PG8_LDB(B1, 1, 1); PG8_SCHED; PG8_LDA(At, 1, 0); PG8_STAGE(PG8_SA(0, 1), a2 + hstep, voffA);
;             PG8_WAIT_V(8); PG8_WAIT_L(0); PG8_BAR; PG8_MMA(0, 0, At, B0); PG8_MMA(0, 1, At, B1); PG8_BAR; PG8_SCHED;
	s_setprio 1
	v_mfma_f32_16x16x32_bf16 v[60:63], v[132:135], v[200:203], v[60:63]
	v_mfma_f32_16x16x32_bf16 v[56:59], v[162:165], v[200:203], v[56:59]
	v_mfma_f32_16x16x32_bf16 v[44:47], v[132:135], v[208:211], v[44:47]
	v_mfma_f32_16x16x32_bf16 v[40:43], v[162:165], v[208:211], v[40:43]
	v_mfma_f32_16x16x32_bf16 v[28:31], v[132:135], v[228:231], v[28:31]
	v_mfma_f32_16x16x32_bf16 v[24:27], v[162:165], v[228:231], v[24:27]
	v_mfma_f32_16x16x32_bf16 v[12:15], v[132:135], v[236:239], v[12:15]
	v_mfma_f32_16x16x32_bf16 v[8:11], v[162:165], v[236:239], v[8:11]
	v_mfma_f32_16x16x32_bf16 v[60:63], v[136:139], v[204:207], v[60:63]
	v_mfma_f32_16x16x32_bf16 v[56:59], v[166:169], v[204:207], v[56:59]
	v_mfma_f32_16x16x32_bf16 v[44:47], v[136:139], v[224:227], v[44:47]
	v_mfma_f32_16x16x32_bf16 v[40:43], v[166:169], v[224:227], v[40:43]
	v_mfma_f32_16x16x32_bf16 v[28:31], v[136:139], v[232:235], v[28:31]
	v_mfma_f32_16x16x32_bf16 v[24:27], v[166:169], v[232:235], v[24:27]
	v_mfma_f32_16x16x32_bf16 v[12:15], v[136:139], v[240:243], v[12:15]
	v_mfma_f32_16x16x32_bf16 v[8:11], v[166:169], v[240:243], v[8:11]
	s_setprio 0
	s_setprio 1
	v_mfma_f32_16x16x32_bf16 v[52:55], v[170:173], v[200:203], v[52:55]
	v_mfma_f32_16x16x32_bf16 v[48:51], v[178:181], v[200:203], v[48:51]
	v_mfma_f32_16x16x32_bf16 v[36:39], v[170:173], v[208:211], v[36:39]
	v_mfma_f32_16x16x32_bf16 v[32:35], v[178:181], v[208:211], v[32:35]
	v_mfma_f32_16x16x32_bf16 v[20:23], v[170:173], v[228:231], v[20:23]
	v_mfma_f32_16x16x32_bf16 v[16:19], v[178:181], v[228:231], v[16:19]
	v_mfma_f32_16x16x32_bf16 v[4:7], v[170:173], v[236:239], v[4:7]
	v_mfma_f32_16x16x32_bf16 v[0:3], v[178:181], v[236:239], v[0:3]
	v_mfma_f32_16x16x32_bf16 v[52:55], v[174:177], v[204:207], v[52:55]
	v_mfma_f32_16x16x32_bf16 v[48:51], v[184:187], v[204:207], v[48:51]
	v_mfma_f32_16x16x32_bf16 v[36:39], v[174:177], v[224:227], v[36:39]
	v_mfma_f32_16x16x32_bf16 v[32:35], v[184:187], v[224:227], v[32:35]
	v_mfma_f32_16x16x32_bf16 v[20:23], v[174:177], v[232:235], v[20:23]
	v_mfma_f32_16x16x32_bf16 v[16:19], v[184:187], v[232:235], v[16:19]
	v_mfma_f32_16x16x32_bf16 v[4:7], v[174:177], v[240:243], v[4:7]
	v_mfma_f32_16x16x32_bf16 v[0:3], v[184:187], v[240:243], v[0:3]
	s_setprio 0
	s_barrier
	s_add_i32 s60, 0, 0x18000
	v_add_u32_e32 v112, s60, v159
	s_add_i32 s61, 0, 0x1c000
	ds_read_b128 v[132:135], v112
	ds_read_b128 v[136:139], v112 offset:1024
	ds_read_b128 v[162:165], v112 offset:2048
	ds_read_b128 v[166:169], v112 offset:3072
	v_add_u32_e32 v112, s61, v159
	ds_read_b128 v[170:173], v112
	ds_read_b128 v[174:177], v112 offset:1024
	ds_read_b128 v[178:181], v112 offset:2048
	ds_read_b128 v[184:187], v112 offset:3072
	s_add_u32 s40, s40, 0x40000
	s_addc_u32 s41, s41, 0
	s_mov_b32 m0, s22
	v_lshl_add_u64 v[118:119], s[40:41], 0, v[140:141]
	ds_read_b128 v[200:203], v161 offset:32768
	ds_read_b128 v[204:207], v161 offset:33792
	ds_read_b128 v[208:211], v161 offset:34816
	ds_read_b128 v[224:227], v161 offset:35840
	ds_read_b128 v[228:231], v161 offset:36864
	ds_read_b128 v[232:235], v161 offset:37888
	ds_read_b128 v[236:239], v161 offset:38912
	ds_read_b128 v[240:243], v161 offset:39936
	global_load_lds_dwordx4 v[118:119], off
	v_lshl_add_u64 v[118:119], s[40:41], 0, v[144:145]
	s_mov_b32 m0, s23
	s_nop 0
	global_load_lds_dwordx4 v[118:119], off
	s_waitcnt vmcnt(8)
	s_waitcnt lgkmcnt(0)
	s_barrier
	s_setprio 1
	v_mfma_f32_16x16x32_bf16 v[128:131], v[132:135], v[200:203], v[128:131]
	v_mfma_f32_16x16x32_bf16 v[124:127], v[162:165], v[200:203], v[124:127]
	v_mfma_f32_16x16x32_bf16 v[108:111], v[132:135], v[208:211], v[108:111]
	v_mfma_f32_16x16x32_bf16 v[104:107], v[162:165], v[208:211], v[104:107]
	v_mfma_f32_16x16x32_bf16 v[92:95], v[132:135], v[228:231], v[92:95]
	v_mfma_f32_16x16x32_bf16 v[88:91], v[162:165], v[228:231], v[88:91]
	v_mfma_f32_16x16x32_bf16 v[76:79], v[132:135], v[236:239], v[76:79]
	v_mfma_f32_16x16x32_bf16 v[72:75], v[162:165], v[236:239], v[72:75]
	v_mfma_f32_16x16x32_bf16 v[128:131], v[136:139], v[204:207], v[128:131]
	v_mfma_f32_16x16x32_bf16 v[124:127], v[166:169], v[204:207], v[124:127]
	v_mfma_f32_16x16x32_bf16 v[108:111], v[136:139], v[224:227], v[108:111]
	v_mfma_f32_16x16x32_bf16 v[104:107], v[166:169], v[224:227], v[104:107]
	v_mfma_f32_16x16x32_bf16 v[92:95], v[136:139], v[232:235], v[92:95]
	v_mfma_f32_16x16x32_bf16 v[88:91], v[166:169], v[232:235], v[88:91]
	v_mfma_f32_16x16x32_bf16 v[76:79], v[136:139], v[240:243], v[76:79]
	v_mfma_f32_16x16x32_bf16 v[72:75], v[166:169], v[240:243], v[72:75]
	s_setprio 0
	s_setprio 1
	v_mfma_f32_16x16x32_bf16 v[118:121], v[170:173], v[200:203], v[120:123]
	v_mfma_f32_16x16x32_bf16 v[114:117], v[178:181], v[200:203], v[114:117]
	v_mfma_f32_16x16x32_bf16 v[100:103], v[170:173], v[208:211], v[100:103]
	v_mfma_f32_16x16x32_bf16 v[96:99], v[178:181], v[208:211], v[96:99]
	v_mfma_f32_16x16x32_bf16 v[84:87], v[170:173], v[228:231], v[84:87]
	v_mfma_f32_16x16x32_bf16 v[80:83], v[178:181], v[228:231], v[80:83]
	v_mfma_f32_16x16x32_bf16 v[68:71], v[170:173], v[236:239], v[68:71]
	v_mfma_f32_16x16x32_bf16 v[64:67], v[178:181], v[236:239], v[64:67]
	v_mfma_f32_16x16x32_bf16 v[120:123], v[174:177], v[204:207], v[118:121]
	v_mfma_f32_16x16x32_bf16 v[116:119], v[184:187], v[204:207], v[114:117]
	v_mfma_f32_16x16x32_bf16 v[100:103], v[174:177], v[224:227], v[100:103]
	v_mfma_f32_16x16x32_bf16 v[96:99], v[184:187], v[224:227], v[96:99]
	v_mfma_f32_16x16x32_bf16 v[84:87], v[174:177], v[232:235], v[84:87]
	v_mfma_f32_16x16x32_bf16 v[80:83], v[184:187], v[232:235], v[80:83]
	v_mfma_f32_16x16x32_bf16 v[68:71], v[174:177], v[240:243], v[68:71]
	v_mfma_f32_16x16x32_bf16 v[64:67], v[184:187], v[240:243], v[64:67]
	s_setprio 0
	s_barrier
; #define PG8_STAGE(bufoff, gbase, voff) do { _Pragma("unroll") for (int _i = 0; _i < 2; ++_i) \
;         __builtin_amdgcn_global_load_lds((const unsigned*)((const char*)(gbase) + (voff)[_i]), (PG8_LAS unsigned*)(lds + (bufoff) + ldsw + _i * 8192), 16, 0, 0); } while (0)
; #define PG8_LDA(dst, b, h) do { _Pragma("unroll") for (int m = 0; m < 4; ++m) _Pragma("unroll") for (int k = 0; k < 2; ++k) dst[m][k] = *(const PG8_LAS bf16x8*)(lds + PG8_SA(b, h) + aoff + m * 2048 + k * 1024); } while (0)
; #define PG8_MMA(ai, bj, At, Bt) do { __builtin_amdgcn_s_setprio(1); _Pragma("unroll") for (int m = 0; m < 4; ++m) _Pragma("unroll") for (int n = 0; n < 2; ++n) _Pragma("unroll") for (int k = 0; k < 2; ++k) \
;         acc[ai][bj][m][n] = __builtin_amdgcn_mfma_f32_16x16x32_bf16(Bt[n][k], At[m][k], acc[ai][bj][m][n], 0, 0, 0); __builtin_amdgcn_s_setprio(0); } while (0)
; template <class Epi, class Sched, bool ALIGN_EPI = false, bool SP2 = false>
; __device__ __forceinline__ void gemm_phase(PG8_LAS unsigned char* lds, const Gemm g, const Sched& S, const Epi& E) {
;     ...
;             PG8_LDA(At, 1, 1); PG8_STAGE(PG8_SB(1, 0), b3, voffB); PG8_STAGE(PG8_SB(1, 1), b3 + hstep, voffB); PG8_STAGE(PG8_SA(1, 0), a3, voffA);
;             PG8_WAIT_V(8); PG8_WAIT_L(0); PG8_BAR; PG8_MMA(1, 0, At, B0); PG8_MMA(1, 1, At, B1); PG8_BAR; PG8_SCHED;
;     __device__ __forceinline__ void mid(acc_t& acc, const Unit& u, int, int, int, int) const {
;         int tid = threadIdx.x; asm volatile("" : "+v"(tid));
;         const int wid = tid >> 6, lane = tid & 63, wr = wid >> 2, wc = wid & 3, fr = lane & 15, fq = lane >> 4;
;         const int row0 = u.pm * 256 + wr * 64 + fr, col0 = u.pn * 256 + wc * 32 + 8 * fq;
; #pragma unroll
;         for (int ai = 0; ai < 2; ++ai)
; #pragma unroll
;             for (int m = 0; m < 4; ++m) { const bf16_t* gr = gates + (size_t)(row0 + ai * 128 + m * 16) * 2048 + col0;
; #pragma unroll
;                 for (int bj = 0; bj < 2; ++bj) { f32x4 a0, a1, b0, b1; unpack8(*(const u32x4*)(gr + bj * 128), a0, a1); unpack8(*(const u32x4*)(gr + 1024 + bj * 128), b0, b1);
; #pragma unroll
;                     for (int j = 0; j < 4; ++j) { a0[j] *= __builtin_amdgcn_rcpf(fmaxf(b0[j], 1e-20f)); a1[j] *= __builtin_amdgcn_rcpf(fmaxf(b1[j], 1e-20f)); }
;                     acc[ai][bj][m][0] *= a0; acc[ai][bj][m][1] *= a1; }
;                 asm volatile("" ::: "memory"); }
	s_add_i32 s40, s60, s19
	v_lshl_add_u64 v[114:115], v[156:157], 0, s[36:37]
	s_mov_b32 m0, s40
	ds_read_b128 v[200:203], v161 offset:49152
	ds_read_b128 v[204:207], v161 offset:50176
	ds_read_b128 v[208:211], v161 offset:51200
	ds_read_b128 v[224:227], v161 offset:52224
	ds_read_b128 v[228:231], v161 offset:53248
	ds_read_b128 v[232:235], v161 offset:54272
	ds_read_b128 v[236:239], v161 offset:55296
	ds_read_b128 v[240:243], v161 offset:56320
	global_load_lds_dwordx4 v[114:115], off
	s_add_i32 m0, s40, 0x2000
	s_add_u32 s0, s0, 0x40080
	v_lshl_add_u64 v[114:115], v[212:213], 0, s[36:37]
	s_addc_u32 s1, s1, 0
	s_add_i32 s40, s61, s19
	global_load_lds_dwordx4 v[114:115], off
	v_lshl_add_u64 v[114:115], s[0:1], 0, v[142:143]
	s_mov_b32 m0, s40
	s_nop 0
	global_load_lds_dwordx4 v[114:115], off
	v_lshl_add_u64 v[114:115], s[0:1], 0, v[146:147]
	s_add_i32 m0, s40, 0x2000
	s_nop 0
	global_load_lds_dwordx4 v[114:115], off
	v_lshl_add_u64 v[114:115], v[244:245], 0, s[36:37]
	s_mov_b32 m0, s45
	s_nop 0
	global_load_lds_dwordx4 v[114:115], off
	v_lshl_add_u64 v[114:115], v[246:247], 0, s[36:37]
	s_mov_b32 m0, s53
	s_nop 0
	global_load_lds_dwordx4 v[114:115], off
	s_waitcnt vmcnt(8)
	s_waitcnt lgkmcnt(0)
	s_barrier
	s_setprio 1
	v_mfma_f32_16x16x32_bf16 v[60:63], v[132:135], v[200:203], v[60:63]
	v_mfma_f32_16x16x32_bf16 v[56:59], v[162:165], v[200:203], v[56:59]
	v_mfma_f32_16x16x32_bf16 v[44:47], v[132:135], v[208:211], v[44:47]
	v_mfma_f32_16x16x32_bf16 v[40:43], v[162:165], v[208:211], v[40:43]
	v_mfma_f32_16x16x32_bf16 v[28:31], v[132:135], v[228:231], v[28:31]
	v_mfma_f32_16x16x32_bf16 v[24:27], v[162:165], v[228:231], v[24:27]
	v_mfma_f32_16x16x32_bf16 v[12:15], v[132:135], v[236:239], v[12:15]
	v_mfma_f32_16x16x32_bf16 v[8:11], v[162:165], v[236:239], v[8:11]
	v_mfma_f32_16x16x32_bf16 v[60:63], v[136:139], v[204:207], v[60:63]
	v_mfma_f32_16x16x32_bf16 v[56:59], v[166:169], v[204:207], v[56:59]
	v_mfma_f32_16x16x32_bf16 v[44:47], v[136:139], v[224:227], v[44:47]
	v_mfma_f32_16x16x32_bf16 v[40:43], v[166:169], v[224:227], v[40:43]
	v_mfma_f32_16x16x32_bf16 v[28:31], v[136:139], v[232:235], v[28:31]
	v_mfma_f32_16x16x32_bf16 v[24:27], v[166:169], v[232:235], v[24:27]
	v_mfma_f32_16x16x32_bf16 v[12:15], v[136:139], v[240:243], v[12:15]
	v_mfma_f32_16x16x32_bf16 v[8:11], v[166:169], v[240:243], v[8:11]
	s_setprio 0
	s_setprio 1
	v_mfma_f32_16x16x32_bf16 v[52:55], v[170:173], v[200:203], v[52:55]
	v_mfma_f32_16x16x32_bf16 v[48:51], v[178:181], v[200:203], v[48:51]
	v_mfma_f32_16x16x32_bf16 v[36:39], v[170:173], v[208:211], v[36:39]
	v_mfma_f32_16x16x32_bf16 v[32:35], v[178:181], v[208:211], v[32:35]
	v_mfma_f32_16x16x32_bf16 v[20:23], v[170:173], v[228:231], v[20:23]
	v_mfma_f32_16x16x32_bf16 v[16:19], v[178:181], v[228:231], v[16:19]
	v_mfma_f32_16x16x32_bf16 v[4:7], v[170:173], v[236:239], v[4:7]
	v_mfma_f32_16x16x32_bf16 v[0:3], v[178:181], v[236:239], v[0:3]
	v_mfma_f32_16x16x32_bf16 v[52:55], v[174:177], v[204:207], v[52:55]
	v_mfma_f32_16x16x32_bf16 v[48:51], v[184:187], v[204:207], v[48:51]
	v_mfma_f32_16x16x32_bf16 v[36:39], v[174:177], v[224:227], v[36:39]
	v_mfma_f32_16x16x32_bf16 v[32:35], v[184:187], v[224:227], v[32:35]
	v_mfma_f32_16x16x32_bf16 v[20:23], v[174:177], v[232:235], v[20:23]
	v_mfma_f32_16x16x32_bf16 v[16:19], v[184:187], v[232:235], v[16:19]
	v_mfma_f32_16x16x32_bf16 v[4:7], v[174:177], v[240:243], v[4:7]
	v_mfma_f32_16x16x32_bf16 v[0:3], v[184:187], v[240:243], v[0:3]
	s_setprio 0
	s_barrier
	s_cmpk_lg_i32 s62, 0x300
	s_cbranch_scc1 .LBB0_434
	v_mov_b32_e32 v112, v182
	s_movk_i32 s0, 0xffc0
	v_and_b32_e32 v115, 15, v112
	v_ashrrev_i32_e32 v132, 2, v112
	v_lshrrev_b32_e32 v112, 1, v112
	v_and_b32_e32 v112, 0x78, v112
	v_or_b32_e32 v114, s33, v112
	v_and_or_b32 v112, v132, s0, v115
	v_add_u32_e32 v136, s26, v112
	v_ashrrev_i32_e32 v137, 31, v136
	v_ashrrev_i32_e32 v115, 31, v114
	v_lshlrev_b64 v[132:133], 12, v[136:137]
	v_lshl_add_u64 v[132:133], s[48:49], 0, v[132:133]
	v_lshlrev_b64 v[138:139], 1, v[114:115]
	v_lshl_add_u64 v[114:115], v[132:133], 0, v[138:139]
	global_load_dwordx4 v[132:135], v[114:115], off
	global_load_dwordx4 v[162:165], v[114:115], off offset:2048
	s_mov_b64 s[0:1], 0x80000
	s_waitcnt vmcnt(0)
	v_lshlrev_b32_e32 v112, 16, v162
	v_max_f32_e32 v112, v112, v112
	v_lshlrev_b32_e32 v157, 16, v164
	v_max_f32_e32 v112, 0x1e3ce508, v112
	v_rcp_f32_e32 v156, v112
	v_max_f32_e32 v112, v157, v157
	v_and_b32_e32 v137, 0xffff0000, v162
	v_max_f32_e32 v112, 0x1e3ce508, v112
	v_rcp_f32_e32 v162, v112
	v_max_f32_e32 v112, v137, v137
	v_lshlrev_b32_e32 v166, 16, v163
	v_and_b32_e32 v167, 0xffff0000, v163
	v_and_b32_e32 v163, 0xffff0000, v164
	v_max_f32_e32 v112, 0x1e3ce508, v112
	v_rcp_f32_e32 v157, v112
	v_max_f32_e32 v112, v163, v163
	v_max_f32_e32 v112, 0x1e3ce508, v112
	v_rcp_f32_e32 v163, v112
	v_lshlrev_b32_e32 v168, 16, v165
	v_and_b32_e32 v169, 0xffff0000, v165
	v_lshlrev_b32_e32 v164, 16, v132
	v_and_b32_e32 v165, 0xffff0000, v132
	v_max_f32_e32 v112, v166, v166
	v_pk_mul_f32 v[156:157], v[156:157], v[164:165]
	v_lshlrev_b32_e32 v164, 16, v134
	v_and_b32_e32 v165, 0xffff0000, v134
	v_max_f32_e32 v112, 0x1e3ce508, v112
	v_pk_mul_f32 v[162:163], v[162:163], v[164:165]
	v_rcp_f32_e32 v164, v112
	v_max_f32_e32 v112, v168, v168
	v_max_f32_e32 v112, 0x1e3ce508, v112
	v_rcp_f32_e32 v132, v112
	v_max_f32_e32 v112, v167, v167
	v_max_f32_e32 v112, 0x1e3ce508, v112
	v_rcp_f32_e32 v165, v112
	v_max_f32_e32 v112, v169, v169
	v_max_f32_e32 v112, 0x1e3ce508, v112
	v_lshlrev_b32_e32 v166, 16, v133
	v_and_b32_e32 v167, 0xffff0000, v133
	v_rcp_f32_e32 v133, v112
	v_lshlrev_b32_e32 v134, 16, v135
	v_and_b32_e32 v135, 0xffff0000, v135
	v_pk_mul_f32 v[164:165], v[164:165], v[166:167]
	v_pk_mul_f32 v[132:133], v[132:133], v[134:135]
	v_pk_mul_f32 v[130:131], v[130:131], v[164:165]
	v_pk_mul_f32 v[126:127], v[126:127], v[132:133]
	v_pk_mul_f32 v[124:125], v[124:125], v[162:163]
	global_load_dwordx4 v[132:135], v[114:115], off offset:256
	global_load_dwordx4 v[162:165], v[114:115], off offset:2304
	v_pk_mul_f32 v[128:129], v[128:129], v[156:157]
	s_waitcnt vmcnt(0)
;     __device__ __forceinline__ void mid(acc_t& acc, const Unit& u, int, int, int, int) const {
;     ...
;             for (int m = 0; m < 4; ++m) { const bf16_t* gr = gates + (size_t)(row0 + ai * 128 + m * 16) * 2048 + col0;
; #pragma unroll
;                 for (int bj = 0; bj < 2; ++bj) { f32x4 a0, a1, b0, b1; unpack8(*(const u32x4*)(gr + bj * 128), a0, a1); unpack8(*(const u32x4*)(gr + 1024 + bj * 128), b0, b1);
; #pragma unroll
;                     for (int j = 0; j < 4; ++j) { a0[j] *= __builtin_amdgcn_rcpf(fmaxf(b0[j], 1e-20f)); a1[j] *= __builtin_amdgcn_rcpf(fmaxf(b1[j], 1e-20f)); }
;                     acc[ai][bj][m][0] *= a0; acc[ai][bj][m][1] *= a1; }
	v_lshlrev_b32_e32 v112, 16, v162
	v_max_f32_e32 v112, v112, v112
	v_lshlrev_b32_e32 v157, 16, v164
	v_max_f32_e32 v112, 0x1e3ce508, v112
	v_rcp_f32_e32 v156, v112
	v_max_f32_e32 v112, v157, v157
	v_and_b32_e32 v137, 0xffff0000, v162
	v_max_f32_e32 v112, 0x1e3ce508, v112
	v_rcp_f32_e32 v162, v112
	v_max_f32_e32 v112, v137, v137
	v_lshlrev_b32_e32 v166, 16, v163
	v_and_b32_e32 v167, 0xffff0000, v163
	v_and_b32_e32 v163, 0xffff0000, v164
	v_max_f32_e32 v112, 0x1e3ce508, v112
	v_rcp_f32_e32 v157, v112
	v_max_f32_e32 v112, v163, v163
	v_max_f32_e32 v112, 0x1e3ce508, v112
	v_rcp_f32_e32 v163, v112
	v_lshlrev_b32_e32 v168, 16, v165
	v_and_b32_e32 v169, 0xffff0000, v165
	v_lshlrev_b32_e32 v164, 16, v132
	v_and_b32_e32 v165, 0xffff0000, v132
	v_max_f32_e32 v112, v166, v166
	v_pk_mul_f32 v[156:157], v[156:157], v[164:165]
	v_lshlrev_b32_e32 v164, 16, v134
	v_and_b32_e32 v165, 0xffff0000, v134
	v_max_f32_e32 v112, 0x1e3ce508, v112
	v_pk_mul_f32 v[162:163], v[162:163], v[164:165]
	v_rcp_f32_e32 v164, v112
	v_max_f32_e32 v112, v168, v168
	v_max_f32_e32 v112, 0x1e3ce508, v112
	v_rcp_f32_e32 v132, v112
	v_max_f32_e32 v112, v167, v167
	v_max_f32_e32 v112, 0x1e3ce508, v112
	v_rcp_f32_e32 v165, v112
	v_max_f32_e32 v112, v169, v169
	v_max_f32_e32 v112, 0x1e3ce508, v112
	v_lshlrev_b32_e32 v166, 16, v133
	v_and_b32_e32 v167, 0xffff0000, v133
	v_rcp_f32_e32 v133, v112
	v_lshlrev_b32_e32 v134, 16, v135
	v_and_b32_e32 v135, 0xffff0000, v135
	v_pk_mul_f32 v[164:165], v[164:165], v[166:167]
	v_pk_mul_f32 v[132:133], v[132:133], v[134:135]
	v_pk_mul_f32 v[120:121], v[120:121], v[156:157]
	v_pk_mul_f32 v[118:119], v[118:119], v[132:133]
	v_or_b32_e32 v132, 16, v136
	v_ashrrev_i32_e32 v133, 31, v132
	v_lshlrev_b64 v[132:133], 12, v[132:133]
	v_lshl_add_u64 v[132:133], s[48:49], 0, v[132:133]
	v_lshl_add_u64 v[156:157], v[132:133], 0, v[138:139]
	v_pk_mul_f32 v[122:123], v[122:123], v[164:165]
	v_pk_mul_f32 v[116:117], v[116:117], v[162:163]
	global_load_dwordx4 v[132:135], v[156:157], off
	global_load_dwordx4 v[162:165], v[156:157], off offset:2048
	s_waitcnt vmcnt(1)
	v_lshlrev_b32_e32 v166, 16, v132
	s_waitcnt vmcnt(0)
	v_lshlrev_b32_e32 v112, 16, v162
	v_max_f32_e32 v112, v112, v112
	v_lshlrev_b32_e32 v168, 16, v163
	v_and_b32_e32 v169, 0xffff0000, v163
	v_lshlrev_b32_e32 v163, 16, v164
	v_max_f32_e32 v112, 0x1e3ce508, v112
	v_and_b32_e32 v137, 0xffff0000, v162
	v_rcp_f32_e32 v162, v112
	v_max_f32_e32 v112, v163, v163
	v_max_f32_e32 v112, 0x1e3ce508, v112
	v_and_b32_e32 v170, 0xffff0000, v164
	v_rcp_f32_e32 v164, v112
	v_max_f32_e32 v112, v137, v137
	v_max_f32_e32 v112, 0x1e3ce508, v112
	v_rcp_f32_e32 v163, v112
	v_max_f32_e32 v112, v170, v170
	v_max_f32_e32 v112, 0x1e3ce508, v112
	v_lshlrev_b32_e32 v171, 16, v165
	v_and_b32_e32 v172, 0xffff0000, v165
	v_rcp_f32_e32 v165, v112
	v_and_b32_e32 v167, 0xffff0000, v132
	v_max_f32_e32 v112, v168, v168
	v_pk_mul_f32 v[162:163], v[162:163], v[166:167]
	v_lshlrev_b32_e32 v166, 16, v134
	v_and_b32_e32 v167, 0xffff0000, v134
	v_max_f32_e32 v112, 0x1e3ce508, v112
	v_pk_mul_f32 v[164:165], v[164:165], v[166:167]
	v_rcp_f32_e32 v166, v112
	v_max_f32_e32 v112, v171, v171
	v_max_f32_e32 v112, 0x1e3ce508, v112
	v_rcp_f32_e32 v132, v112
	v_max_f32_e32 v112, v169, v169
	v_max_f32_e32 v112, 0x1e3ce508, v112
	v_rcp_f32_e32 v167, v112
	v_max_f32_e32 v112, v172, v172
	v_max_f32_e32 v112, 0x1e3ce508, v112
	v_lshlrev_b32_e32 v168, 16, v133
	v_and_b32_e32 v169, 0xffff0000, v133
	v_rcp_f32_e32 v133, v112
	v_lshlrev_b32_e32 v134, 16, v135
	v_and_b32_e32 v135, 0xffff0000, v135
	v_pk_mul_f32 v[108:109], v[108:109], v[162:163]
	v_pk_mul_f32 v[132:133], v[132:133], v[134:135]
	v_pk_mul_f32 v[104:105], v[104:105], v[164:165]
	v_pk_mul_f32 v[106:107], v[106:107], v[132:133]
	global_load_dwordx4 v[132:135], v[156:157], off offset:256
	global_load_dwordx4 v[162:165], v[156:157], off offset:2304
	v_pk_mul_f32 v[166:167], v[166:167], v[168:169]
	s_waitcnt vmcnt(0)
	v_lshlrev_b32_e32 v112, 16, v162
	v_max_f32_e32 v112, v112, v112
	v_lshlrev_b32_e32 v157, 16, v164
	v_max_f32_e32 v112, 0x1e3ce508, v112
	v_rcp_f32_e32 v156, v112
	v_max_f32_e32 v112, v157, v157
	v_and_b32_e32 v137, 0xffff0000, v162
	v_max_f32_e32 v112, 0x1e3ce508, v112
	v_rcp_f32_e32 v162, v112
	v_max_f32_e32 v112, v137, v137
	v_pk_mul_f32 v[110:111], v[110:111], v[166:167]
	v_lshlrev_b32_e32 v166, 16, v163
	v_and_b32_e32 v167, 0xffff0000, v163
	v_and_b32_e32 v163, 0xffff0000, v164
	v_max_f32_e32 v112, 0x1e3ce508, v112
	v_rcp_f32_e32 v157, v112
	v_max_f32_e32 v112, v163, v163
	v_max_f32_e32 v112, 0x1e3ce508, v112
	v_rcp_f32_e32 v163, v112
	v_lshlrev_b32_e32 v168, 16, v165
	v_and_b32_e32 v169, 0xffff0000, v165
	v_lshlrev_b32_e32 v164, 16, v132
	v_and_b32_e32 v165, 0xffff0000, v132
	v_max_f32_e32 v112, v166, v166
	v_pk_mul_f32 v[156:157], v[156:157], v[164:165]
	v_lshlrev_b32_e32 v164, 16, v134
	v_and_b32_e32 v165, 0xffff0000, v134
	v_max_f32_e32 v112, 0x1e3ce508, v112
	v_pk_mul_f32 v[162:163], v[162:163], v[164:165]
	v_rcp_f32_e32 v164, v112
	v_max_f32_e32 v112, v168, v168
	v_max_f32_e32 v112, 0x1e3ce508, v112
	v_rcp_f32_e32 v132, v112
	v_max_f32_e32 v112, v167, v167
	v_max_f32_e32 v112, 0x1e3ce508, v112
	v_rcp_f32_e32 v165, v112
	v_max_f32_e32 v112, v169, v169
	v_max_f32_e32 v112, 0x1e3ce508, v112
	v_lshlrev_b32_e32 v166, 16, v133
	v_and_b32_e32 v167, 0xffff0000, v133
	v_rcp_f32_e32 v133, v112
	v_lshlrev_b32_e32 v134, 16, v135
	v_and_b32_e32 v135, 0xffff0000, v135
	v_pk_mul_f32 v[164:165], v[164:165], v[166:167]
	v_pk_mul_f32 v[132:133], v[132:133], v[134:135]
	v_pk_mul_f32 v[100:101], v[100:101], v[156:157]
	v_pk_mul_f32 v[98:99], v[98:99], v[132:133]
	v_or_b32_e32 v132, 32, v136
	v_ashrrev_i32_e32 v133, 31, v132
	v_lshlrev_b64 v[132:133], 12, v[132:133]
	v_lshl_add_u64 v[132:133], s[48:49], 0, v[132:133]
	v_lshl_add_u64 v[156:157], v[132:133], 0, v[138:139]
	v_pk_mul_f32 v[102:103], v[102:103], v[164:165]
	v_pk_mul_f32 v[96:97], v[96:97], v[162:163]
	global_load_dwordx4 v[132:135], v[156:157], off
	global_load_dwordx4 v[162:165], v[156:157], off offset:2048
	s_waitcnt vmcnt(1)
;     __device__ __forceinline__ void mid(acc_t& acc, const Unit& u, int, int, int, int) const {
;     ...
;             for (int m = 0; m < 4; ++m) { const bf16_t* gr = gates + (size_t)(row0 + ai * 128 + m * 16) * 2048 + col0;
; #pragma unroll
;                 for (int bj = 0; bj < 2; ++bj) { f32x4 a0, a1, b0, b1; unpack8(*(const u32x4*)(gr + bj * 128), a0, a1); unpack8(*(const u32x4*)(gr + 1024 + bj * 128), b0, b1);
; #pragma unroll
;                     for (int j = 0; j < 4; ++j) { a0[j] *= __builtin_amdgcn_rcpf(fmaxf(b0[j], 1e-20f)); a1[j] *= __builtin_amdgcn_rcpf(fmaxf(b1[j], 1e-20f)); }
;                     acc[ai][bj][m][0] *= a0; acc[ai][bj][m][1] *= a1; }
	v_lshlrev_b32_e32 v166, 16, v132
	s_waitcnt vmcnt(0)
	v_lshlrev_b32_e32 v112, 16, v162
	v_max_f32_e32 v112, v112, v112
	v_lshlrev_b32_e32 v168, 16, v163
	v_and_b32_e32 v169, 0xffff0000, v163
	v_lshlrev_b32_e32 v163, 16, v164
	v_max_f32_e32 v112, 0x1e3ce508, v112
	v_and_b32_e32 v137, 0xffff0000, v162
	v_rcp_f32_e32 v162, v112
	v_max_f32_e32 v112, v163, v163
	v_max_f32_e32 v112, 0x1e3ce508, v112
	v_and_b32_e32 v170, 0xffff0000, v164
	v_rcp_f32_e32 v164, v112
	v_max_f32_e32 v112, v137, v137
	v_max_f32_e32 v112, 0x1e3ce508, v112
	v_rcp_f32_e32 v163, v112
	v_max_f32_e32 v112, v170, v170
	v_max_f32_e32 v112, 0x1e3ce508, v112
	v_lshlrev_b32_e32 v171, 16, v165
	v_and_b32_e32 v172, 0xffff0000, v165
	v_rcp_f32_e32 v165, v112
	v_and_b32_e32 v167, 0xffff0000, v132
	v_max_f32_e32 v112, v168, v168
	v_pk_mul_f32 v[162:163], v[162:163], v[166:167]
	v_lshlrev_b32_e32 v166, 16, v134
	v_and_b32_e32 v167, 0xffff0000, v134
	v_max_f32_e32 v112, 0x1e3ce508, v112
	v_pk_mul_f32 v[164:165], v[164:165], v[166:167]
	v_rcp_f32_e32 v166, v112
	v_max_f32_e32 v112, v171, v171
	v_max_f32_e32 v112, 0x1e3ce508, v112
	v_rcp_f32_e32 v132, v112
	v_max_f32_e32 v112, v169, v169
	v_max_f32_e32 v112, 0x1e3ce508, v112
	v_rcp_f32_e32 v167, v112
	v_max_f32_e32 v112, v172, v172
	v_max_f32_e32 v112, 0x1e3ce508, v112
	v_lshlrev_b32_e32 v168, 16, v133
	v_and_b32_e32 v169, 0xffff0000, v133
	v_rcp_f32_e32 v133, v112
	v_lshlrev_b32_e32 v134, 16, v135
	v_and_b32_e32 v135, 0xffff0000, v135
	v_pk_mul_f32 v[92:93], v[92:93], v[162:163]
	v_pk_mul_f32 v[132:133], v[132:133], v[134:135]
	v_pk_mul_f32 v[88:89], v[88:89], v[164:165]
	v_pk_mul_f32 v[90:91], v[90:91], v[132:133]
	global_load_dwordx4 v[132:135], v[156:157], off offset:256
	global_load_dwordx4 v[162:165], v[156:157], off offset:2304
	v_pk_mul_f32 v[166:167], v[166:167], v[168:169]
	s_waitcnt vmcnt(0)
	v_lshlrev_b32_e32 v112, 16, v162
	v_max_f32_e32 v112, v112, v112
	v_lshlrev_b32_e32 v157, 16, v164
	v_max_f32_e32 v112, 0x1e3ce508, v112
	v_rcp_f32_e32 v156, v112
	v_max_f32_e32 v112, v157, v157
	v_and_b32_e32 v137, 0xffff0000, v162
	v_max_f32_e32 v112, 0x1e3ce508, v112
	v_rcp_f32_e32 v162, v112
	v_max_f32_e32 v112, v137, v137
	v_pk_mul_f32 v[94:95], v[94:95], v[166:167]
	v_lshlrev_b32_e32 v166, 16, v163
	v_and_b32_e32 v167, 0xffff0000, v163
	v_and_b32_e32 v163, 0xffff0000, v164
	v_max_f32_e32 v112, 0x1e3ce508, v112
	v_rcp_f32_e32 v157, v112
	v_max_f32_e32 v112, v163, v163
	v_max_f32_e32 v112, 0x1e3ce508, v112
	v_rcp_f32_e32 v163, v112
	v_lshlrev_b32_e32 v168, 16, v165
	v_and_b32_e32 v169, 0xffff0000, v165
	v_lshlrev_b32_e32 v164, 16, v132
	v_and_b32_e32 v165, 0xffff0000, v132
	v_max_f32_e32 v112, v166, v166
	v_pk_mul_f32 v[156:157], v[156:157], v[164:165]
	v_lshlrev_b32_e32 v164, 16, v134
	v_and_b32_e32 v165, 0xffff0000, v134
	v_max_f32_e32 v112, 0x1e3ce508, v112
	v_pk_mul_f32 v[162:163], v[162:163], v[164:165]
	v_rcp_f32_e32 v164, v112
	v_max_f32_e32 v112, v168, v168
	v_max_f32_e32 v112, 0x1e3ce508, v112
	v_rcp_f32_e32 v132, v112
	v_max_f32_e32 v112, v167, v167
	v_max_f32_e32 v112, 0x1e3ce508, v112
	v_rcp_f32_e32 v165, v112
	v_max_f32_e32 v112, v169, v169
	v_max_f32_e32 v112, 0x1e3ce508, v112
	v_lshlrev_b32_e32 v166, 16, v133
	v_and_b32_e32 v167, 0xffff0000, v133
	v_rcp_f32_e32 v133, v112
	v_lshlrev_b32_e32 v134, 16, v135
	v_and_b32_e32 v135, 0xffff0000, v135
	v_pk_mul_f32 v[164:165], v[164:165], v[166:167]
	v_pk_mul_f32 v[132:133], v[132:133], v[134:135]
	v_pk_mul_f32 v[86:87], v[86:87], v[164:165]
	v_pk_mul_f32 v[82:83], v[82:83], v[132:133]
	v_or_b32_e32 v132, 48, v136
	v_ashrrev_i32_e32 v133, 31, v132
	v_lshlrev_b64 v[132:133], 12, v[132:133]
	v_lshl_add_u64 v[132:133], s[48:49], 0, v[132:133]
	v_lshl_add_u64 v[136:137], v[132:133], 0, v[138:139]
	v_pk_mul_f32 v[80:81], v[80:81], v[162:163]
	global_load_dwordx4 v[132:135], v[136:137], off
	global_load_dwordx4 v[162:165], v[136:137], off offset:2048
	v_pk_mul_f32 v[84:85], v[84:85], v[156:157]
	s_waitcnt vmcnt(0)
	v_lshlrev_b32_e32 v112, 16, v162
	v_max_f32_e32 v112, v112, v112
	v_lshlrev_b32_e32 v156, 16, v164
	v_max_f32_e32 v112, 0x1e3ce508, v112
	v_rcp_f32_e32 v138, v112
	v_max_f32_e32 v112, v156, v156
	v_and_b32_e32 v139, 0xffff0000, v162
	v_max_f32_e32 v112, 0x1e3ce508, v112
	v_rcp_f32_e32 v156, v112
	v_max_f32_e32 v112, v139, v139
	v_and_b32_e32 v157, 0xffff0000, v164
	v_max_f32_e32 v112, 0x1e3ce508, v112
	v_rcp_f32_e32 v139, v112
	v_max_f32_e32 v112, v157, v157
	v_max_f32_e32 v112, 0x1e3ce508, v112
	v_rcp_f32_e32 v157, v112
	v_lshlrev_b32_e32 v166, 16, v163
	v_and_b32_e32 v167, 0xffff0000, v163
	v_lshlrev_b32_e32 v162, 16, v132
	v_and_b32_e32 v163, 0xffff0000, v132
	v_max_f32_e32 v112, v166, v166
	v_lshlrev_b32_e32 v164, 16, v165
	v_pk_mul_f32 v[138:139], v[138:139], v[162:163]
	v_lshlrev_b32_e32 v162, 16, v134
	v_and_b32_e32 v163, 0xffff0000, v134
	v_max_f32_e32 v112, 0x1e3ce508, v112
	v_pk_mul_f32 v[156:157], v[156:157], v[162:163]
	v_rcp_f32_e32 v162, v112
	v_max_f32_e32 v112, v164, v164
	v_max_f32_e32 v112, 0x1e3ce508, v112
	v_rcp_f32_e32 v132, v112
	v_max_f32_e32 v112, v167, v167
	v_and_b32_e32 v168, 0xffff0000, v165
	v_max_f32_e32 v112, 0x1e3ce508, v112
	v_rcp_f32_e32 v163, v112
	v_max_f32_e32 v112, v168, v168
	v_max_f32_e32 v112, 0x1e3ce508, v112
	v_lshlrev_b32_e32 v164, 16, v133
	v_and_b32_e32 v165, 0xffff0000, v133
	v_rcp_f32_e32 v133, v112
	v_lshlrev_b32_e32 v134, 16, v135
	v_and_b32_e32 v135, 0xffff0000, v135
	v_pk_mul_f32 v[76:77], v[76:77], v[138:139]
	v_pk_mul_f32 v[132:133], v[132:133], v[134:135]
	v_pk_mul_f32 v[162:163], v[162:163], v[164:165]
	v_pk_mul_f32 v[74:75], v[74:75], v[132:133]
	global_load_dwordx4 v[132:135], v[136:137], off offset:256
	s_nop 0
	global_load_dwordx4 v[136:139], v[136:137], off offset:2304
	v_pk_mul_f32 v[78:79], v[78:79], v[162:163]
	v_pk_mul_f32 v[72:73], v[72:73], v[156:157]
	s_waitcnt vmcnt(1)
;     __device__ __forceinline__ void mid(acc_t& acc, const Unit& u, int, int, int, int) const {
;     ...
;             for (int m = 0; m < 4; ++m) { const bf16_t* gr = gates + (size_t)(row0 + ai * 128 + m * 16) * 2048 + col0;
; #pragma unroll
;                 for (int bj = 0; bj < 2; ++bj) { f32x4 a0, a1, b0, b1; unpack8(*(const u32x4*)(gr + bj * 128), a0, a1); unpack8(*(const u32x4*)(gr + 1024 + bj * 128), b0, b1);
; #pragma unroll
;                     for (int j = 0; j < 4; ++j) { a0[j] *= __builtin_amdgcn_rcpf(fmaxf(b0[j], 1e-20f)); a1[j] *= __builtin_amdgcn_rcpf(fmaxf(b1[j], 1e-20f)); }
;                     acc[ai][bj][m][0] *= a0; acc[ai][bj][m][1] *= a1; }
	v_and_b32_e32 v157, 0xffff0000, v132
	s_waitcnt vmcnt(0)
	v_lshlrev_b32_e32 v112, 16, v136
	v_max_f32_e32 v112, v112, v112
	v_lshlrev_b32_e32 v162, 16, v137
	v_and_b32_e32 v163, 0xffff0000, v137
	v_lshlrev_b32_e32 v137, 16, v138
	v_max_f32_e32 v112, 0x1e3ce508, v112
	v_and_b32_e32 v156, 0xffff0000, v136
	v_rcp_f32_e32 v136, v112
	v_max_f32_e32 v112, v137, v137
	v_max_f32_e32 v112, 0x1e3ce508, v112
	v_and_b32_e32 v164, 0xffff0000, v138
	v_rcp_f32_e32 v138, v112
	v_max_f32_e32 v112, v156, v156
	v_max_f32_e32 v112, 0x1e3ce508, v112
	v_rcp_f32_e32 v137, v112
	v_max_f32_e32 v112, v164, v164
	v_max_f32_e32 v112, 0x1e3ce508, v112
	v_lshlrev_b32_e32 v165, 16, v139
	v_and_b32_e32 v166, 0xffff0000, v139
	v_rcp_f32_e32 v139, v112
	v_lshlrev_b32_e32 v156, 16, v132
	v_max_f32_e32 v112, v162, v162
	v_pk_mul_f32 v[136:137], v[136:137], v[156:157]
	v_lshlrev_b32_e32 v156, 16, v134
	v_and_b32_e32 v157, 0xffff0000, v134
	v_max_f32_e32 v112, 0x1e3ce508, v112
	v_pk_mul_f32 v[138:139], v[138:139], v[156:157]
	v_rcp_f32_e32 v156, v112
	v_max_f32_e32 v112, v165, v165
	v_max_f32_e32 v112, 0x1e3ce508, v112
	v_rcp_f32_e32 v132, v112
	v_max_f32_e32 v112, v163, v163
	v_max_f32_e32 v112, 0x1e3ce508, v112
	v_rcp_f32_e32 v157, v112
	v_max_f32_e32 v112, v166, v166
	v_max_f32_e32 v112, 0x1e3ce508, v112
	v_lshlrev_b32_e32 v162, 16, v133
	v_and_b32_e32 v163, 0xffff0000, v133
	v_rcp_f32_e32 v133, v112
	v_lshlrev_b32_e32 v134, 16, v135
	v_and_b32_e32 v135, 0xffff0000, v135
	v_pk_mul_f32 v[68:69], v[68:69], v[136:137]
	v_pk_mul_f32 v[132:133], v[132:133], v[134:135]
	v_lshl_add_u64 v[136:137], v[114:115], 0, s[0:1]
	s_mov_b32 s0, 0x80000
	v_pk_mul_f32 v[66:67], v[66:67], v[132:133]
	v_add_co_u32_e32 v132, vcc, s0, v114
	v_pk_mul_f32 v[156:157], v[156:157], v[162:163]
	s_nop 0
	v_addc_co_u32_e32 v133, vcc, 0, v115, vcc
	global_load_dwordx4 v[132:135], v[132:133], off
	s_nop 0
	global_load_dwordx4 v[162:165], v[136:137], off offset:2048
	v_pk_mul_f32 v[70:71], v[70:71], v[156:157]
	v_pk_mul_f32 v[64:65], v[64:65], v[138:139]
	s_mov_b64 s[0:1], 0x90000
	s_waitcnt vmcnt(0)
	v_lshlrev_b32_e32 v112, 16, v162
	v_max_f32_e32 v112, v112, v112
	v_lshlrev_b32_e32 v156, 16, v164
	v_max_f32_e32 v112, 0x1e3ce508, v112
	v_rcp_f32_e32 v138, v112
	v_max_f32_e32 v112, v156, v156
	v_and_b32_e32 v139, 0xffff0000, v162
	v_max_f32_e32 v112, 0x1e3ce508, v112
	v_rcp_f32_e32 v156, v112
	v_max_f32_e32 v112, v139, v139
	v_and_b32_e32 v157, 0xffff0000, v164
	v_max_f32_e32 v112, 0x1e3ce508, v112
	v_rcp_f32_e32 v139, v112
	v_max_f32_e32 v112, v157, v157
	v_max_f32_e32 v112, 0x1e3ce508, v112
	v_rcp_f32_e32 v157, v112
	v_lshlrev_b32_e32 v166, 16, v163
	v_and_b32_e32 v167, 0xffff0000, v163
	v_lshlrev_b32_e32 v162, 16, v132
	v_and_b32_e32 v163, 0xffff0000, v132
	v_max_f32_e32 v112, v166, v166
	v_lshlrev_b32_e32 v164, 16, v165
	v_pk_mul_f32 v[138:139], v[138:139], v[162:163]
	v_lshlrev_b32_e32 v162, 16, v134
	v_and_b32_e32 v163, 0xffff0000, v134
	v_max_f32_e32 v112, 0x1e3ce508, v112
	v_pk_mul_f32 v[156:157], v[156:157], v[162:163]
	v_rcp_f32_e32 v162, v112
	v_max_f32_e32 v112, v164, v164
	v_max_f32_e32 v112, 0x1e3ce508, v112
	v_rcp_f32_e32 v132, v112
	v_max_f32_e32 v112, v167, v167
	v_and_b32_e32 v168, 0xffff0000, v165
	v_max_f32_e32 v112, 0x1e3ce508, v112
	v_rcp_f32_e32 v163, v112
	v_max_f32_e32 v112, v168, v168
	v_max_f32_e32 v112, 0x1e3ce508, v112
	v_lshlrev_b32_e32 v164, 16, v133
	v_and_b32_e32 v165, 0xffff0000, v133
	v_rcp_f32_e32 v133, v112
	v_lshlrev_b32_e32 v134, 16, v135
	v_and_b32_e32 v135, 0xffff0000, v135
	v_pk_mul_f32 v[60:61], v[60:61], v[138:139]
	v_pk_mul_f32 v[132:133], v[132:133], v[134:135]
	v_pk_mul_f32 v[162:163], v[162:163], v[164:165]
	v_pk_mul_f32 v[58:59], v[58:59], v[132:133]
	global_load_dwordx4 v[132:135], v[136:137], off offset:256
	s_nop 0
	global_load_dwordx4 v[136:139], v[136:137], off offset:2304
	v_pk_mul_f32 v[62:63], v[62:63], v[162:163]
	v_pk_mul_f32 v[56:57], v[56:57], v[156:157]
	s_waitcnt vmcnt(1)
	v_and_b32_e32 v157, 0xffff0000, v132
	s_waitcnt vmcnt(0)
	v_lshlrev_b32_e32 v112, 16, v136
	v_max_f32_e32 v112, v112, v112
	v_lshlrev_b32_e32 v162, 16, v137
	v_and_b32_e32 v163, 0xffff0000, v137
	v_lshlrev_b32_e32 v137, 16, v138
	v_max_f32_e32 v112, 0x1e3ce508, v112
	v_and_b32_e32 v156, 0xffff0000, v136
	v_rcp_f32_e32 v136, v112
	v_max_f32_e32 v112, v137, v137
	v_max_f32_e32 v112, 0x1e3ce508, v112
	v_and_b32_e32 v164, 0xffff0000, v138
	v_rcp_f32_e32 v138, v112
	v_max_f32_e32 v112, v156, v156
	v_max_f32_e32 v112, 0x1e3ce508, v112
	v_rcp_f32_e32 v137, v112
	v_max_f32_e32 v112, v164, v164
	v_max_f32_e32 v112, 0x1e3ce508, v112
	v_lshlrev_b32_e32 v165, 16, v139
	v_and_b32_e32 v166, 0xffff0000, v139
	v_rcp_f32_e32 v139, v112
	v_lshlrev_b32_e32 v156, 16, v132
	v_max_f32_e32 v112, v162, v162
	v_pk_mul_f32 v[136:137], v[136:137], v[156:157]
	v_lshlrev_b32_e32 v156, 16, v134
	v_and_b32_e32 v157, 0xffff0000, v134
	v_max_f32_e32 v112, 0x1e3ce508, v112
	v_pk_mul_f32 v[138:139], v[138:139], v[156:157]
	v_rcp_f32_e32 v156, v112
	v_max_f32_e32 v112, v165, v165
	v_max_f32_e32 v112, 0x1e3ce508, v112
	v_rcp_f32_e32 v132, v112
	v_max_f32_e32 v112, v163, v163
	v_max_f32_e32 v112, 0x1e3ce508, v112
	v_rcp_f32_e32 v157, v112
	v_max_f32_e32 v112, v166, v166
	v_max_f32_e32 v112, 0x1e3ce508, v112
	v_lshlrev_b32_e32 v162, 16, v133
	v_and_b32_e32 v163, 0xffff0000, v133
	v_rcp_f32_e32 v133, v112
	v_lshlrev_b32_e32 v134, 16, v135
	v_and_b32_e32 v135, 0xffff0000, v135
	v_pk_mul_f32 v[52:53], v[52:53], v[136:137]
	v_pk_mul_f32 v[132:133], v[132:133], v[134:135]
	v_lshl_add_u64 v[136:137], v[114:115], 0, s[0:1]
	s_mov_b32 s0, 0x90000
	v_pk_mul_f32 v[50:51], v[50:51], v[132:133]
	v_add_co_u32_e32 v132, vcc, s0, v114
	v_pk_mul_f32 v[156:157], v[156:157], v[162:163]
	s_nop 0
	v_addc_co_u32_e32 v133, vcc, 0, v115, vcc
	global_load_dwordx4 v[132:135], v[132:133], off
	s_nop 0
	global_load_dwordx4 v[162:165], v[136:137], off offset:2048
	v_pk_mul_f32 v[54:55], v[54:55], v[156:157]
	v_pk_mul_f32 v[48:49], v[48:49], v[138:139]
	s_mov_b64 s[0:1], 0xa0000
	s_waitcnt vmcnt(0)
;     __device__ __forceinline__ void mid(acc_t& acc, const Unit& u, int, int, int, int) const {
;     ...
;             for (int m = 0; m < 4; ++m) { const bf16_t* gr = gates + (size_t)(row0 + ai * 128 + m * 16) * 2048 + col0;
; #pragma unroll
;                 for (int bj = 0; bj < 2; ++bj) { f32x4 a0, a1, b0, b1; unpack8(*(const u32x4*)(gr + bj * 128), a0, a1); unpack8(*(const u32x4*)(gr + 1024 + bj * 128), b0, b1);
; #pragma unroll
;                     for (int j = 0; j < 4; ++j) { a0[j] *= __builtin_amdgcn_rcpf(fmaxf(b0[j], 1e-20f)); a1[j] *= __builtin_amdgcn_rcpf(fmaxf(b1[j], 1e-20f)); }
;                     acc[ai][bj][m][0] *= a0; acc[ai][bj][m][1] *= a1; }
	v_lshlrev_b32_e32 v112, 16, v162
	v_max_f32_e32 v112, v112, v112
	v_lshlrev_b32_e32 v156, 16, v164
	v_max_f32_e32 v112, 0x1e3ce508, v112
	v_rcp_f32_e32 v138, v112
	v_max_f32_e32 v112, v156, v156
	v_and_b32_e32 v139, 0xffff0000, v162
	v_max_f32_e32 v112, 0x1e3ce508, v112
	v_rcp_f32_e32 v156, v112
	v_max_f32_e32 v112, v139, v139
	v_and_b32_e32 v157, 0xffff0000, v164
	v_max_f32_e32 v112, 0x1e3ce508, v112
	v_rcp_f32_e32 v139, v112
	v_max_f32_e32 v112, v157, v157
	v_max_f32_e32 v112, 0x1e3ce508, v112
	v_rcp_f32_e32 v157, v112
	v_lshlrev_b32_e32 v166, 16, v163
	v_and_b32_e32 v167, 0xffff0000, v163
	v_lshlrev_b32_e32 v162, 16, v132
	v_and_b32_e32 v163, 0xffff0000, v132
	v_max_f32_e32 v112, v166, v166
	v_lshlrev_b32_e32 v164, 16, v165
	v_pk_mul_f32 v[138:139], v[138:139], v[162:163]
	v_lshlrev_b32_e32 v162, 16, v134
	v_and_b32_e32 v163, 0xffff0000, v134
	v_max_f32_e32 v112, 0x1e3ce508, v112
	v_pk_mul_f32 v[156:157], v[156:157], v[162:163]
	v_rcp_f32_e32 v162, v112
	v_max_f32_e32 v112, v164, v164
	v_max_f32_e32 v112, 0x1e3ce508, v112
	v_rcp_f32_e32 v132, v112
	v_max_f32_e32 v112, v167, v167
	v_and_b32_e32 v168, 0xffff0000, v165
	v_max_f32_e32 v112, 0x1e3ce508, v112
	v_rcp_f32_e32 v163, v112
	v_max_f32_e32 v112, v168, v168
	v_max_f32_e32 v112, 0x1e3ce508, v112
	v_lshlrev_b32_e32 v164, 16, v133
	v_and_b32_e32 v165, 0xffff0000, v133
	v_rcp_f32_e32 v133, v112
	v_lshlrev_b32_e32 v134, 16, v135
	v_and_b32_e32 v135, 0xffff0000, v135
	v_pk_mul_f32 v[44:45], v[44:45], v[138:139]
	v_pk_mul_f32 v[132:133], v[132:133], v[134:135]
	v_pk_mul_f32 v[162:163], v[162:163], v[164:165]
	v_pk_mul_f32 v[42:43], v[42:43], v[132:133]
	global_load_dwordx4 v[132:135], v[136:137], off offset:256
	s_nop 0
	global_load_dwordx4 v[136:139], v[136:137], off offset:2304
	v_pk_mul_f32 v[46:47], v[46:47], v[162:163]
	v_pk_mul_f32 v[40:41], v[40:41], v[156:157]
	s_waitcnt vmcnt(1)
	v_and_b32_e32 v157, 0xffff0000, v132
	s_waitcnt vmcnt(0)
	v_lshlrev_b32_e32 v112, 16, v136
	v_max_f32_e32 v112, v112, v112
	v_lshlrev_b32_e32 v162, 16, v137
	v_and_b32_e32 v163, 0xffff0000, v137
	v_lshlrev_b32_e32 v137, 16, v138
	v_max_f32_e32 v112, 0x1e3ce508, v112
	v_and_b32_e32 v156, 0xffff0000, v136
	v_rcp_f32_e32 v136, v112
	v_max_f32_e32 v112, v137, v137
	v_max_f32_e32 v112, 0x1e3ce508, v112
	v_and_b32_e32 v164, 0xffff0000, v138
	v_rcp_f32_e32 v138, v112
	v_max_f32_e32 v112, v156, v156
	v_max_f32_e32 v112, 0x1e3ce508, v112
	v_rcp_f32_e32 v137, v112
	v_max_f32_e32 v112, v164, v164
	v_max_f32_e32 v112, 0x1e3ce508, v112
	v_lshlrev_b32_e32 v165, 16, v139
	v_and_b32_e32 v166, 0xffff0000, v139
	v_rcp_f32_e32 v139, v112
	v_lshlrev_b32_e32 v156, 16, v132
	v_max_f32_e32 v112, v162, v162
	v_pk_mul_f32 v[136:137], v[136:137], v[156:157]
	v_lshlrev_b32_e32 v156, 16, v134
	v_and_b32_e32 v157, 0xffff0000, v134
	v_max_f32_e32 v112, 0x1e3ce508, v112
	v_pk_mul_f32 v[138:139], v[138:139], v[156:157]
	v_rcp_f32_e32 v156, v112
	v_max_f32_e32 v112, v165, v165
	v_max_f32_e32 v112, 0x1e3ce508, v112
	v_rcp_f32_e32 v132, v112
	v_max_f32_e32 v112, v163, v163
	v_max_f32_e32 v112, 0x1e3ce508, v112
	v_rcp_f32_e32 v157, v112
	v_max_f32_e32 v112, v166, v166
	v_max_f32_e32 v112, 0x1e3ce508, v112
	v_lshlrev_b32_e32 v162, 16, v133
	v_and_b32_e32 v163, 0xffff0000, v133
	v_rcp_f32_e32 v133, v112
	v_lshlrev_b32_e32 v134, 16, v135
	v_and_b32_e32 v135, 0xffff0000, v135
	v_pk_mul_f32 v[36:37], v[36:37], v[136:137]
	v_pk_mul_f32 v[132:133], v[132:133], v[134:135]
	v_lshl_add_u64 v[136:137], v[114:115], 0, s[0:1]
	s_mov_b32 s0, 0xa0000
	v_pk_mul_f32 v[34:35], v[34:35], v[132:133]
	v_add_co_u32_e32 v132, vcc, s0, v114
	v_pk_mul_f32 v[156:157], v[156:157], v[162:163]
	s_nop 0
	v_addc_co_u32_e32 v133, vcc, 0, v115, vcc
	global_load_dwordx4 v[132:135], v[132:133], off
	s_nop 0
	global_load_dwordx4 v[162:165], v[136:137], off offset:2048
	v_pk_mul_f32 v[38:39], v[38:39], v[156:157]
	v_pk_mul_f32 v[32:33], v[32:33], v[138:139]
	s_mov_b64 s[0:1], 0xb0000
	s_waitcnt vmcnt(0)
	v_lshlrev_b32_e32 v112, 16, v162
	v_max_f32_e32 v112, v112, v112
	v_lshlrev_b32_e32 v156, 16, v164
	v_max_f32_e32 v112, 0x1e3ce508, v112
	v_rcp_f32_e32 v138, v112
	v_max_f32_e32 v112, v156, v156
	v_and_b32_e32 v139, 0xffff0000, v162
	v_max_f32_e32 v112, 0x1e3ce508, v112
	v_rcp_f32_e32 v156, v112
	v_max_f32_e32 v112, v139, v139
	v_and_b32_e32 v157, 0xffff0000, v164
	v_max_f32_e32 v112, 0x1e3ce508, v112
	v_rcp_f32_e32 v139, v112
	v_max_f32_e32 v112, v157, v157
	v_max_f32_e32 v112, 0x1e3ce508, v112
	v_rcp_f32_e32 v157, v112
	v_lshlrev_b32_e32 v166, 16, v163
	v_and_b32_e32 v167, 0xffff0000, v163
	v_lshlrev_b32_e32 v162, 16, v132
	v_and_b32_e32 v163, 0xffff0000, v132
	v_max_f32_e32 v112, v166, v166
	v_lshlrev_b32_e32 v164, 16, v165
	v_pk_mul_f32 v[138:139], v[138:139], v[162:163]
	v_lshlrev_b32_e32 v162, 16, v134
	v_and_b32_e32 v163, 0xffff0000, v134
	v_max_f32_e32 v112, 0x1e3ce508, v112
	v_pk_mul_f32 v[156:157], v[156:157], v[162:163]
	v_rcp_f32_e32 v162, v112
	v_max_f32_e32 v112, v164, v164
	v_max_f32_e32 v112, 0x1e3ce508, v112
	v_rcp_f32_e32 v132, v112
	v_max_f32_e32 v112, v167, v167
	v_and_b32_e32 v168, 0xffff0000, v165
	v_max_f32_e32 v112, 0x1e3ce508, v112
	v_rcp_f32_e32 v163, v112
	v_max_f32_e32 v112, v168, v168
	v_max_f32_e32 v112, 0x1e3ce508, v112
	v_lshlrev_b32_e32 v164, 16, v133
	v_and_b32_e32 v165, 0xffff0000, v133
	v_rcp_f32_e32 v133, v112
	v_lshlrev_b32_e32 v134, 16, v135
	v_and_b32_e32 v135, 0xffff0000, v135
	v_pk_mul_f32 v[28:29], v[28:29], v[138:139]
	v_pk_mul_f32 v[132:133], v[132:133], v[134:135]
	v_pk_mul_f32 v[162:163], v[162:163], v[164:165]
	v_pk_mul_f32 v[26:27], v[26:27], v[132:133]
	global_load_dwordx4 v[132:135], v[136:137], off offset:256
	s_nop 0
	global_load_dwordx4 v[136:139], v[136:137], off offset:2304
	v_pk_mul_f32 v[30:31], v[30:31], v[162:163]
	v_pk_mul_f32 v[24:25], v[24:25], v[156:157]
	s_waitcnt vmcnt(1)
;     __device__ __forceinline__ void mid(acc_t& acc, const Unit& u, int, int, int, int) const {
;     ...
;             for (int m = 0; m < 4; ++m) { const bf16_t* gr = gates + (size_t)(row0 + ai * 128 + m * 16) * 2048 + col0;
; #pragma unroll
;                 for (int bj = 0; bj < 2; ++bj) { f32x4 a0, a1, b0, b1; unpack8(*(const u32x4*)(gr + bj * 128), a0, a1); unpack8(*(const u32x4*)(gr + 1024 + bj * 128), b0, b1);
; #pragma unroll
;                     for (int j = 0; j < 4; ++j) { a0[j] *= __builtin_amdgcn_rcpf(fmaxf(b0[j], 1e-20f)); a1[j] *= __builtin_amdgcn_rcpf(fmaxf(b1[j], 1e-20f)); }
;                     acc[ai][bj][m][0] *= a0; acc[ai][bj][m][1] *= a1; }
;                 asm volatile("" ::: "memory"); }
;     }
	v_and_b32_e32 v157, 0xffff0000, v132
	s_waitcnt vmcnt(0)
	v_lshlrev_b32_e32 v112, 16, v136
	v_max_f32_e32 v112, v112, v112
	v_lshlrev_b32_e32 v162, 16, v137
	v_and_b32_e32 v163, 0xffff0000, v137
	v_lshlrev_b32_e32 v137, 16, v138
	v_max_f32_e32 v112, 0x1e3ce508, v112
	v_and_b32_e32 v156, 0xffff0000, v136
	v_rcp_f32_e32 v136, v112
	v_max_f32_e32 v112, v137, v137
	v_max_f32_e32 v112, 0x1e3ce508, v112
	v_and_b32_e32 v164, 0xffff0000, v138
	v_rcp_f32_e32 v138, v112
	v_max_f32_e32 v112, v156, v156
	v_max_f32_e32 v112, 0x1e3ce508, v112
	v_rcp_f32_e32 v137, v112
	v_max_f32_e32 v112, v164, v164
	v_max_f32_e32 v112, 0x1e3ce508, v112
	v_lshlrev_b32_e32 v165, 16, v139
	v_and_b32_e32 v166, 0xffff0000, v139
	v_rcp_f32_e32 v139, v112
	v_lshlrev_b32_e32 v156, 16, v132
	v_max_f32_e32 v112, v162, v162
	v_pk_mul_f32 v[136:137], v[136:137], v[156:157]
	v_lshlrev_b32_e32 v156, 16, v134
	v_and_b32_e32 v157, 0xffff0000, v134
	v_max_f32_e32 v112, 0x1e3ce508, v112
	v_pk_mul_f32 v[138:139], v[138:139], v[156:157]
	v_rcp_f32_e32 v156, v112
	v_max_f32_e32 v112, v165, v165
	v_max_f32_e32 v112, 0x1e3ce508, v112
	v_rcp_f32_e32 v132, v112
	v_max_f32_e32 v112, v163, v163
	v_max_f32_e32 v112, 0x1e3ce508, v112
	v_rcp_f32_e32 v157, v112
	v_max_f32_e32 v112, v166, v166
	v_max_f32_e32 v112, 0x1e3ce508, v112
	v_lshlrev_b32_e32 v162, 16, v133
	v_and_b32_e32 v163, 0xffff0000, v133
	v_rcp_f32_e32 v133, v112
	v_pk_mul_f32 v[20:21], v[20:21], v[136:137]
	v_lshl_add_u64 v[136:137], v[114:115], 0, s[0:1]
	s_mov_b32 s0, 0xb0000
	v_lshlrev_b32_e32 v134, 16, v135
	v_and_b32_e32 v135, 0xffff0000, v135
	v_add_co_u32_e32 v114, vcc, s0, v114
	v_pk_mul_f32 v[132:133], v[132:133], v[134:135]
	s_nop 0
	v_addc_co_u32_e32 v115, vcc, 0, v115, vcc
	v_pk_mul_f32 v[156:157], v[156:157], v[162:163]
	v_pk_mul_f32 v[18:19], v[18:19], v[132:133]
	global_load_dwordx4 v[132:135], v[114:115], off
	global_load_dwordx4 v[162:165], v[136:137], off offset:2048
	v_pk_mul_f32 v[16:17], v[16:17], v[138:139]
	v_pk_mul_f32 v[22:23], v[22:23], v[156:157]
	s_waitcnt vmcnt(1)
	v_lshlrev_b32_e32 v156, 16, v132
	s_waitcnt vmcnt(0)
	v_lshlrev_b32_e32 v112, 16, v162
	v_max_f32_e32 v112, v112, v112
	v_lshlrev_b32_e32 v138, 16, v164
	v_max_f32_e32 v112, 0x1e3ce508, v112
	v_rcp_f32_e32 v114, v112
	v_max_f32_e32 v112, v138, v138
	v_and_b32_e32 v115, 0xffff0000, v162
	v_max_f32_e32 v112, 0x1e3ce508, v112
	v_rcp_f32_e32 v138, v112
	v_max_f32_e32 v112, v115, v115
	v_and_b32_e32 v139, 0xffff0000, v164
	v_max_f32_e32 v112, 0x1e3ce508, v112
	v_rcp_f32_e32 v115, v112
	v_max_f32_e32 v112, v139, v139
	v_max_f32_e32 v112, 0x1e3ce508, v112
	v_rcp_f32_e32 v139, v112
	v_lshlrev_b32_e32 v162, 16, v163
	v_and_b32_e32 v157, 0xffff0000, v132
	v_max_f32_e32 v112, v162, v162
	v_lshlrev_b32_e32 v164, 16, v165
	v_pk_mul_f32 v[114:115], v[114:115], v[156:157]
	v_lshlrev_b32_e32 v156, 16, v134
	v_and_b32_e32 v157, 0xffff0000, v134
	v_max_f32_e32 v112, 0x1e3ce508, v112
	v_pk_mul_f32 v[138:139], v[138:139], v[156:157]
	v_rcp_f32_e32 v156, v112
	v_max_f32_e32 v112, v164, v164
	v_and_b32_e32 v163, 0xffff0000, v163
	v_max_f32_e32 v112, 0x1e3ce508, v112
	v_rcp_f32_e32 v132, v112
	v_max_f32_e32 v112, v163, v163
	v_and_b32_e32 v165, 0xffff0000, v165
	v_max_f32_e32 v112, 0x1e3ce508, v112
	v_rcp_f32_e32 v157, v112
	v_max_f32_e32 v112, v165, v165
	v_max_f32_e32 v112, 0x1e3ce508, v112
	v_lshlrev_b32_e32 v162, 16, v133
	v_and_b32_e32 v163, 0xffff0000, v133
	v_rcp_f32_e32 v133, v112
	v_lshlrev_b32_e32 v134, 16, v135
	v_and_b32_e32 v135, 0xffff0000, v135
	v_pk_mul_f32 v[8:9], v[8:9], v[138:139]
	v_pk_mul_f32 v[132:133], v[132:133], v[134:135]
	v_pk_mul_f32 v[12:13], v[12:13], v[114:115]
	v_pk_mul_f32 v[10:11], v[10:11], v[132:133]
	global_load_dwordx4 v[132:135], v[136:137], off offset:256
	s_nop 0
	global_load_dwordx4 v[136:139], v[136:137], off offset:2304
	v_pk_mul_f32 v[156:157], v[156:157], v[162:163]
	s_waitcnt vmcnt(0)
	v_lshlrev_b32_e32 v112, 16, v136
	v_max_f32_e32 v112, v112, v112
	v_and_b32_e32 v115, 0xffff0000, v136
	v_lshlrev_b32_e32 v136, 16, v138
	v_max_f32_e32 v112, 0x1e3ce508, v112
	v_rcp_f32_e32 v114, v112
	v_max_f32_e32 v112, v136, v136
	v_max_f32_e32 v112, 0x1e3ce508, v112
	v_rcp_f32_e32 v136, v112
	v_max_f32_e32 v112, v115, v115
	v_pk_mul_f32 v[14:15], v[14:15], v[156:157]
	v_lshlrev_b32_e32 v156, 16, v137
	v_and_b32_e32 v157, 0xffff0000, v137
	v_and_b32_e32 v137, 0xffff0000, v138
	v_max_f32_e32 v112, 0x1e3ce508, v112
	v_rcp_f32_e32 v115, v112
	v_max_f32_e32 v112, v137, v137
	v_max_f32_e32 v112, 0x1e3ce508, v112
	v_rcp_f32_e32 v137, v112
	v_lshlrev_b32_e32 v162, 16, v139
	v_and_b32_e32 v163, 0xffff0000, v139
	v_lshlrev_b32_e32 v138, 16, v132
	v_and_b32_e32 v139, 0xffff0000, v132
	v_max_f32_e32 v112, v156, v156
	v_pk_mul_f32 v[114:115], v[114:115], v[138:139]
	v_lshlrev_b32_e32 v138, 16, v134
	v_and_b32_e32 v139, 0xffff0000, v134
	v_max_f32_e32 v112, 0x1e3ce508, v112
	v_pk_mul_f32 v[136:137], v[136:137], v[138:139]
	v_rcp_f32_e32 v138, v112
	v_max_f32_e32 v112, v162, v162
	v_max_f32_e32 v112, 0x1e3ce508, v112
	v_rcp_f32_e32 v132, v112
	v_max_f32_e32 v112, v157, v157
	v_max_f32_e32 v112, 0x1e3ce508, v112
	v_rcp_f32_e32 v139, v112
	v_max_f32_e32 v112, v163, v163
	v_max_f32_e32 v112, 0x1e3ce508, v112
	v_lshlrev_b32_e32 v156, 16, v133
	v_and_b32_e32 v157, 0xffff0000, v133
	v_rcp_f32_e32 v133, v112
	v_lshlrev_b32_e32 v134, 16, v135
	v_and_b32_e32 v135, 0xffff0000, v135
	v_pk_mul_f32 v[138:139], v[138:139], v[156:157]
	v_pk_mul_f32 v[132:133], v[132:133], v[134:135]
	v_pk_mul_f32 v[6:7], v[6:7], v[138:139]
	v_pk_mul_f32 v[4:5], v[4:5], v[114:115]
	v_pk_mul_f32 v[2:3], v[2:3], v[132:133]
	v_pk_mul_f32 v[0:1], v[0:1], v[136:137]
	s_branch .LBB0_434

; #define PG8_STAGE(bufoff, gbase, voff) do { _Pragma("unroll") for (int _i = 0; _i < 2; ++_i) \
;         __builtin_amdgcn_global_load_lds((const unsigned*)((const char*)(gbase) + (voff)[_i]), (PG8_LAS unsigned*)(lds + (bufoff) + ldsw + _i * 8192), 16, 0, 0); } while (0)
; #define PG8_LDA(dst, b, h) do { _Pragma("unroll") for (int m = 0; m < 4; ++m) _Pragma("unroll") for (int k = 0; k < 2; ++k) dst[m][k] = *(const PG8_LAS bf16x8*)(lds + PG8_SA(b, h) + aoff + m * 2048 + k * 1024); } while (0)
; #define PG8_LDB(dst, b, h) do { _Pragma("unroll") for (int n = 0; n < 2; ++n) _Pragma("unroll") for (int k = 0; k < 2; ++k) dst[n][k] = *(const PG8_LAS bf16x8*)(lds + PG8_SB(b, h) + boff + n * 2048 + k * 1024); } while (0)
; #define PG8_MMA(ai, bj, At, Bt) do { __builtin_amdgcn_s_setprio(1); _Pragma("unroll") for (int m = 0; m < 4; ++m) _Pragma("unroll") for (int n = 0; n < 2; ++n) _Pragma("unroll") for (int k = 0; k < 2; ++k) \
;         acc[ai][bj][m][n] = __builtin_amdgcn_mfma_f32_16x16x32_bf16(Bt[n][k], At[m][k], acc[ai][bj][m][n], 0, 0, 0); __builtin_amdgcn_s_setprio(0); } while (0)
; #define PG8_WAIT_V(n) asm volatile("s_waitcnt vmcnt(" #n ")" ::: "memory")
; #define PG8_WAIT_L(n) asm volatile("s_waitcnt lgkmcnt(" #n ")" ::: "memory")
; template <class Epi, class Sched, bool ALIGN_EPI = false, bool SP2 = false>
; __device__ __forceinline__ void gemm_phase(PG8_LAS unsigned char* lds, const Gemm g, const Sched& S, const Epi& E) {
;     ...
;             const bool last = (t == nt - 2);
;             const char* a1 = cA + (size_t)(t + 1) * kstep;
;             const char* a2 = last ? nA : cA + (size_t)(t + 2) * kstep; const char* b2 = last ? nB : cB + (size_t)(t + 2) * kstep;
;             const char* a3 = a2 + kstep; const char* b3 = b2 + kstep;
;             if (last && has_next) S.a_ready(nxt);
;             if constexpr (SP2) {
;             PG8_LDB(B0, 0, 0); PG8_LDB(B1, 0, 1); PG8_SCHED; PG8_LDA(At, 0, 0); PG8_STAGE(PG8_SA(1, 1), a1 + hstep, voffA);
;             PG8_WAIT_V(8); PG8_WAIT_L(0); PG8_BAR; PG8_MMA(0, 0, At, B0); PG8_MMA(0, 1, At, B1); PG8_BAR; PG8_SCHED;
;             PG8_LDA(At, 0, 1); PG8_STAGE(PG8_SB(0, 0), b2, voffB); PG8_STAGE(PG8_SB(0, 1), b2 + hstep, voffB); PG8_STAGE(PG8_SA(0, 0), a2, voffA);
;             PG8_WAIT_V(8); PG8_WAIT_L(0); PG8_BAR; PG8_MMA(1, 0, At, B0); PG8_MMA(1, 1, At, B1); PG8_BAR; PG8_SCHED;
.LBB0_511:
	s_add_u32 s40, s0, 0x100
	s_addc_u32 s41, s1, 0
	s_add_i32 s63, 0, 0x10000
	s_cmp_eq_u32 s60, 12
	s_cselect_b32 vcc_hi, s12, s41
	s_cselect_b32 vcc_lo, s13, s40
	s_cselect_b32 s57, s47, s61
	s_cselect_b32 s56, s49, s58
	s_add_i32 s65, 0, 0x14000
	v_add_u32_e32 v148, s63, v179
	v_add_u32_e32 v164, s65, v179
	ds_read_b128 v[136:139], v148
	ds_read_b128 v[140:143], v148 offset:1024
	ds_read_b128 v[144:147], v148 offset:2048
	ds_read_b128 v[148:151], v148 offset:3072
	ds_read_b128 v[152:155], v164
	ds_read_b128 v[156:159], v164 offset:1024
	ds_read_b128 v[160:163], v164 offset:2048
	ds_read_b128 v[164:167], v164 offset:3072
	v_lshl_add_u64 v[176:177], s[0:1], 0, v[132:133]
	s_add_i32 m0, s20, 0xc000
	ds_read_b128 v[168:171], v181
	ds_read_b128 v[172:175], v181 offset:1024
	ds_read_b128 v[184:187], v181 offset:2048
	ds_read_b128 v[200:203], v181 offset:3072
	ds_read_b128 v[204:207], v181 offset:4096
	ds_read_b128 v[208:211], v181 offset:5120
	ds_read_b128 v[224:227], v181 offset:6144
	ds_read_b128 v[228:231], v181 offset:7168
	global_load_lds_dwordx4 v[176:177], off
	v_lshl_add_u64 v[176:177], s[0:1], 0, v[134:135]
	s_add_i32 m0, s20, 0xe000
	s_nop 0
	global_load_lds_dwordx4 v[176:177], off
	s_waitcnt vmcnt(8)
	s_waitcnt lgkmcnt(0)
	s_barrier
	s_setprio 1
	v_mfma_f32_16x16x32_bf16 v[126:129], v[136:139], v[168:171], v[126:129]
	v_mfma_f32_16x16x32_bf16 v[122:125], v[144:147], v[168:171], v[122:125]
	v_mfma_f32_16x16x32_bf16 v[108:111], v[136:139], v[184:187], v[108:111]
	v_mfma_f32_16x16x32_bf16 v[104:107], v[144:147], v[184:187], v[104:107]
	v_mfma_f32_16x16x32_bf16 v[92:95], v[136:139], v[204:207], v[92:95]
	v_mfma_f32_16x16x32_bf16 v[88:91], v[144:147], v[204:207], v[88:91]
	v_mfma_f32_16x16x32_bf16 v[76:79], v[136:139], v[224:227], v[76:79]
	v_mfma_f32_16x16x32_bf16 v[72:75], v[144:147], v[224:227], v[72:75]
	v_mfma_f32_16x16x32_bf16 v[126:129], v[140:143], v[172:175], v[126:129]
	v_mfma_f32_16x16x32_bf16 v[122:125], v[148:151], v[172:175], v[122:125]
	v_mfma_f32_16x16x32_bf16 v[108:111], v[140:143], v[200:203], v[108:111]
	v_mfma_f32_16x16x32_bf16 v[104:107], v[148:151], v[200:203], v[104:107]
	v_mfma_f32_16x16x32_bf16 v[92:95], v[140:143], v[208:211], v[92:95]
	v_mfma_f32_16x16x32_bf16 v[88:91], v[148:151], v[208:211], v[88:91]
	v_mfma_f32_16x16x32_bf16 v[76:79], v[140:143], v[228:231], v[76:79]
	v_mfma_f32_16x16x32_bf16 v[72:75], v[148:151], v[228:231], v[72:75]
	s_setprio 0
	s_setprio 1
	v_mfma_f32_16x16x32_bf16 v[118:121], v[152:155], v[168:171], v[118:121]
	v_mfma_f32_16x16x32_bf16 v[114:117], v[160:163], v[168:171], v[114:117]
	v_mfma_f32_16x16x32_bf16 v[100:103], v[152:155], v[184:187], v[100:103]
	v_mfma_f32_16x16x32_bf16 v[96:99], v[160:163], v[184:187], v[96:99]
	v_mfma_f32_16x16x32_bf16 v[84:87], v[152:155], v[204:207], v[84:87]
	v_mfma_f32_16x16x32_bf16 v[80:83], v[160:163], v[204:207], v[80:83]
	v_mfma_f32_16x16x32_bf16 v[68:71], v[152:155], v[224:227], v[68:71]
	v_mfma_f32_16x16x32_bf16 v[64:67], v[160:163], v[224:227], v[64:67]
	v_mfma_f32_16x16x32_bf16 v[118:121], v[156:159], v[172:175], v[118:121]
	v_mfma_f32_16x16x32_bf16 v[114:117], v[164:167], v[172:175], v[114:117]
	v_mfma_f32_16x16x32_bf16 v[100:103], v[156:159], v[200:203], v[100:103]
	v_mfma_f32_16x16x32_bf16 v[96:99], v[164:167], v[200:203], v[96:99]
	v_mfma_f32_16x16x32_bf16 v[84:87], v[156:159], v[208:211], v[84:87]
	v_mfma_f32_16x16x32_bf16 v[80:83], v[164:167], v[208:211], v[80:83]
	v_mfma_f32_16x16x32_bf16 v[68:71], v[156:159], v[228:231], v[68:71]
	v_mfma_f32_16x16x32_bf16 v[64:67], v[164:167], v[228:231], v[64:67]
	s_setprio 0
	s_barrier
	s_add_i32 s0, s63, s19
	v_lshl_add_u64 v[176:177], s[56:57], 0, v[112:113]
	s_mov_b32 m0, s0
	ds_read_b128 v[168:171], v181 offset:16384
	ds_read_b128 v[172:175], v181 offset:17408
	ds_read_b128 v[184:187], v181 offset:18432
	ds_read_b128 v[200:203], v181 offset:19456
	ds_read_b128 v[204:207], v181 offset:20480
	ds_read_b128 v[208:211], v181 offset:21504
	ds_read_b128 v[224:227], v181 offset:22528
	ds_read_b128 v[228:231], v181 offset:23552
	global_load_lds_dwordx4 v[176:177], off
	s_add_i32 m0, s0, 0x2000
	s_add_u32 s0, s56, 0x40000
	v_lshl_add_u64 v[212:213], s[56:57], 0, v[130:131]
	s_addc_u32 s1, s57, 0
	s_add_i32 s63, s65, s19
	global_load_lds_dwordx4 v[212:213], off
	v_lshl_add_u64 v[232:233], s[0:1], 0, v[112:113]
	s_mov_b32 m0, s63
	v_lshl_add_u64 v[234:235], vcc, 0, v[130:131]
	global_load_lds_dwordx4 v[232:233], off
	v_lshl_add_u64 v[232:233], s[0:1], 0, v[130:131]
	s_add_i32 m0, s63, 0x2000
	s_nop 0
	global_load_lds_dwordx4 v[232:233], off
	v_lshl_add_u64 v[232:233], vcc, 0, v[112:113]
	s_mov_b32 m0, s20
	s_nop 0
	global_load_lds_dwordx4 v[232:233], off
	s_mov_b32 m0, s21
	s_nop 0
	global_load_lds_dwordx4 v[234:235], off
	s_waitcnt vmcnt(8)
	s_waitcnt lgkmcnt(0)
	s_barrier
; #define PG8_STAGE(bufoff, gbase, voff) do { _Pragma("unroll") for (int _i = 0; _i < 2; ++_i) \
;         __builtin_amdgcn_global_load_lds((const unsigned*)((const char*)(gbase) + (voff)[_i]), (PG8_LAS unsigned*)(lds + (bufoff) + ldsw + _i * 8192), 16, 0, 0); } while (0)
; #define PG8_LDA(dst, b, h) do { _Pragma("unroll") for (int m = 0; m < 4; ++m) _Pragma("unroll") for (int k = 0; k < 2; ++k) dst[m][k] = *(const PG8_LAS bf16x8*)(lds + PG8_SA(b, h) + aoff + m * 2048 + k * 1024); } while (0)
; #define PG8_LDB(dst, b, h) do { _Pragma("unroll") for (int n = 0; n < 2; ++n) _Pragma("unroll") for (int k = 0; k < 2; ++k) dst[n][k] = *(const PG8_LAS bf16x8*)(lds + PG8_SB(b, h) + boff + n * 2048 + k * 1024); } while (0)
; #define PG8_MMA(ai, bj, At, Bt) do { __builtin_amdgcn_s_setprio(1); _Pragma("unroll") for (int m = 0; m < 4; ++m) _Pragma("unroll") for (int n = 0; n < 2; ++n) _Pragma("unroll") for (int k = 0; k < 2; ++k) \
;         acc[ai][bj][m][n] = __builtin_amdgcn_mfma_f32_16x16x32_bf16(Bt[n][k], At[m][k], acc[ai][bj][m][n], 0, 0, 0); __builtin_amdgcn_s_setprio(0); } while (0)
; #define PG8_WAIT_V(n) asm volatile("s_waitcnt vmcnt(" #n ")" ::: "memory")
; #define PG8_WAIT_L(n) asm volatile("s_waitcnt lgkmcnt(" #n ")" ::: "memory")
; #define PG8_BAR __builtin_amdgcn_s_barrier()
; #define PG8_SCHED __builtin_amdgcn_sched_barrier(0)
; template <class Epi, class Sched, bool ALIGN_EPI = false, bool SP2 = false>
; __device__ __forceinline__ void gemm_phase(PG8_LAS unsigned char* lds, const Gemm g, const Sched& S, const Epi& E) {
;     ...
;             PG8_WAIT_V(8); PG8_WAIT_L(0); PG8_BAR; PG8_MMA(1, 0, At, B0); PG8_MMA(1, 1, At, B1); PG8_BAR; PG8_SCHED;
;             PG8_LDB(B0, 1, 0); PG8_LDB(B1, 1, 1); PG8_SCHED; PG8_LDA(At, 1, 0); PG8_STAGE(PG8_SA(0, 1), a2 + hstep, voffA);
;             PG8_WAIT_V(8); PG8_WAIT_L(0); PG8_BAR; PG8_MMA(0, 0, At, B0); PG8_MMA(0, 1, At, B1); PG8_BAR; PG8_SCHED;
	s_setprio 1
	v_mfma_f32_16x16x32_bf16 v[60:63], v[136:139], v[168:171], v[60:63]
	v_mfma_f32_16x16x32_bf16 v[56:59], v[144:147], v[168:171], v[56:59]
	v_mfma_f32_16x16x32_bf16 v[44:47], v[136:139], v[184:187], v[44:47]
	v_mfma_f32_16x16x32_bf16 v[40:43], v[144:147], v[184:187], v[40:43]
	v_mfma_f32_16x16x32_bf16 v[28:31], v[136:139], v[204:207], v[28:31]
	v_mfma_f32_16x16x32_bf16 v[24:27], v[144:147], v[204:207], v[24:27]
	v_mfma_f32_16x16x32_bf16 v[12:15], v[136:139], v[224:227], v[12:15]
	v_mfma_f32_16x16x32_bf16 v[8:11], v[144:147], v[224:227], v[8:11]
	v_mfma_f32_16x16x32_bf16 v[60:63], v[140:143], v[172:175], v[60:63]
	v_mfma_f32_16x16x32_bf16 v[56:59], v[148:151], v[172:175], v[56:59]
	v_mfma_f32_16x16x32_bf16 v[44:47], v[140:143], v[200:203], v[44:47]
	v_mfma_f32_16x16x32_bf16 v[40:43], v[148:151], v[200:203], v[40:43]
	v_mfma_f32_16x16x32_bf16 v[28:31], v[140:143], v[208:211], v[28:31]
	v_mfma_f32_16x16x32_bf16 v[24:27], v[148:151], v[208:211], v[24:27]
	v_mfma_f32_16x16x32_bf16 v[12:15], v[140:143], v[228:231], v[12:15]
	v_mfma_f32_16x16x32_bf16 v[8:11], v[148:151], v[228:231], v[8:11]
	s_setprio 0
	s_setprio 1
	v_mfma_f32_16x16x32_bf16 v[52:55], v[152:155], v[168:171], v[52:55]
	v_mfma_f32_16x16x32_bf16 v[48:51], v[160:163], v[168:171], v[48:51]
	v_mfma_f32_16x16x32_bf16 v[36:39], v[152:155], v[184:187], v[36:39]
	v_mfma_f32_16x16x32_bf16 v[32:35], v[160:163], v[184:187], v[32:35]
	v_mfma_f32_16x16x32_bf16 v[20:23], v[152:155], v[204:207], v[20:23]
	v_mfma_f32_16x16x32_bf16 v[16:19], v[160:163], v[204:207], v[16:19]
	v_mfma_f32_16x16x32_bf16 v[4:7], v[152:155], v[224:227], v[4:7]
	v_mfma_f32_16x16x32_bf16 v[0:3], v[160:163], v[224:227], v[0:3]
	v_mfma_f32_16x16x32_bf16 v[52:55], v[156:159], v[172:175], v[52:55]
	v_mfma_f32_16x16x32_bf16 v[48:51], v[164:167], v[172:175], v[48:51]
	v_mfma_f32_16x16x32_bf16 v[36:39], v[156:159], v[200:203], v[36:39]
	v_mfma_f32_16x16x32_bf16 v[32:35], v[164:167], v[200:203], v[32:35]
	v_mfma_f32_16x16x32_bf16 v[20:23], v[156:159], v[208:211], v[20:23]
	v_mfma_f32_16x16x32_bf16 v[16:19], v[164:167], v[208:211], v[16:19]
	v_mfma_f32_16x16x32_bf16 v[4:7], v[156:159], v[228:231], v[4:7]
	v_mfma_f32_16x16x32_bf16 v[0:3], v[164:167], v[228:231], v[0:3]
	s_setprio 0
	s_barrier
	s_add_i32 s63, 0, 0x18000
	s_add_i32 s65, 0, 0x1c000
	v_add_u32_e32 v148, s63, v179
	v_add_u32_e32 v164, s65, v179
	ds_read_b128 v[136:139], v148
	ds_read_b128 v[140:143], v148 offset:1024
	ds_read_b128 v[144:147], v148 offset:2048
	ds_read_b128 v[148:151], v148 offset:3072
	ds_read_b128 v[152:155], v164
	ds_read_b128 v[156:159], v164 offset:1024
	ds_read_b128 v[160:163], v164 offset:2048
	ds_read_b128 v[164:167], v164 offset:3072
	s_add_u32 s0, vcc_lo, 0x40000
	s_addc_u32 s1, vcc_hi, 0
	s_mov_b32 m0, s22
	v_lshl_add_u64 v[236:237], s[0:1], 0, v[112:113]
	ds_read_b128 v[168:171], v181 offset:32768
	ds_read_b128 v[172:175], v181 offset:33792
	ds_read_b128 v[184:187], v181 offset:34816
	ds_read_b128 v[200:203], v181 offset:35840
	ds_read_b128 v[204:207], v181 offset:36864
	ds_read_b128 v[208:211], v181 offset:37888
	ds_read_b128 v[224:227], v181 offset:38912
	ds_read_b128 v[228:231], v181 offset:39936
	global_load_lds_dwordx4 v[236:237], off
	v_lshl_add_u64 v[236:237], s[0:1], 0, v[130:131]
	s_mov_b32 m0, s23
	s_nop 0
	global_load_lds_dwordx4 v[236:237], off
	s_waitcnt vmcnt(8)
	s_waitcnt lgkmcnt(0)
	s_barrier
	s_setprio 1
	v_mfma_f32_16x16x32_bf16 v[126:129], v[136:139], v[168:171], v[126:129]
	v_mfma_f32_16x16x32_bf16 v[122:125], v[144:147], v[168:171], v[122:125]
	v_mfma_f32_16x16x32_bf16 v[108:111], v[136:139], v[184:187], v[108:111]
	v_mfma_f32_16x16x32_bf16 v[104:107], v[144:147], v[184:187], v[104:107]
	v_mfma_f32_16x16x32_bf16 v[92:95], v[136:139], v[204:207], v[92:95]
	v_mfma_f32_16x16x32_bf16 v[88:91], v[144:147], v[204:207], v[88:91]
	v_mfma_f32_16x16x32_bf16 v[76:79], v[136:139], v[224:227], v[76:79]
	v_mfma_f32_16x16x32_bf16 v[72:75], v[144:147], v[224:227], v[72:75]
	v_mfma_f32_16x16x32_bf16 v[126:129], v[140:143], v[172:175], v[126:129]
	v_mfma_f32_16x16x32_bf16 v[122:125], v[148:151], v[172:175], v[122:125]
	v_mfma_f32_16x16x32_bf16 v[108:111], v[140:143], v[200:203], v[108:111]
	v_mfma_f32_16x16x32_bf16 v[104:107], v[148:151], v[200:203], v[104:107]
	v_mfma_f32_16x16x32_bf16 v[92:95], v[140:143], v[208:211], v[92:95]
	v_mfma_f32_16x16x32_bf16 v[88:91], v[148:151], v[208:211], v[88:91]
	v_mfma_f32_16x16x32_bf16 v[76:79], v[140:143], v[228:231], v[76:79]
	v_mfma_f32_16x16x32_bf16 v[72:75], v[148:151], v[228:231], v[72:75]
	s_setprio 0
	s_setprio 1
	v_mfma_f32_16x16x32_bf16 v[118:121], v[152:155], v[168:171], v[118:121]
	v_mfma_f32_16x16x32_bf16 v[114:117], v[160:163], v[168:171], v[114:117]
	v_mfma_f32_16x16x32_bf16 v[100:103], v[152:155], v[184:187], v[100:103]
	v_mfma_f32_16x16x32_bf16 v[96:99], v[160:163], v[184:187], v[96:99]
	v_mfma_f32_16x16x32_bf16 v[84:87], v[152:155], v[204:207], v[84:87]
	v_mfma_f32_16x16x32_bf16 v[80:83], v[160:163], v[204:207], v[80:83]
	v_mfma_f32_16x16x32_bf16 v[68:71], v[152:155], v[224:227], v[68:71]
	v_mfma_f32_16x16x32_bf16 v[64:67], v[160:163], v[224:227], v[64:67]
	v_mfma_f32_16x16x32_bf16 v[118:121], v[156:159], v[172:175], v[118:121]
	v_mfma_f32_16x16x32_bf16 v[114:117], v[164:167], v[172:175], v[114:117]
	v_mfma_f32_16x16x32_bf16 v[100:103], v[156:159], v[200:203], v[100:103]
	v_mfma_f32_16x16x32_bf16 v[96:99], v[164:167], v[200:203], v[96:99]
	v_mfma_f32_16x16x32_bf16 v[84:87], v[156:159], v[208:211], v[84:87]
	v_mfma_f32_16x16x32_bf16 v[80:83], v[164:167], v[208:211], v[80:83]
	v_mfma_f32_16x16x32_bf16 v[68:71], v[156:159], v[228:231], v[68:71]
	v_mfma_f32_16x16x32_bf16 v[64:67], v[164:167], v[228:231], v[64:67]
	s_setprio 0
	s_barrier
; #define PG8_STAGE(bufoff, gbase, voff) do { _Pragma("unroll") for (int _i = 0; _i < 2; ++_i) \
;         __builtin_amdgcn_global_load_lds((const unsigned*)((const char*)(gbase) + (voff)[_i]), (PG8_LAS unsigned*)(lds + (bufoff) + ldsw + _i * 8192), 16, 0, 0); } while (0)
; #define PG8_LDA(dst, b, h) do { _Pragma("unroll") for (int m = 0; m < 4; ++m) _Pragma("unroll") for (int k = 0; k < 2; ++k) dst[m][k] = *(const PG8_LAS bf16x8*)(lds + PG8_SA(b, h) + aoff + m * 2048 + k * 1024); } while (0)
; #define PG8_MMA(ai, bj, At, Bt) do { __builtin_amdgcn_s_setprio(1); _Pragma("unroll") for (int m = 0; m < 4; ++m) _Pragma("unroll") for (int n = 0; n < 2; ++n) _Pragma("unroll") for (int k = 0; k < 2; ++k) \
;         acc[ai][bj][m][n] = __builtin_amdgcn_mfma_f32_16x16x32_bf16(Bt[n][k], At[m][k], acc[ai][bj][m][n], 0, 0, 0); __builtin_amdgcn_s_setprio(0); } while (0)
; #define PG8_WAIT_V(n) asm volatile("s_waitcnt vmcnt(" #n ")" ::: "memory")
; #define PG8_WAIT_L(n) asm volatile("s_waitcnt lgkmcnt(" #n ")" ::: "memory")
; #define PG8_BAR __builtin_amdgcn_s_barrier()
; #define PG8_SCHED __builtin_amdgcn_sched_barrier(0)
; template <class Epi, class Sched, bool ALIGN_EPI = false, bool SP2 = false>
; __device__ __forceinline__ void gemm_phase(PG8_LAS unsigned char* lds, const Gemm g, const Sched& S, const Epi& E) {
;     ...
;             PG8_LDA(At, 1, 1); PG8_STAGE(PG8_SB(1, 0), b3, voffB); PG8_STAGE(PG8_SB(1, 1), b3 + hstep, voffB); PG8_STAGE(PG8_SA(1, 0), a3, voffA);
;             PG8_WAIT_V(8); PG8_WAIT_L(0); PG8_BAR; PG8_MMA(1, 0, At, B0); PG8_MMA(1, 1, At, B1); PG8_BAR; PG8_SCHED;
;     ...
;         if constexpr (ALIGN_EPI) { if (wr == 0) PG8_BAR; }
	s_add_i32 s0, s63, s19
	v_lshl_add_u64 v[176:177], v[176:177], 0, s[36:37]
	s_mov_b32 m0, s0
	ds_read_b128 v[168:171], v181 offset:49152
	ds_read_b128 v[172:175], v181 offset:50176
	ds_read_b128 v[184:187], v181 offset:51200
	ds_read_b128 v[200:203], v181 offset:52224
	ds_read_b128 v[204:207], v181 offset:53248
	ds_read_b128 v[208:211], v181 offset:54272
	ds_read_b128 v[224:227], v181 offset:55296
	ds_read_b128 v[228:231], v181 offset:56320
	global_load_lds_dwordx4 v[176:177], off
	s_add_i32 m0, s0, 0x2000
	s_add_u32 s0, s56, 0x40080
	v_lshl_add_u64 v[176:177], v[212:213], 0, s[36:37]
	s_addc_u32 s1, s57, 0
	s_add_i32 s56, s65, s19
	global_load_lds_dwordx4 v[176:177], off
	v_lshl_add_u64 v[176:177], s[0:1], 0, v[112:113]
	s_mov_b32 m0, s56
	s_nop 0
	global_load_lds_dwordx4 v[176:177], off
	v_lshl_add_u64 v[176:177], s[0:1], 0, v[130:131]
	s_add_i32 m0, s56, 0x2000
	s_nop 0
	global_load_lds_dwordx4 v[176:177], off
	v_lshl_add_u64 v[176:177], v[232:233], 0, s[36:37]
	s_mov_b32 m0, s26
	s_nop 0
	global_load_lds_dwordx4 v[176:177], off
	v_lshl_add_u64 v[176:177], v[234:235], 0, s[36:37]
	s_mov_b32 m0, s33
	s_nop 0
	global_load_lds_dwordx4 v[176:177], off
	s_waitcnt vmcnt(8)
	s_waitcnt lgkmcnt(0)
	s_barrier
	s_setprio 1
	v_mfma_f32_16x16x32_bf16 v[60:63], v[136:139], v[168:171], v[60:63]
	v_mfma_f32_16x16x32_bf16 v[56:59], v[144:147], v[168:171], v[56:59]
	v_mfma_f32_16x16x32_bf16 v[44:47], v[136:139], v[184:187], v[44:47]
	v_mfma_f32_16x16x32_bf16 v[40:43], v[144:147], v[184:187], v[40:43]
	v_mfma_f32_16x16x32_bf16 v[28:31], v[136:139], v[204:207], v[28:31]
	v_mfma_f32_16x16x32_bf16 v[24:27], v[144:147], v[204:207], v[24:27]
	v_mfma_f32_16x16x32_bf16 v[12:15], v[136:139], v[224:227], v[12:15]
	v_mfma_f32_16x16x32_bf16 v[8:11], v[144:147], v[224:227], v[8:11]
	v_mfma_f32_16x16x32_bf16 v[60:63], v[140:143], v[172:175], v[60:63]
	v_mfma_f32_16x16x32_bf16 v[56:59], v[148:151], v[172:175], v[56:59]
	v_mfma_f32_16x16x32_bf16 v[44:47], v[140:143], v[200:203], v[44:47]
	v_mfma_f32_16x16x32_bf16 v[40:43], v[148:151], v[200:203], v[40:43]
	v_mfma_f32_16x16x32_bf16 v[28:31], v[140:143], v[208:211], v[28:31]
	v_mfma_f32_16x16x32_bf16 v[24:27], v[148:151], v[208:211], v[24:27]
	v_mfma_f32_16x16x32_bf16 v[12:15], v[140:143], v[228:231], v[12:15]
	v_mfma_f32_16x16x32_bf16 v[8:11], v[148:151], v[228:231], v[8:11]
	s_setprio 0
	s_setprio 1
	v_mfma_f32_16x16x32_bf16 v[52:55], v[152:155], v[168:171], v[52:55]
	v_mfma_f32_16x16x32_bf16 v[48:51], v[160:163], v[168:171], v[48:51]
	v_mfma_f32_16x16x32_bf16 v[36:39], v[152:155], v[184:187], v[36:39]
	v_mfma_f32_16x16x32_bf16 v[32:35], v[160:163], v[184:187], v[32:35]
	v_mfma_f32_16x16x32_bf16 v[20:23], v[152:155], v[204:207], v[20:23]
	v_mfma_f32_16x16x32_bf16 v[16:19], v[160:163], v[204:207], v[16:19]
	v_mfma_f32_16x16x32_bf16 v[4:7], v[152:155], v[224:227], v[4:7]
	v_mfma_f32_16x16x32_bf16 v[0:3], v[160:163], v[224:227], v[0:3]
	v_mfma_f32_16x16x32_bf16 v[52:55], v[156:159], v[172:175], v[52:55]
	v_mfma_f32_16x16x32_bf16 v[48:51], v[164:167], v[172:175], v[48:51]
	v_mfma_f32_16x16x32_bf16 v[36:39], v[156:159], v[200:203], v[36:39]
	v_mfma_f32_16x16x32_bf16 v[32:35], v[164:167], v[200:203], v[32:35]
	v_mfma_f32_16x16x32_bf16 v[20:23], v[156:159], v[208:211], v[20:23]
	v_mfma_f32_16x16x32_bf16 v[16:19], v[164:167], v[208:211], v[16:19]
	v_mfma_f32_16x16x32_bf16 v[4:7], v[156:159], v[228:231], v[4:7]
	v_mfma_f32_16x16x32_bf16 v[0:3], v[164:167], v[228:231], v[0:3]
	s_setprio 0
	s_barrier
	s_add_i32 s60, s60, 2
	s_add_u32 s58, s58, 0x100
	s_addc_u32 s61, s61, 0
	s_cmp_gt_u32 s60, 13
	s_mov_b64 s[0:1], s[40:41]
	s_cbranch_scc0 .LBB0_511
	s_and_b64 vcc, exec, s[42:43]
	s_cbranch_vccz .LBB0_514
	s_barrier

; #define PG8_STAGE(bufoff, gbase, voff) do { _Pragma("unroll") for (int _i = 0; _i < 2; ++_i) \
;         __builtin_amdgcn_global_load_lds((const unsigned*)((const char*)(gbase) + (voff)[_i]), (PG8_LAS unsigned*)(lds + (bufoff) + ldsw + _i * 8192), 16, 0, 0); } while (0)
; #define PG8_LDA(dst, b, h) do { _Pragma("unroll") for (int m = 0; m < 4; ++m) _Pragma("unroll") for (int k = 0; k < 2; ++k) dst[m][k] = *(const PG8_LAS bf16x8*)(lds + PG8_SA(b, h) + aoff + m * 2048 + k * 1024); } while (0)
; #define PG8_LDB(dst, b, h) do { _Pragma("unroll") for (int n = 0; n < 2; ++n) _Pragma("unroll") for (int k = 0; k < 2; ++k) dst[n][k] = *(const PG8_LAS bf16x8*)(lds + PG8_SB(b, h) + boff + n * 2048 + k * 1024); } while (0)
; #define PG8_MMA(ai, bj, At, Bt) do { __builtin_amdgcn_s_setprio(1); _Pragma("unroll") for (int m = 0; m < 4; ++m) _Pragma("unroll") for (int n = 0; n < 2; ++n) _Pragma("unroll") for (int k = 0; k < 2; ++k) \
;         acc[ai][bj][m][n] = __builtin_amdgcn_mfma_f32_16x16x32_bf16(Bt[n][k], At[m][k], acc[ai][bj][m][n], 0, 0, 0); __builtin_amdgcn_s_setprio(0); } while (0)
; #define PG8_WAIT_V(n) asm volatile("s_waitcnt vmcnt(" #n ")" ::: "memory")
; #define PG8_WAIT_L(n) asm volatile("s_waitcnt lgkmcnt(" #n ")" ::: "memory")
; template <class Epi, class Sched, bool ALIGN_EPI = false, bool SP2 = false>
; __device__ __forceinline__ void gemm_phase(PG8_LAS unsigned char* lds, const Gemm g, const Sched& S, const Epi& E) {
;     ...
;             const bool last = (t == nt - 2);
;             const char* a1 = cA + (size_t)(t + 1) * kstep;
;             const char* a2 = last ? nA : cA + (size_t)(t + 2) * kstep; const char* b2 = last ? nB : cB + (size_t)(t + 2) * kstep;
;             const char* a3 = a2 + kstep; const char* b3 = b2 + kstep;
;             if (last && has_next) S.a_ready(nxt);
;             if constexpr (SP2) {
;             PG8_LDB(B0, 0, 0); PG8_LDB(B1, 0, 1); PG8_SCHED; PG8_LDA(At, 0, 0); PG8_STAGE(PG8_SA(1, 1), a1 + hstep, voffA);
;             PG8_WAIT_V(8); PG8_WAIT_L(0); PG8_BAR; PG8_MMA(0, 0, At, B0); PG8_MMA(0, 1, At, B1); PG8_BAR; PG8_SCHED;
;             PG8_LDA(At, 0, 1); PG8_STAGE(PG8_SB(0, 0), b2, voffB); PG8_STAGE(PG8_SB(0, 1), b2 + hstep, voffB); PG8_STAGE(PG8_SA(0, 0), a2, voffA);
;             PG8_WAIT_V(8); PG8_WAIT_L(0); PG8_BAR; PG8_MMA(1, 0, At, B0); PG8_MMA(1, 1, At, B1); PG8_BAR; PG8_SCHED;
.LBB0_555:
	s_add_u32 s40, s0, 0xfffc0080
	s_addc_u32 s41, s1, -1
	s_add_i32 s63, 0, 0x10000
	s_cmp_eq_u32 s60, 12
	s_cselect_b32 s57, s12, s41
	s_cselect_b32 s56, s13, s40
	s_cselect_b32 s41, s47, s61
	s_cselect_b32 s40, s49, s58
	s_add_i32 s65, 0, 0x14000
	v_add_u32_e32 v142, s63, v224
	v_add_u32_e32 v158, s65, v224
	ds_read_b128 v[130:133], v142
	ds_read_b128 v[134:137], v142 offset:1024
	ds_read_b128 v[138:141], v142 offset:2048
	ds_read_b128 v[142:145], v142 offset:3072
	ds_read_b128 v[146:149], v158
	ds_read_b128 v[150:153], v158 offset:1024
	ds_read_b128 v[154:157], v158 offset:2048
	ds_read_b128 v[158:161], v158 offset:3072
	v_lshl_add_u64 v[228:229], s[0:1], 0, v[180:181]
	s_add_i32 m0, s20, 0xc000
	ds_read_b128 v[162:165], v226
	ds_read_b128 v[166:169], v226 offset:1024
	ds_read_b128 v[170:173], v226 offset:2048
	ds_read_b128 v[174:177], v226 offset:3072
	ds_read_b128 v[184:187], v226 offset:4096
	ds_read_b128 v[202:205], v226 offset:5120
	ds_read_b128 v[206:209], v226 offset:6144
	ds_read_b128 v[210:213], v226 offset:7168
	global_load_lds_dwordx4 v[228:229], off
	v_lshl_add_u64 v[228:229], s[0:1], 0, v[200:201]
	s_add_i32 m0, s20, 0xe000
	s_nop 0
	global_load_lds_dwordx4 v[228:229], off
	s_waitcnt vmcnt(8)
	s_waitcnt lgkmcnt(0)
	s_barrier
	s_setprio 1
	v_mfma_f32_16x16x32_bf16 v[126:129], v[130:133], v[162:165], v[126:129]
	v_mfma_f32_16x16x32_bf16 v[122:125], v[138:141], v[162:165], v[122:125]
	v_mfma_f32_16x16x32_bf16 v[108:111], v[130:133], v[170:173], v[108:111]
	v_mfma_f32_16x16x32_bf16 v[104:107], v[138:141], v[170:173], v[104:107]
	v_mfma_f32_16x16x32_bf16 v[92:95], v[130:133], v[184:187], v[92:95]
	v_mfma_f32_16x16x32_bf16 v[88:91], v[138:141], v[184:187], v[88:91]
	v_mfma_f32_16x16x32_bf16 v[76:79], v[130:133], v[206:209], v[76:79]
	v_mfma_f32_16x16x32_bf16 v[72:75], v[138:141], v[206:209], v[72:75]
	v_mfma_f32_16x16x32_bf16 v[126:129], v[134:137], v[166:169], v[126:129]
	v_mfma_f32_16x16x32_bf16 v[122:125], v[142:145], v[166:169], v[122:125]
	v_mfma_f32_16x16x32_bf16 v[108:111], v[134:137], v[174:177], v[108:111]
	v_mfma_f32_16x16x32_bf16 v[104:107], v[142:145], v[174:177], v[104:107]
	v_mfma_f32_16x16x32_bf16 v[92:95], v[134:137], v[202:205], v[92:95]
	v_mfma_f32_16x16x32_bf16 v[88:91], v[142:145], v[202:205], v[88:91]
	v_mfma_f32_16x16x32_bf16 v[76:79], v[134:137], v[210:213], v[76:79]
	v_mfma_f32_16x16x32_bf16 v[72:75], v[142:145], v[210:213], v[72:75]
	s_setprio 0
	s_setprio 1
	v_mfma_f32_16x16x32_bf16 v[118:121], v[146:149], v[162:165], v[118:121]
	v_mfma_f32_16x16x32_bf16 v[114:117], v[154:157], v[162:165], v[114:117]
	v_mfma_f32_16x16x32_bf16 v[100:103], v[146:149], v[170:173], v[100:103]
	v_mfma_f32_16x16x32_bf16 v[96:99], v[154:157], v[170:173], v[96:99]
	v_mfma_f32_16x16x32_bf16 v[84:87], v[146:149], v[184:187], v[84:87]
	v_mfma_f32_16x16x32_bf16 v[80:83], v[154:157], v[184:187], v[80:83]
	v_mfma_f32_16x16x32_bf16 v[68:71], v[146:149], v[206:209], v[68:71]
	v_mfma_f32_16x16x32_bf16 v[64:67], v[154:157], v[206:209], v[64:67]
	v_mfma_f32_16x16x32_bf16 v[118:121], v[150:153], v[166:169], v[118:121]
	v_mfma_f32_16x16x32_bf16 v[114:117], v[158:161], v[166:169], v[114:117]
	v_mfma_f32_16x16x32_bf16 v[100:103], v[150:153], v[174:177], v[100:103]
	v_mfma_f32_16x16x32_bf16 v[96:99], v[158:161], v[174:177], v[96:99]
	v_mfma_f32_16x16x32_bf16 v[84:87], v[150:153], v[202:205], v[84:87]
	v_mfma_f32_16x16x32_bf16 v[80:83], v[158:161], v[202:205], v[80:83]
	v_mfma_f32_16x16x32_bf16 v[68:71], v[150:153], v[210:213], v[68:71]
	v_mfma_f32_16x16x32_bf16 v[64:67], v[158:161], v[210:213], v[64:67]
	s_setprio 0
	s_barrier
	s_add_i32 s63, s63, s19
	v_lshl_add_u64 v[228:229], s[40:41], 0, v[112:113]
	s_mov_b32 m0, s63
	ds_read_b128 v[162:165], v226 offset:16384
	ds_read_b128 v[166:169], v226 offset:17408
	ds_read_b128 v[170:173], v226 offset:18432
	ds_read_b128 v[174:177], v226 offset:19456
	ds_read_b128 v[184:187], v226 offset:20480
	ds_read_b128 v[202:205], v226 offset:21504
	ds_read_b128 v[206:209], v226 offset:22528
	ds_read_b128 v[210:213], v226 offset:23552
	global_load_lds_dwordx4 v[228:229], off
	s_add_i32 m0, s63, 0x2000
	s_add_u32 s66, s40, 0x40000
	v_lshl_add_u64 v[230:231], s[40:41], 0, v[178:179]
	s_addc_u32 s67, s41, 0
	s_add_i32 s63, s65, s19
	global_load_lds_dwordx4 v[230:231], off
	v_lshl_add_u64 v[232:233], s[66:67], 0, v[112:113]
	s_mov_b32 m0, s63
	v_lshl_add_u64 v[234:235], s[56:57], 0, v[178:179]
	global_load_lds_dwordx4 v[232:233], off
	v_lshl_add_u64 v[232:233], s[66:67], 0, v[178:179]
	s_add_i32 m0, s63, 0x2000
	s_nop 0
	global_load_lds_dwordx4 v[232:233], off
	v_lshl_add_u64 v[232:233], s[56:57], 0, v[112:113]
	s_mov_b32 m0, s20
	s_nop 0
	global_load_lds_dwordx4 v[232:233], off
	s_mov_b32 m0, s21
	s_nop 0
	global_load_lds_dwordx4 v[234:235], off
	s_waitcnt vmcnt(8)
	s_waitcnt lgkmcnt(0)
	s_barrier
; #define PG8_STAGE(bufoff, gbase, voff) do { _Pragma("unroll") for (int _i = 0; _i < 2; ++_i) \
;         __builtin_amdgcn_global_load_lds((const unsigned*)((const char*)(gbase) + (voff)[_i]), (PG8_LAS unsigned*)(lds + (bufoff) + ldsw + _i * 8192), 16, 0, 0); } while (0)
; #define PG8_LDA(dst, b, h) do { _Pragma("unroll") for (int m = 0; m < 4; ++m) _Pragma("unroll") for (int k = 0; k < 2; ++k) dst[m][k] = *(const PG8_LAS bf16x8*)(lds + PG8_SA(b, h) + aoff + m * 2048 + k * 1024); } while (0)
; #define PG8_LDB(dst, b, h) do { _Pragma("unroll") for (int n = 0; n < 2; ++n) _Pragma("unroll") for (int k = 0; k < 2; ++k) dst[n][k] = *(const PG8_LAS bf16x8*)(lds + PG8_SB(b, h) + boff + n * 2048 + k * 1024); } while (0)
; #define PG8_MMA(ai, bj, At, Bt) do { __builtin_amdgcn_s_setprio(1); _Pragma("unroll") for (int m = 0; m < 4; ++m) _Pragma("unroll") for (int n = 0; n < 2; ++n) _Pragma("unroll") for (int k = 0; k < 2; ++k) \
;         acc[ai][bj][m][n] = __builtin_amdgcn_mfma_f32_16x16x32_bf16(Bt[n][k], At[m][k], acc[ai][bj][m][n], 0, 0, 0); __builtin_amdgcn_s_setprio(0); } while (0)
; #define PG8_WAIT_V(n) asm volatile("s_waitcnt vmcnt(" #n ")" ::: "memory")
; #define PG8_WAIT_L(n) asm volatile("s_waitcnt lgkmcnt(" #n ")" ::: "memory")
; #define PG8_BAR __builtin_amdgcn_s_barrier()
; #define PG8_SCHED __builtin_amdgcn_sched_barrier(0)
; template <class Epi, class Sched, bool ALIGN_EPI = false, bool SP2 = false>
; __device__ __forceinline__ void gemm_phase(PG8_LAS unsigned char* lds, const Gemm g, const Sched& S, const Epi& E) {
;     ...
;             PG8_WAIT_V(8); PG8_WAIT_L(0); PG8_BAR; PG8_MMA(1, 0, At, B0); PG8_MMA(1, 1, At, B1); PG8_BAR; PG8_SCHED;
;             PG8_LDB(B0, 1, 0); PG8_LDB(B1, 1, 1); PG8_SCHED; PG8_LDA(At, 1, 0); PG8_STAGE(PG8_SA(0, 1), a2 + hstep, voffA);
;             PG8_WAIT_V(8); PG8_WAIT_L(0); PG8_BAR; PG8_MMA(0, 0, At, B0); PG8_MMA(0, 1, At, B1); PG8_BAR; PG8_SCHED;
	s_setprio 1
	v_mfma_f32_16x16x32_bf16 v[60:63], v[130:133], v[162:165], v[60:63]
	v_mfma_f32_16x16x32_bf16 v[56:59], v[138:141], v[162:165], v[56:59]
	v_mfma_f32_16x16x32_bf16 v[44:47], v[130:133], v[170:173], v[44:47]
	v_mfma_f32_16x16x32_bf16 v[40:43], v[138:141], v[170:173], v[40:43]
	v_mfma_f32_16x16x32_bf16 v[28:31], v[130:133], v[184:187], v[28:31]
	v_mfma_f32_16x16x32_bf16 v[24:27], v[138:141], v[184:187], v[24:27]
	v_mfma_f32_16x16x32_bf16 v[12:15], v[130:133], v[206:209], v[12:15]
	v_mfma_f32_16x16x32_bf16 v[8:11], v[138:141], v[206:209], v[8:11]
	v_mfma_f32_16x16x32_bf16 v[60:63], v[134:137], v[166:169], v[60:63]
	v_mfma_f32_16x16x32_bf16 v[56:59], v[142:145], v[166:169], v[56:59]
	v_mfma_f32_16x16x32_bf16 v[44:47], v[134:137], v[174:177], v[44:47]
	v_mfma_f32_16x16x32_bf16 v[40:43], v[142:145], v[174:177], v[40:43]
	v_mfma_f32_16x16x32_bf16 v[28:31], v[134:137], v[202:205], v[28:31]
	v_mfma_f32_16x16x32_bf16 v[24:27], v[142:145], v[202:205], v[24:27]
	v_mfma_f32_16x16x32_bf16 v[12:15], v[134:137], v[210:213], v[12:15]
	v_mfma_f32_16x16x32_bf16 v[8:11], v[142:145], v[210:213], v[8:11]
	s_setprio 0
	s_setprio 1
	v_mfma_f32_16x16x32_bf16 v[52:55], v[146:149], v[162:165], v[52:55]
	v_mfma_f32_16x16x32_bf16 v[48:51], v[154:157], v[162:165], v[48:51]
	v_mfma_f32_16x16x32_bf16 v[36:39], v[146:149], v[170:173], v[36:39]
	v_mfma_f32_16x16x32_bf16 v[32:35], v[154:157], v[170:173], v[32:35]
	v_mfma_f32_16x16x32_bf16 v[20:23], v[146:149], v[184:187], v[20:23]
	v_mfma_f32_16x16x32_bf16 v[16:19], v[154:157], v[184:187], v[16:19]
	v_mfma_f32_16x16x32_bf16 v[4:7], v[146:149], v[206:209], v[4:7]
	v_mfma_f32_16x16x32_bf16 v[0:3], v[154:157], v[206:209], v[0:3]
	v_mfma_f32_16x16x32_bf16 v[52:55], v[150:153], v[166:169], v[52:55]
	v_mfma_f32_16x16x32_bf16 v[48:51], v[158:161], v[166:169], v[48:51]
	v_mfma_f32_16x16x32_bf16 v[36:39], v[150:153], v[174:177], v[36:39]
	v_mfma_f32_16x16x32_bf16 v[32:35], v[158:161], v[174:177], v[32:35]
	v_mfma_f32_16x16x32_bf16 v[20:23], v[150:153], v[202:205], v[20:23]
	v_mfma_f32_16x16x32_bf16 v[16:19], v[158:161], v[202:205], v[16:19]
	v_mfma_f32_16x16x32_bf16 v[4:7], v[150:153], v[210:213], v[4:7]
	v_mfma_f32_16x16x32_bf16 v[0:3], v[158:161], v[210:213], v[0:3]
	s_setprio 0
	s_barrier
	s_add_i32 s63, 0, 0x18000
	s_add_i32 s65, 0, 0x1c000
	v_add_u32_e32 v142, s63, v224
	v_add_u32_e32 v158, s65, v224
	ds_read_b128 v[130:133], v142
	ds_read_b128 v[134:137], v142 offset:1024
	ds_read_b128 v[138:141], v142 offset:2048
	ds_read_b128 v[142:145], v142 offset:3072
	ds_read_b128 v[146:149], v158
	ds_read_b128 v[150:153], v158 offset:1024
	ds_read_b128 v[154:157], v158 offset:2048
	ds_read_b128 v[158:161], v158 offset:3072
	s_add_u32 s56, s56, 0x40000
	s_addc_u32 s57, s57, 0
	s_mov_b32 m0, s22
	v_lshl_add_u64 v[236:237], s[56:57], 0, v[112:113]
	ds_read_b128 v[162:165], v226 offset:32768
	ds_read_b128 v[166:169], v226 offset:33792
	ds_read_b128 v[170:173], v226 offset:34816
	ds_read_b128 v[174:177], v226 offset:35840
	ds_read_b128 v[184:187], v226 offset:36864
	ds_read_b128 v[202:205], v226 offset:37888
	ds_read_b128 v[206:209], v226 offset:38912
	ds_read_b128 v[210:213], v226 offset:39936
	global_load_lds_dwordx4 v[236:237], off
	v_lshl_add_u64 v[236:237], s[56:57], 0, v[178:179]
	s_mov_b32 m0, s23
	s_nop 0
	global_load_lds_dwordx4 v[236:237], off
	s_waitcnt vmcnt(8)
	s_waitcnt lgkmcnt(0)
	s_barrier
	s_setprio 1
	v_mfma_f32_16x16x32_bf16 v[126:129], v[130:133], v[162:165], v[126:129]
	v_mfma_f32_16x16x32_bf16 v[122:125], v[138:141], v[162:165], v[122:125]
	v_mfma_f32_16x16x32_bf16 v[108:111], v[130:133], v[170:173], v[108:111]
	v_mfma_f32_16x16x32_bf16 v[104:107], v[138:141], v[170:173], v[104:107]
	v_mfma_f32_16x16x32_bf16 v[92:95], v[130:133], v[184:187], v[92:95]
	v_mfma_f32_16x16x32_bf16 v[88:91], v[138:141], v[184:187], v[88:91]
	v_mfma_f32_16x16x32_bf16 v[76:79], v[130:133], v[206:209], v[76:79]
	v_mfma_f32_16x16x32_bf16 v[72:75], v[138:141], v[206:209], v[72:75]
	v_mfma_f32_16x16x32_bf16 v[126:129], v[134:137], v[166:169], v[126:129]
	v_mfma_f32_16x16x32_bf16 v[122:125], v[142:145], v[166:169], v[122:125]
	v_mfma_f32_16x16x32_bf16 v[108:111], v[134:137], v[174:177], v[108:111]
	v_mfma_f32_16x16x32_bf16 v[104:107], v[142:145], v[174:177], v[104:107]
	v_mfma_f32_16x16x32_bf16 v[92:95], v[134:137], v[202:205], v[92:95]
	v_mfma_f32_16x16x32_bf16 v[88:91], v[142:145], v[202:205], v[88:91]
	v_mfma_f32_16x16x32_bf16 v[76:79], v[134:137], v[210:213], v[76:79]
	v_mfma_f32_16x16x32_bf16 v[72:75], v[142:145], v[210:213], v[72:75]
	s_setprio 0
	s_setprio 1
	v_mfma_f32_16x16x32_bf16 v[118:121], v[146:149], v[162:165], v[118:121]
	v_mfma_f32_16x16x32_bf16 v[114:117], v[154:157], v[162:165], v[114:117]
	v_mfma_f32_16x16x32_bf16 v[100:103], v[146:149], v[170:173], v[100:103]
	v_mfma_f32_16x16x32_bf16 v[96:99], v[154:157], v[170:173], v[96:99]
	v_mfma_f32_16x16x32_bf16 v[84:87], v[146:149], v[184:187], v[84:87]
	v_mfma_f32_16x16x32_bf16 v[80:83], v[154:157], v[184:187], v[80:83]
	v_mfma_f32_16x16x32_bf16 v[68:71], v[146:149], v[206:209], v[68:71]
	v_mfma_f32_16x16x32_bf16 v[64:67], v[154:157], v[206:209], v[64:67]
	v_mfma_f32_16x16x32_bf16 v[118:121], v[150:153], v[166:169], v[118:121]
	v_mfma_f32_16x16x32_bf16 v[114:117], v[158:161], v[166:169], v[114:117]
	v_mfma_f32_16x16x32_bf16 v[100:103], v[150:153], v[174:177], v[100:103]
	v_mfma_f32_16x16x32_bf16 v[96:99], v[158:161], v[174:177], v[96:99]
	v_mfma_f32_16x16x32_bf16 v[84:87], v[150:153], v[202:205], v[84:87]
	v_mfma_f32_16x16x32_bf16 v[80:83], v[158:161], v[202:205], v[80:83]
	v_mfma_f32_16x16x32_bf16 v[68:71], v[150:153], v[210:213], v[68:71]
	v_mfma_f32_16x16x32_bf16 v[64:67], v[158:161], v[210:213], v[64:67]
	s_setprio 0
	s_barrier
; #define PG8_STAGE(bufoff, gbase, voff) do { _Pragma("unroll") for (int _i = 0; _i < 2; ++_i) \
;         __builtin_amdgcn_global_load_lds((const unsigned*)((const char*)(gbase) + (voff)[_i]), (PG8_LAS unsigned*)(lds + (bufoff) + ldsw + _i * 8192), 16, 0, 0); } while (0)
; #define PG8_LDA(dst, b, h) do { _Pragma("unroll") for (int m = 0; m < 4; ++m) _Pragma("unroll") for (int k = 0; k < 2; ++k) dst[m][k] = *(const PG8_LAS bf16x8*)(lds + PG8_SA(b, h) + aoff + m * 2048 + k * 1024); } while (0)
; #define PG8_MMA(ai, bj, At, Bt) do { __builtin_amdgcn_s_setprio(1); _Pragma("unroll") for (int m = 0; m < 4; ++m) _Pragma("unroll") for (int n = 0; n < 2; ++n) _Pragma("unroll") for (int k = 0; k < 2; ++k) \
;         acc[ai][bj][m][n] = __builtin_amdgcn_mfma_f32_16x16x32_bf16(Bt[n][k], At[m][k], acc[ai][bj][m][n], 0, 0, 0); __builtin_amdgcn_s_setprio(0); } while (0)
; #define PG8_WAIT_V(n) asm volatile("s_waitcnt vmcnt(" #n ")" ::: "memory")
; #define PG8_WAIT_L(n) asm volatile("s_waitcnt lgkmcnt(" #n ")" ::: "memory")
; #define PG8_BAR __builtin_amdgcn_s_barrier()
; #define PG8_SCHED __builtin_amdgcn_sched_barrier(0)
; template <class Epi, class Sched, bool ALIGN_EPI = false, bool SP2 = false>
; __device__ __forceinline__ void gemm_phase(PG8_LAS unsigned char* lds, const Gemm g, const Sched& S, const Epi& E) {
;     ...
;             PG8_LDA(At, 1, 1); PG8_STAGE(PG8_SB(1, 0), b3, voffB); PG8_STAGE(PG8_SB(1, 1), b3 + hstep, voffB); PG8_STAGE(PG8_SA(1, 0), a3, voffA);
;             PG8_WAIT_V(8); PG8_WAIT_L(0); PG8_BAR; PG8_MMA(1, 0, At, B0); PG8_MMA(1, 1, At, B1); PG8_BAR; PG8_SCHED;
;     ...
;         if constexpr (ALIGN_EPI) { if (wr == 0) PG8_BAR; }
	s_add_i32 s56, s63, s19
	v_lshl_add_u64 v[228:229], v[228:229], 0, s[36:37]
	s_mov_b32 m0, s56
	ds_read_b128 v[162:165], v226 offset:49152
	ds_read_b128 v[166:169], v226 offset:50176
	ds_read_b128 v[170:173], v226 offset:51200
	ds_read_b128 v[174:177], v226 offset:52224
	ds_read_b128 v[184:187], v226 offset:53248
	ds_read_b128 v[202:205], v226 offset:54272
	ds_read_b128 v[206:209], v226 offset:55296
	ds_read_b128 v[210:213], v226 offset:56320
	global_load_lds_dwordx4 v[228:229], off
	s_add_i32 m0, s56, 0x2000
	s_add_u32 s40, s40, 0x40080
	v_lshl_add_u64 v[228:229], v[230:231], 0, s[36:37]
	s_addc_u32 s41, s41, 0
	s_add_i32 s56, s65, s19
	global_load_lds_dwordx4 v[228:229], off
	v_lshl_add_u64 v[228:229], s[40:41], 0, v[112:113]
	s_mov_b32 m0, s56
	s_nop 0
	global_load_lds_dwordx4 v[228:229], off
	v_lshl_add_u64 v[228:229], s[40:41], 0, v[178:179]
	s_add_i32 m0, s56, 0x2000
	s_nop 0
	global_load_lds_dwordx4 v[228:229], off
	v_lshl_add_u64 v[228:229], v[232:233], 0, s[36:37]
	s_mov_b32 m0, s26
	s_nop 0
	global_load_lds_dwordx4 v[228:229], off
	v_lshl_add_u64 v[228:229], v[234:235], 0, s[36:37]
	s_mov_b32 m0, s33
	s_nop 0
	global_load_lds_dwordx4 v[228:229], off
	s_waitcnt vmcnt(8)
	s_waitcnt lgkmcnt(0)
	s_barrier
	s_setprio 1
	v_mfma_f32_16x16x32_bf16 v[60:63], v[130:133], v[162:165], v[60:63]
	v_mfma_f32_16x16x32_bf16 v[56:59], v[138:141], v[162:165], v[56:59]
	v_mfma_f32_16x16x32_bf16 v[44:47], v[130:133], v[170:173], v[44:47]
	v_mfma_f32_16x16x32_bf16 v[40:43], v[138:141], v[170:173], v[40:43]
	v_mfma_f32_16x16x32_bf16 v[28:31], v[130:133], v[184:187], v[28:31]
	v_mfma_f32_16x16x32_bf16 v[24:27], v[138:141], v[184:187], v[24:27]
	v_mfma_f32_16x16x32_bf16 v[12:15], v[130:133], v[206:209], v[12:15]
	v_mfma_f32_16x16x32_bf16 v[8:11], v[138:141], v[206:209], v[8:11]
	v_mfma_f32_16x16x32_bf16 v[60:63], v[134:137], v[166:169], v[60:63]
	v_mfma_f32_16x16x32_bf16 v[56:59], v[142:145], v[166:169], v[56:59]
	v_mfma_f32_16x16x32_bf16 v[44:47], v[134:137], v[174:177], v[44:47]
	v_mfma_f32_16x16x32_bf16 v[40:43], v[142:145], v[174:177], v[40:43]
	v_mfma_f32_16x16x32_bf16 v[28:31], v[134:137], v[202:205], v[28:31]
	v_mfma_f32_16x16x32_bf16 v[24:27], v[142:145], v[202:205], v[24:27]
	v_mfma_f32_16x16x32_bf16 v[12:15], v[134:137], v[210:213], v[12:15]
	v_mfma_f32_16x16x32_bf16 v[8:11], v[142:145], v[210:213], v[8:11]
	s_setprio 0
	s_setprio 1
	v_mfma_f32_16x16x32_bf16 v[52:55], v[146:149], v[162:165], v[52:55]
	v_mfma_f32_16x16x32_bf16 v[48:51], v[154:157], v[162:165], v[48:51]
	v_mfma_f32_16x16x32_bf16 v[36:39], v[146:149], v[170:173], v[36:39]
	v_mfma_f32_16x16x32_bf16 v[32:35], v[154:157], v[170:173], v[32:35]
	v_mfma_f32_16x16x32_bf16 v[20:23], v[146:149], v[184:187], v[20:23]
	v_mfma_f32_16x16x32_bf16 v[16:19], v[154:157], v[184:187], v[16:19]
	v_mfma_f32_16x16x32_bf16 v[4:7], v[146:149], v[206:209], v[4:7]
	v_mfma_f32_16x16x32_bf16 v[0:3], v[154:157], v[206:209], v[0:3]
	v_mfma_f32_16x16x32_bf16 v[52:55], v[150:153], v[166:169], v[52:55]
	v_mfma_f32_16x16x32_bf16 v[48:51], v[158:161], v[166:169], v[48:51]
	v_mfma_f32_16x16x32_bf16 v[36:39], v[150:153], v[174:177], v[36:39]
	v_mfma_f32_16x16x32_bf16 v[32:35], v[158:161], v[174:177], v[32:35]
	v_mfma_f32_16x16x32_bf16 v[20:23], v[150:153], v[202:205], v[20:23]
	v_mfma_f32_16x16x32_bf16 v[16:19], v[158:161], v[202:205], v[16:19]
	v_mfma_f32_16x16x32_bf16 v[4:7], v[150:153], v[210:213], v[4:7]
	v_mfma_f32_16x16x32_bf16 v[0:3], v[158:161], v[210:213], v[0:3]
	s_setprio 0
	s_barrier
	s_add_i32 s60, s60, 2
	s_add_u32 s0, s0, 0x100
	s_addc_u32 s1, s1, 0
	s_add_u32 s58, s58, 0x100
	s_addc_u32 s61, s61, 0
	s_cmp_gt_u32 s60, 13
	s_cbranch_scc0 .LBB0_555
	s_mov_b32 s49, s79
	s_mov_b32 s47, s78
	s_mov_b64 s[56:57], s[76:77]
	s_and_b64 vcc, exec, s[42:43]
	s_cbranch_vccz .LBB0_558
	s_barrier

; #define PG8_STAGE(bufoff, gbase, voff) do { _Pragma("unroll") for (int _i = 0; _i < 2; ++_i) \
;         __builtin_amdgcn_global_load_lds((const unsigned*)((const char*)(gbase) + (voff)[_i]), (PG8_LAS unsigned*)(lds + (bufoff) + ldsw + _i * 8192), 16, 0, 0); } while (0)
; #define PG8_LDA(dst, b, h) do { _Pragma("unroll") for (int m = 0; m < 4; ++m) _Pragma("unroll") for (int k = 0; k < 2; ++k) dst[m][k] = *(const PG8_LAS bf16x8*)(lds + PG8_SA(b, h) + aoff + m * 2048 + k * 1024); } while (0)
; #define PG8_LDB(dst, b, h) do { _Pragma("unroll") for (int n = 0; n < 2; ++n) _Pragma("unroll") for (int k = 0; k < 2; ++k) dst[n][k] = *(const PG8_LAS bf16x8*)(lds + PG8_SB(b, h) + boff + n * 2048 + k * 1024); } while (0)
; #define PG8_MMA(ai, bj, At, Bt) do { __builtin_amdgcn_s_setprio(1); _Pragma("unroll") for (int m = 0; m < 4; ++m) _Pragma("unroll") for (int n = 0; n < 2; ++n) _Pragma("unroll") for (int k = 0; k < 2; ++k) \
;         acc[ai][bj][m][n] = __builtin_amdgcn_mfma_f32_16x16x32_bf16(Bt[n][k], At[m][k], acc[ai][bj][m][n], 0, 0, 0); __builtin_amdgcn_s_setprio(0); } while (0)
; #define PG8_WAIT_V(n) asm volatile("s_waitcnt vmcnt(" #n ")" ::: "memory")
; #define PG8_WAIT_L(n) asm volatile("s_waitcnt lgkmcnt(" #n ")" ::: "memory")
; template <class Epi, class Sched, bool ALIGN_EPI = false, bool SP2 = false>
; __device__ __forceinline__ void gemm_phase(PG8_LAS unsigned char* lds, const Gemm g, const Sched& S, const Epi& E) {
;     ...
;             const bool last = (t == nt - 2);
;             const char* a1 = cA + (size_t)(t + 1) * kstep;
;             const char* a2 = last ? nA : cA + (size_t)(t + 2) * kstep; const char* b2 = last ? nB : cB + (size_t)(t + 2) * kstep;
;             const char* a3 = a2 + kstep; const char* b3 = b2 + kstep;
;             if (last && has_next) S.a_ready(nxt);
;             if constexpr (SP2) {
;             PG8_LDB(B0, 0, 0); PG8_LDB(B1, 0, 1); PG8_SCHED; PG8_LDA(At, 0, 0); PG8_STAGE(PG8_SA(1, 1), a1 + hstep, voffA);
;             PG8_WAIT_V(8); PG8_WAIT_L(0); PG8_BAR; PG8_MMA(0, 0, At, B0); PG8_MMA(0, 1, At, B1); PG8_BAR; PG8_SCHED;
;             PG8_LDA(At, 0, 1); PG8_STAGE(PG8_SB(0, 0), b2, voffB); PG8_STAGE(PG8_SB(0, 1), b2 + hstep, voffB); PG8_STAGE(PG8_SA(0, 0), a2, voffA);
;             PG8_WAIT_V(8); PG8_WAIT_L(0); PG8_BAR; PG8_MMA(1, 0, At, B0); PG8_MMA(1, 1, At, B1); PG8_BAR; PG8_SCHED;
.LBB0_643:
	s_add_u32 s40, s54, 0xfffc0080
	s_addc_u32 s41, s55, -1
	s_add_i32 s61, 0, 0x10000
	s_cmp_eq_u32 s60, 12
	s_cselect_b32 s57, s12, s41
	s_cselect_b32 s56, s13, s40
	v_add_u32_e32 v140, s61, v143
	s_cselect_b32 s41, s43, s58
	s_cselect_b32 s40, s47, s53
	s_add_i32 s64, 0, 0x14000
	ds_read_b128 v[146:149], v140
	ds_read_b128 v[150:153], v140 offset:1024
	ds_read_b128 v[154:157], v140 offset:2048
	ds_read_b128 v[158:161], v140 offset:3072
	v_add_u32_e32 v140, s64, v143
	ds_read_b128 v[162:165], v140
	ds_read_b128 v[166:169], v140 offset:1024
	ds_read_b128 v[170:173], v140 offset:2048
	ds_read_b128 v[174:177], v140 offset:3072
	v_lshl_add_u64 v[140:141], s[54:55], 0, v[136:137]
	s_add_i32 m0, s21, 0xc000
	ds_read_b128 v[178:181], v145
	ds_read_b128 v[184:187], v145 offset:1024
	ds_read_b128 v[200:203], v145 offset:2048
	ds_read_b128 v[204:207], v145 offset:3072
	ds_read_b128 v[208:211], v145 offset:4096
	ds_read_b128 v[224:227], v145 offset:5120
	ds_read_b128 v[228:231], v145 offset:6144
	ds_read_b128 v[232:235], v145 offset:7168
	global_load_lds_dwordx4 v[140:141], off
	v_lshl_add_u64 v[140:141], s[54:55], 0, v[138:139]
	s_add_i32 m0, s21, 0xe000
	s_nop 0
	global_load_lds_dwordx4 v[140:141], off
	s_waitcnt vmcnt(8)
	s_waitcnt lgkmcnt(0)
	s_barrier
	s_setprio 1
	v_mfma_f32_16x16x32_bf16 v[126:129], v[146:149], v[178:181], v[126:129]
	v_mfma_f32_16x16x32_bf16 v[122:125], v[154:157], v[178:181], v[122:125]
	v_mfma_f32_16x16x32_bf16 v[108:111], v[146:149], v[200:203], v[108:111]
	v_mfma_f32_16x16x32_bf16 v[104:107], v[154:157], v[200:203], v[104:107]
	v_mfma_f32_16x16x32_bf16 v[92:95], v[146:149], v[208:211], v[92:95]
	v_mfma_f32_16x16x32_bf16 v[88:91], v[154:157], v[208:211], v[88:91]
	v_mfma_f32_16x16x32_bf16 v[76:79], v[146:149], v[228:231], v[76:79]
	v_mfma_f32_16x16x32_bf16 v[72:75], v[154:157], v[228:231], v[72:75]
	v_mfma_f32_16x16x32_bf16 v[126:129], v[150:153], v[184:187], v[126:129]
	v_mfma_f32_16x16x32_bf16 v[122:125], v[158:161], v[184:187], v[122:125]
	v_mfma_f32_16x16x32_bf16 v[108:111], v[150:153], v[204:207], v[108:111]
	v_mfma_f32_16x16x32_bf16 v[104:107], v[158:161], v[204:207], v[104:107]
	v_mfma_f32_16x16x32_bf16 v[92:95], v[150:153], v[224:227], v[92:95]
	v_mfma_f32_16x16x32_bf16 v[88:91], v[158:161], v[224:227], v[88:91]
	v_mfma_f32_16x16x32_bf16 v[76:79], v[150:153], v[232:235], v[76:79]
	v_mfma_f32_16x16x32_bf16 v[72:75], v[158:161], v[232:235], v[72:75]
	s_setprio 0
	s_setprio 1
	v_mfma_f32_16x16x32_bf16 v[118:121], v[162:165], v[178:181], v[118:121]
	v_mfma_f32_16x16x32_bf16 v[114:117], v[170:173], v[178:181], v[114:117]
	v_mfma_f32_16x16x32_bf16 v[100:103], v[162:165], v[200:203], v[100:103]
	v_mfma_f32_16x16x32_bf16 v[96:99], v[170:173], v[200:203], v[96:99]
	v_mfma_f32_16x16x32_bf16 v[84:87], v[162:165], v[208:211], v[84:87]
	v_mfma_f32_16x16x32_bf16 v[80:83], v[170:173], v[208:211], v[80:83]
	v_mfma_f32_16x16x32_bf16 v[68:71], v[162:165], v[228:231], v[68:71]
	v_mfma_f32_16x16x32_bf16 v[64:67], v[170:173], v[228:231], v[64:67]
	v_mfma_f32_16x16x32_bf16 v[118:121], v[166:169], v[184:187], v[118:121]
	v_mfma_f32_16x16x32_bf16 v[114:117], v[174:177], v[184:187], v[114:117]
	v_mfma_f32_16x16x32_bf16 v[100:103], v[166:169], v[204:207], v[100:103]
	v_mfma_f32_16x16x32_bf16 v[96:99], v[174:177], v[204:207], v[96:99]
	v_mfma_f32_16x16x32_bf16 v[84:87], v[166:169], v[224:227], v[84:87]
	v_mfma_f32_16x16x32_bf16 v[80:83], v[174:177], v[224:227], v[80:83]
	v_mfma_f32_16x16x32_bf16 v[68:71], v[166:169], v[232:235], v[68:71]
	v_mfma_f32_16x16x32_bf16 v[64:67], v[174:177], v[232:235], v[64:67]
	s_setprio 0
	s_barrier
	s_add_i32 s61, s61, s20
	v_lshl_add_u64 v[140:141], s[40:41], 0, v[112:113]
	s_mov_b32 m0, s61
	ds_read_b128 v[178:181], v145 offset:16384
	ds_read_b128 v[184:187], v145 offset:17408
	ds_read_b128 v[200:203], v145 offset:18432
	ds_read_b128 v[204:207], v145 offset:19456
	ds_read_b128 v[208:211], v145 offset:20480
	ds_read_b128 v[224:227], v145 offset:21504
	ds_read_b128 v[228:231], v145 offset:22528
	ds_read_b128 v[232:235], v145 offset:23552
	global_load_lds_dwordx4 v[140:141], off
	s_add_i32 m0, s61, 0x2000
	s_add_u32 s62, s40, 0x40000
	v_lshl_add_u64 v[212:213], s[40:41], 0, v[134:135]
	s_addc_u32 s63, s41, 0
	s_add_i32 s61, s64, s20
	global_load_lds_dwordx4 v[212:213], off
	v_lshl_add_u64 v[236:237], s[62:63], 0, v[112:113]
	s_mov_b32 m0, s61
	v_lshl_add_u64 v[238:239], s[56:57], 0, v[132:133]
	global_load_lds_dwordx4 v[236:237], off
	v_lshl_add_u64 v[236:237], s[62:63], 0, v[134:135]
	s_add_i32 m0, s61, 0x2000
	s_nop 0
	global_load_lds_dwordx4 v[236:237], off
	v_lshl_add_u64 v[236:237], s[56:57], 0, v[130:131]
	s_mov_b32 m0, s21
	s_nop 0
	global_load_lds_dwordx4 v[236:237], off
	s_mov_b32 m0, s22
	s_nop 0
	global_load_lds_dwordx4 v[238:239], off
	s_waitcnt vmcnt(8)
	s_waitcnt lgkmcnt(0)
	s_barrier
; #define PG8_STAGE(bufoff, gbase, voff) do { _Pragma("unroll") for (int _i = 0; _i < 2; ++_i) \
;         __builtin_amdgcn_global_load_lds((const unsigned*)((const char*)(gbase) + (voff)[_i]), (PG8_LAS unsigned*)(lds + (bufoff) + ldsw + _i * 8192), 16, 0, 0); } while (0)
; #define PG8_LDA(dst, b, h) do { _Pragma("unroll") for (int m = 0; m < 4; ++m) _Pragma("unroll") for (int k = 0; k < 2; ++k) dst[m][k] = *(const PG8_LAS bf16x8*)(lds + PG8_SA(b, h) + aoff + m * 2048 + k * 1024); } while (0)
; #define PG8_LDB(dst, b, h) do { _Pragma("unroll") for (int n = 0; n < 2; ++n) _Pragma("unroll") for (int k = 0; k < 2; ++k) dst[n][k] = *(const PG8_LAS bf16x8*)(lds + PG8_SB(b, h) + boff + n * 2048 + k * 1024); } while (0)
; #define PG8_MMA(ai, bj, At, Bt) do { __builtin_amdgcn_s_setprio(1); _Pragma("unroll") for (int m = 0; m < 4; ++m) _Pragma("unroll") for (int n = 0; n < 2; ++n) _Pragma("unroll") for (int k = 0; k < 2; ++k) \
;         acc[ai][bj][m][n] = __builtin_amdgcn_mfma_f32_16x16x32_bf16(Bt[n][k], At[m][k], acc[ai][bj][m][n], 0, 0, 0); __builtin_amdgcn_s_setprio(0); } while (0)
; #define PG8_WAIT_V(n) asm volatile("s_waitcnt vmcnt(" #n ")" ::: "memory")
; #define PG8_WAIT_L(n) asm volatile("s_waitcnt lgkmcnt(" #n ")" ::: "memory")
; #define PG8_BAR __builtin_amdgcn_s_barrier()
; #define PG8_SCHED __builtin_amdgcn_sched_barrier(0)
; template <class Epi, class Sched, bool ALIGN_EPI = false, bool SP2 = false>
; __device__ __forceinline__ void gemm_phase(PG8_LAS unsigned char* lds, const Gemm g, const Sched& S, const Epi& E) {
;     ...
;             PG8_WAIT_V(8); PG8_WAIT_L(0); PG8_BAR; PG8_MMA(1, 0, At, B0); PG8_MMA(1, 1, At, B1); PG8_BAR; PG8_SCHED;
;             PG8_LDB(B0, 1, 0); PG8_LDB(B1, 1, 1); PG8_SCHED; PG8_LDA(At, 1, 0); PG8_STAGE(PG8_SA(0, 1), a2 + hstep, voffA);
;             PG8_WAIT_V(8); PG8_WAIT_L(0); PG8_BAR; PG8_MMA(0, 0, At, B0); PG8_MMA(0, 1, At, B1); PG8_BAR; PG8_SCHED;
	s_setprio 1
	v_mfma_f32_16x16x32_bf16 v[60:63], v[146:149], v[178:181], v[60:63]
	v_mfma_f32_16x16x32_bf16 v[56:59], v[154:157], v[178:181], v[56:59]
	v_mfma_f32_16x16x32_bf16 v[44:47], v[146:149], v[200:203], v[44:47]
	v_mfma_f32_16x16x32_bf16 v[40:43], v[154:157], v[200:203], v[40:43]
	v_mfma_f32_16x16x32_bf16 v[28:31], v[146:149], v[208:211], v[28:31]
	v_mfma_f32_16x16x32_bf16 v[24:27], v[154:157], v[208:211], v[24:27]
	v_mfma_f32_16x16x32_bf16 v[12:15], v[146:149], v[228:231], v[12:15]
	v_mfma_f32_16x16x32_bf16 v[8:11], v[154:157], v[228:231], v[8:11]
	v_mfma_f32_16x16x32_bf16 v[60:63], v[150:153], v[184:187], v[60:63]
	v_mfma_f32_16x16x32_bf16 v[56:59], v[158:161], v[184:187], v[56:59]
	v_mfma_f32_16x16x32_bf16 v[44:47], v[150:153], v[204:207], v[44:47]
	v_mfma_f32_16x16x32_bf16 v[40:43], v[158:161], v[204:207], v[40:43]
	v_mfma_f32_16x16x32_bf16 v[28:31], v[150:153], v[224:227], v[28:31]
	v_mfma_f32_16x16x32_bf16 v[24:27], v[158:161], v[224:227], v[24:27]
	v_mfma_f32_16x16x32_bf16 v[12:15], v[150:153], v[232:235], v[12:15]
	v_mfma_f32_16x16x32_bf16 v[8:11], v[158:161], v[232:235], v[8:11]
	s_setprio 0
	s_setprio 1
	v_mfma_f32_16x16x32_bf16 v[52:55], v[162:165], v[178:181], v[52:55]
	v_mfma_f32_16x16x32_bf16 v[48:51], v[170:173], v[178:181], v[48:51]
	v_mfma_f32_16x16x32_bf16 v[36:39], v[162:165], v[200:203], v[36:39]
	v_mfma_f32_16x16x32_bf16 v[32:35], v[170:173], v[200:203], v[32:35]
	v_mfma_f32_16x16x32_bf16 v[20:23], v[162:165], v[208:211], v[20:23]
	v_mfma_f32_16x16x32_bf16 v[16:19], v[170:173], v[208:211], v[16:19]
	v_mfma_f32_16x16x32_bf16 v[4:7], v[162:165], v[228:231], v[4:7]
	v_mfma_f32_16x16x32_bf16 v[0:3], v[170:173], v[228:231], v[0:3]
	v_mfma_f32_16x16x32_bf16 v[52:55], v[166:169], v[184:187], v[52:55]
	v_mfma_f32_16x16x32_bf16 v[48:51], v[174:177], v[184:187], v[48:51]
	v_mfma_f32_16x16x32_bf16 v[36:39], v[166:169], v[204:207], v[36:39]
	v_mfma_f32_16x16x32_bf16 v[32:35], v[174:177], v[204:207], v[32:35]
	v_mfma_f32_16x16x32_bf16 v[20:23], v[166:169], v[224:227], v[20:23]
	v_mfma_f32_16x16x32_bf16 v[16:19], v[174:177], v[224:227], v[16:19]
	v_mfma_f32_16x16x32_bf16 v[4:7], v[166:169], v[232:235], v[4:7]
	v_mfma_f32_16x16x32_bf16 v[0:3], v[174:177], v[232:235], v[0:3]
	s_setprio 0
	s_barrier
	s_add_i32 s61, 0, 0x18000
	s_add_i32 s62, 0, 0x1c000
	v_add_u32_e32 v158, s61, v143
	v_add_u32_e32 v174, s62, v143
	ds_read_b128 v[146:149], v158
	ds_read_b128 v[150:153], v158 offset:1024
	ds_read_b128 v[154:157], v158 offset:2048
	ds_read_b128 v[158:161], v158 offset:3072
	ds_read_b128 v[162:165], v174
	ds_read_b128 v[166:169], v174 offset:1024
	ds_read_b128 v[170:173], v174 offset:2048
	ds_read_b128 v[174:177], v174 offset:3072
	s_add_u32 s56, s56, 0x40000
	s_addc_u32 s57, s57, 0
	s_mov_b32 m0, s23
	v_lshl_add_u64 v[240:241], s[56:57], 0, v[130:131]
	ds_read_b128 v[178:181], v145 offset:32768
	ds_read_b128 v[184:187], v145 offset:33792
	ds_read_b128 v[200:203], v145 offset:34816
	ds_read_b128 v[204:207], v145 offset:35840
	ds_read_b128 v[208:211], v145 offset:36864
	ds_read_b128 v[224:227], v145 offset:37888
	ds_read_b128 v[228:231], v145 offset:38912
	ds_read_b128 v[232:235], v145 offset:39936
	global_load_lds_dwordx4 v[240:241], off
	v_lshl_add_u64 v[240:241], s[56:57], 0, v[132:133]
	s_mov_b32 m0, s24
	s_nop 0
	global_load_lds_dwordx4 v[240:241], off
	s_waitcnt vmcnt(8)
	s_waitcnt lgkmcnt(0)
	s_barrier
	s_setprio 1
	v_mfma_f32_16x16x32_bf16 v[126:129], v[146:149], v[178:181], v[126:129]
	v_mfma_f32_16x16x32_bf16 v[122:125], v[154:157], v[178:181], v[122:125]
	v_mfma_f32_16x16x32_bf16 v[108:111], v[146:149], v[200:203], v[108:111]
	v_mfma_f32_16x16x32_bf16 v[104:107], v[154:157], v[200:203], v[104:107]
	v_mfma_f32_16x16x32_bf16 v[92:95], v[146:149], v[208:211], v[92:95]
	v_mfma_f32_16x16x32_bf16 v[88:91], v[154:157], v[208:211], v[88:91]
	v_mfma_f32_16x16x32_bf16 v[76:79], v[146:149], v[228:231], v[76:79]
	v_mfma_f32_16x16x32_bf16 v[72:75], v[154:157], v[228:231], v[72:75]
	v_mfma_f32_16x16x32_bf16 v[126:129], v[150:153], v[184:187], v[126:129]
	v_mfma_f32_16x16x32_bf16 v[122:125], v[158:161], v[184:187], v[122:125]
	v_mfma_f32_16x16x32_bf16 v[108:111], v[150:153], v[204:207], v[108:111]
	v_mfma_f32_16x16x32_bf16 v[104:107], v[158:161], v[204:207], v[104:107]
	v_mfma_f32_16x16x32_bf16 v[92:95], v[150:153], v[224:227], v[92:95]
	v_mfma_f32_16x16x32_bf16 v[88:91], v[158:161], v[224:227], v[88:91]
	v_mfma_f32_16x16x32_bf16 v[76:79], v[150:153], v[232:235], v[76:79]
	v_mfma_f32_16x16x32_bf16 v[72:75], v[158:161], v[232:235], v[72:75]
	s_setprio 0
	s_setprio 1
	v_mfma_f32_16x16x32_bf16 v[118:121], v[162:165], v[178:181], v[118:121]
	v_mfma_f32_16x16x32_bf16 v[114:117], v[170:173], v[178:181], v[114:117]
	v_mfma_f32_16x16x32_bf16 v[100:103], v[162:165], v[200:203], v[100:103]
	v_mfma_f32_16x16x32_bf16 v[96:99], v[170:173], v[200:203], v[96:99]
	v_mfma_f32_16x16x32_bf16 v[84:87], v[162:165], v[208:211], v[84:87]
	v_mfma_f32_16x16x32_bf16 v[80:83], v[170:173], v[208:211], v[80:83]
	v_mfma_f32_16x16x32_bf16 v[68:71], v[162:165], v[228:231], v[68:71]
	v_mfma_f32_16x16x32_bf16 v[64:67], v[170:173], v[228:231], v[64:67]
	v_mfma_f32_16x16x32_bf16 v[118:121], v[166:169], v[184:187], v[118:121]
	v_mfma_f32_16x16x32_bf16 v[114:117], v[174:177], v[184:187], v[114:117]
	v_mfma_f32_16x16x32_bf16 v[100:103], v[166:169], v[204:207], v[100:103]
	v_mfma_f32_16x16x32_bf16 v[96:99], v[174:177], v[204:207], v[96:99]
	v_mfma_f32_16x16x32_bf16 v[84:87], v[166:169], v[224:227], v[84:87]
	v_mfma_f32_16x16x32_bf16 v[80:83], v[174:177], v[224:227], v[80:83]
	v_mfma_f32_16x16x32_bf16 v[68:71], v[166:169], v[232:235], v[68:71]
	v_mfma_f32_16x16x32_bf16 v[64:67], v[174:177], v[232:235], v[64:67]
	s_setprio 0
	s_barrier
; #define PG8_STAGE(bufoff, gbase, voff) do { _Pragma("unroll") for (int _i = 0; _i < 2; ++_i) \
;         __builtin_amdgcn_global_load_lds((const unsigned*)((const char*)(gbase) + (voff)[_i]), (PG8_LAS unsigned*)(lds + (bufoff) + ldsw + _i * 8192), 16, 0, 0); } while (0)
; #define PG8_LDA(dst, b, h) do { _Pragma("unroll") for (int m = 0; m < 4; ++m) _Pragma("unroll") for (int k = 0; k < 2; ++k) dst[m][k] = *(const PG8_LAS bf16x8*)(lds + PG8_SA(b, h) + aoff + m * 2048 + k * 1024); } while (0)
; #define PG8_MMA(ai, bj, At, Bt) do { __builtin_amdgcn_s_setprio(1); _Pragma("unroll") for (int m = 0; m < 4; ++m) _Pragma("unroll") for (int n = 0; n < 2; ++n) _Pragma("unroll") for (int k = 0; k < 2; ++k) \
;         acc[ai][bj][m][n] = __builtin_amdgcn_mfma_f32_16x16x32_bf16(Bt[n][k], At[m][k], acc[ai][bj][m][n], 0, 0, 0); __builtin_amdgcn_s_setprio(0); } while (0)
; #define PG8_WAIT_V(n) asm volatile("s_waitcnt vmcnt(" #n ")" ::: "memory")
; #define PG8_WAIT_L(n) asm volatile("s_waitcnt lgkmcnt(" #n ")" ::: "memory")
; #define PG8_BAR __builtin_amdgcn_s_barrier()
; #define PG8_SCHED __builtin_amdgcn_sched_barrier(0)
; template <class Epi, class Sched, bool ALIGN_EPI = false, bool SP2 = false>
; __device__ __forceinline__ void gemm_phase(PG8_LAS unsigned char* lds, const Gemm g, const Sched& S, const Epi& E) {
;     ...
;             PG8_LDA(At, 1, 1); PG8_STAGE(PG8_SB(1, 0), b3, voffB); PG8_STAGE(PG8_SB(1, 1), b3 + hstep, voffB); PG8_STAGE(PG8_SA(1, 0), a3, voffA);
;             PG8_WAIT_V(8); PG8_WAIT_L(0); PG8_BAR; PG8_MMA(1, 0, At, B0); PG8_MMA(1, 1, At, B1); PG8_BAR; PG8_SCHED;
;     ...
;         if constexpr (ALIGN_EPI) { if (wr == 0) PG8_BAR; }
	s_add_i32 s56, s61, s20
	v_lshl_add_u64 v[140:141], v[140:141], 0, s[36:37]
	s_mov_b32 m0, s56
	ds_read_b128 v[178:181], v145 offset:49152
	ds_read_b128 v[184:187], v145 offset:50176
	ds_read_b128 v[200:203], v145 offset:51200
	ds_read_b128 v[204:207], v145 offset:52224
	ds_read_b128 v[208:211], v145 offset:53248
	ds_read_b128 v[224:227], v145 offset:54272
	ds_read_b128 v[228:231], v145 offset:55296
	ds_read_b128 v[232:235], v145 offset:56320
	global_load_lds_dwordx4 v[140:141], off
	s_add_i32 m0, s56, 0x2000
	s_add_u32 s40, s40, 0x40080
	v_lshl_add_u64 v[140:141], v[212:213], 0, s[36:37]
	s_addc_u32 s41, s41, 0
	s_add_i32 s56, s62, s20
	global_load_lds_dwordx4 v[140:141], off
	v_lshl_add_u64 v[140:141], s[40:41], 0, v[112:113]
	s_mov_b32 m0, s56
	s_nop 0
	global_load_lds_dwordx4 v[140:141], off
	v_lshl_add_u64 v[140:141], s[40:41], 0, v[134:135]
	s_add_i32 m0, s56, 0x2000
	s_nop 0
	global_load_lds_dwordx4 v[140:141], off
	v_lshl_add_u64 v[140:141], v[236:237], 0, s[36:37]
	s_mov_b32 m0, s26
	s_nop 0
	global_load_lds_dwordx4 v[140:141], off
	v_lshl_add_u64 v[140:141], v[238:239], 0, s[36:37]
	s_mov_b32 m0, s33
	s_nop 0
	global_load_lds_dwordx4 v[140:141], off
	s_waitcnt vmcnt(8)
	s_waitcnt lgkmcnt(0)
	s_barrier
	s_setprio 1
	v_mfma_f32_16x16x32_bf16 v[60:63], v[146:149], v[178:181], v[60:63]
	v_mfma_f32_16x16x32_bf16 v[56:59], v[154:157], v[178:181], v[56:59]
	v_mfma_f32_16x16x32_bf16 v[44:47], v[146:149], v[200:203], v[44:47]
	v_mfma_f32_16x16x32_bf16 v[40:43], v[154:157], v[200:203], v[40:43]
	v_mfma_f32_16x16x32_bf16 v[28:31], v[146:149], v[208:211], v[28:31]
	v_mfma_f32_16x16x32_bf16 v[24:27], v[154:157], v[208:211], v[24:27]
	v_mfma_f32_16x16x32_bf16 v[12:15], v[146:149], v[228:231], v[12:15]
	v_mfma_f32_16x16x32_bf16 v[8:11], v[154:157], v[228:231], v[8:11]
	v_mfma_f32_16x16x32_bf16 v[60:63], v[150:153], v[184:187], v[60:63]
	v_mfma_f32_16x16x32_bf16 v[56:59], v[158:161], v[184:187], v[56:59]
	v_mfma_f32_16x16x32_bf16 v[44:47], v[150:153], v[204:207], v[44:47]
	v_mfma_f32_16x16x32_bf16 v[40:43], v[158:161], v[204:207], v[40:43]
	v_mfma_f32_16x16x32_bf16 v[28:31], v[150:153], v[224:227], v[28:31]
	v_mfma_f32_16x16x32_bf16 v[24:27], v[158:161], v[224:227], v[24:27]
	v_mfma_f32_16x16x32_bf16 v[12:15], v[150:153], v[232:235], v[12:15]
	v_mfma_f32_16x16x32_bf16 v[8:11], v[158:161], v[232:235], v[8:11]
	s_setprio 0
	s_setprio 1
	v_mfma_f32_16x16x32_bf16 v[52:55], v[162:165], v[178:181], v[52:55]
	v_mfma_f32_16x16x32_bf16 v[48:51], v[170:173], v[178:181], v[48:51]
	v_mfma_f32_16x16x32_bf16 v[36:39], v[162:165], v[200:203], v[36:39]
	v_mfma_f32_16x16x32_bf16 v[32:35], v[170:173], v[200:203], v[32:35]
	v_mfma_f32_16x16x32_bf16 v[20:23], v[162:165], v[208:211], v[20:23]
	v_mfma_f32_16x16x32_bf16 v[16:19], v[170:173], v[208:211], v[16:19]
	v_mfma_f32_16x16x32_bf16 v[4:7], v[162:165], v[228:231], v[4:7]
	v_mfma_f32_16x16x32_bf16 v[0:3], v[170:173], v[228:231], v[0:3]
	v_mfma_f32_16x16x32_bf16 v[52:55], v[166:169], v[184:187], v[52:55]
	v_mfma_f32_16x16x32_bf16 v[48:51], v[174:177], v[184:187], v[48:51]
	v_mfma_f32_16x16x32_bf16 v[36:39], v[166:169], v[204:207], v[36:39]
	v_mfma_f32_16x16x32_bf16 v[32:35], v[174:177], v[204:207], v[32:35]
	v_mfma_f32_16x16x32_bf16 v[20:23], v[166:169], v[224:227], v[20:23]
	v_mfma_f32_16x16x32_bf16 v[16:19], v[174:177], v[224:227], v[16:19]
	v_mfma_f32_16x16x32_bf16 v[4:7], v[166:169], v[232:235], v[4:7]
	v_mfma_f32_16x16x32_bf16 v[0:3], v[174:177], v[232:235], v[0:3]
	s_setprio 0
	s_barrier
	s_add_i32 s60, s60, 2
	s_add_u32 s54, s54, 0x100
	s_addc_u32 s55, s55, 0
	s_add_u32 s53, s53, 0x100
	s_addc_u32 s58, s58, 0
	s_cmp_gt_u32 s60, 13
	s_cbranch_scc0 .LBB0_643
	s_and_b64 vcc, exec, s[38:39]
	s_cbranch_vccz .LBB0_646
	s_barrier

; #define PG8_STAGE(bufoff, gbase, voff) do { _Pragma("unroll") for (int _i = 0; _i < 2; ++_i) \
;         __builtin_amdgcn_global_load_lds((const unsigned*)((const char*)(gbase) + (voff)[_i]), (PG8_LAS unsigned*)(lds + (bufoff) + ldsw + _i * 8192), 16, 0, 0); } while (0)
; #define PG8_LDA(dst, b, h) do { _Pragma("unroll") for (int m = 0; m < 4; ++m) _Pragma("unroll") for (int k = 0; k < 2; ++k) dst[m][k] = *(const PG8_LAS bf16x8*)(lds + PG8_SA(b, h) + aoff + m * 2048 + k * 1024); } while (0)
; #define PG8_LDB(dst, b, h) do { _Pragma("unroll") for (int n = 0; n < 2; ++n) _Pragma("unroll") for (int k = 0; k < 2; ++k) dst[n][k] = *(const PG8_LAS bf16x8*)(lds + PG8_SB(b, h) + boff + n * 2048 + k * 1024); } while (0)
; #define PG8_MMA(ai, bj, At, Bt) do { __builtin_amdgcn_s_setprio(1); _Pragma("unroll") for (int m = 0; m < 4; ++m) _Pragma("unroll") for (int n = 0; n < 2; ++n) _Pragma("unroll") for (int k = 0; k < 2; ++k) \
;         acc[ai][bj][m][n] = __builtin_amdgcn_mfma_f32_16x16x32_bf16(Bt[n][k], At[m][k], acc[ai][bj][m][n], 0, 0, 0); __builtin_amdgcn_s_setprio(0); } while (0)
; #define PG8_WAIT_V(n) asm volatile("s_waitcnt vmcnt(" #n ")" ::: "memory")
; #define PG8_WAIT_L(n) asm volatile("s_waitcnt lgkmcnt(" #n ")" ::: "memory")
; template <class Epi, class Sched, bool ALIGN_EPI = false, bool SP2 = false>
; __device__ __forceinline__ void gemm_phase(PG8_LAS unsigned char* lds, const Gemm g, const Sched& S, const Epi& E) {
;     ...
;             const bool last = (t == nt - 2);
;             const char* a1 = cA + (size_t)(t + 1) * kstep;
;             const char* a2 = last ? nA : cA + (size_t)(t + 2) * kstep; const char* b2 = last ? nB : cB + (size_t)(t + 2) * kstep;
;             const char* a3 = a2 + kstep; const char* b3 = b2 + kstep;
;             if (last && has_next) S.a_ready(nxt);
;             if constexpr (SP2) {
;             PG8_LDB(B0, 0, 0); PG8_LDB(B1, 0, 1); PG8_SCHED; PG8_LDA(At, 0, 0); PG8_STAGE(PG8_SA(1, 1), a1 + hstep, voffA);
;             PG8_WAIT_V(8); PG8_WAIT_L(0); PG8_BAR; PG8_MMA(0, 0, At, B0); PG8_MMA(0, 1, At, B1); PG8_BAR; PG8_SCHED;
;             PG8_LDA(At, 0, 1); PG8_STAGE(PG8_SB(0, 0), b2, voffB); PG8_STAGE(PG8_SB(0, 1), b2 + hstep, voffB); PG8_STAGE(PG8_SA(0, 0), a2, voffA);
;             PG8_WAIT_V(8); PG8_WAIT_L(0); PG8_BAR; PG8_MMA(1, 0, At, B0); PG8_MMA(1, 1, At, B1); PG8_BAR; PG8_SCHED;
.LBB0_718:
	s_add_u32 vcc_lo, s54, 0x100
	s_addc_u32 vcc_hi, s55, 0
	s_add_i32 s66, 0, 0x10000
	s_cmp_eq_u32 s60, 60
	s_cselect_b32 s13, s1, vcc_hi
	s_cselect_b32 s12, s51, vcc_lo
	s_cselect_b32 s63, s49, s65
	s_cselect_b32 s62, s58, s61
	s_add_i32 s67, 0, 0x14000
	v_add_u32_e32 v148, s66, v179
	v_add_u32_e32 v164, s67, v179
	ds_read_b128 v[136:139], v148
	ds_read_b128 v[140:143], v148 offset:1024
	ds_read_b128 v[144:147], v148 offset:2048
	ds_read_b128 v[148:151], v148 offset:3072
	ds_read_b128 v[152:155], v164
	ds_read_b128 v[156:159], v164 offset:1024
	ds_read_b128 v[160:163], v164 offset:2048
	ds_read_b128 v[164:167], v164 offset:3072
	v_lshl_add_u64 v[176:177], s[54:55], 0, v[132:133]
	s_add_i32 m0, s20, 0xc000
	ds_read_b128 v[168:171], v181
	ds_read_b128 v[172:175], v181 offset:1024
	ds_read_b128 v[184:187], v181 offset:2048
	ds_read_b128 v[200:203], v181 offset:3072
	ds_read_b128 v[204:207], v181 offset:4096
	ds_read_b128 v[208:211], v181 offset:5120
	ds_read_b128 v[224:227], v181 offset:6144
	ds_read_b128 v[228:231], v181 offset:7168
	global_load_lds_dwordx4 v[176:177], off
	v_lshl_add_u64 v[176:177], s[54:55], 0, v[134:135]
	s_add_i32 m0, s20, 0xe000
	s_nop 0
	global_load_lds_dwordx4 v[176:177], off
	s_waitcnt vmcnt(8)
	s_waitcnt lgkmcnt(0)
	s_barrier
	s_setprio 1
	v_mfma_f32_16x16x32_bf16 v[126:129], v[136:139], v[168:171], v[126:129]
	v_mfma_f32_16x16x32_bf16 v[122:125], v[144:147], v[168:171], v[122:125]
	v_mfma_f32_16x16x32_bf16 v[108:111], v[136:139], v[184:187], v[108:111]
	v_mfma_f32_16x16x32_bf16 v[104:107], v[144:147], v[184:187], v[104:107]
	v_mfma_f32_16x16x32_bf16 v[92:95], v[136:139], v[204:207], v[92:95]
	v_mfma_f32_16x16x32_bf16 v[88:91], v[144:147], v[204:207], v[88:91]
	v_mfma_f32_16x16x32_bf16 v[76:79], v[136:139], v[224:227], v[76:79]
	v_mfma_f32_16x16x32_bf16 v[72:75], v[144:147], v[224:227], v[72:75]
	v_mfma_f32_16x16x32_bf16 v[126:129], v[140:143], v[172:175], v[126:129]
	v_mfma_f32_16x16x32_bf16 v[122:125], v[148:151], v[172:175], v[122:125]
	v_mfma_f32_16x16x32_bf16 v[108:111], v[140:143], v[200:203], v[108:111]
	v_mfma_f32_16x16x32_bf16 v[104:107], v[148:151], v[200:203], v[104:107]
	v_mfma_f32_16x16x32_bf16 v[92:95], v[140:143], v[208:211], v[92:95]
	v_mfma_f32_16x16x32_bf16 v[88:91], v[148:151], v[208:211], v[88:91]
	v_mfma_f32_16x16x32_bf16 v[76:79], v[140:143], v[228:231], v[76:79]
	v_mfma_f32_16x16x32_bf16 v[72:75], v[148:151], v[228:231], v[72:75]
	s_setprio 0
	s_setprio 1
	v_mfma_f32_16x16x32_bf16 v[118:121], v[152:155], v[168:171], v[118:121]
	v_mfma_f32_16x16x32_bf16 v[114:117], v[160:163], v[168:171], v[114:117]
	v_mfma_f32_16x16x32_bf16 v[100:103], v[152:155], v[184:187], v[100:103]
	v_mfma_f32_16x16x32_bf16 v[96:99], v[160:163], v[184:187], v[96:99]
	v_mfma_f32_16x16x32_bf16 v[84:87], v[152:155], v[204:207], v[84:87]
	v_mfma_f32_16x16x32_bf16 v[80:83], v[160:163], v[204:207], v[80:83]
	v_mfma_f32_16x16x32_bf16 v[68:71], v[152:155], v[224:227], v[68:71]
	v_mfma_f32_16x16x32_bf16 v[64:67], v[160:163], v[224:227], v[64:67]
	v_mfma_f32_16x16x32_bf16 v[118:121], v[156:159], v[172:175], v[118:121]
	v_mfma_f32_16x16x32_bf16 v[114:117], v[164:167], v[172:175], v[114:117]
	v_mfma_f32_16x16x32_bf16 v[100:103], v[156:159], v[200:203], v[100:103]
	v_mfma_f32_16x16x32_bf16 v[96:99], v[164:167], v[200:203], v[96:99]
	v_mfma_f32_16x16x32_bf16 v[84:87], v[156:159], v[208:211], v[84:87]
	v_mfma_f32_16x16x32_bf16 v[80:83], v[164:167], v[208:211], v[80:83]
	v_mfma_f32_16x16x32_bf16 v[68:71], v[156:159], v[228:231], v[68:71]
	v_mfma_f32_16x16x32_bf16 v[64:67], v[164:167], v[228:231], v[64:67]
	s_setprio 0
	s_barrier
	s_add_i32 s54, s66, s19
	v_lshl_add_u64 v[176:177], s[62:63], 0, v[112:113]
	s_mov_b32 m0, s54
	ds_read_b128 v[168:171], v181 offset:16384
	ds_read_b128 v[172:175], v181 offset:17408
	ds_read_b128 v[184:187], v181 offset:18432
	ds_read_b128 v[200:203], v181 offset:19456
	ds_read_b128 v[204:207], v181 offset:20480
	ds_read_b128 v[208:211], v181 offset:21504
	ds_read_b128 v[224:227], v181 offset:22528
	ds_read_b128 v[228:231], v181 offset:23552
	global_load_lds_dwordx4 v[176:177], off
	s_add_i32 m0, s54, 0x2000
	s_add_u32 s54, s62, 0x100000
	v_lshl_add_u64 v[212:213], s[62:63], 0, v[130:131]
	s_addc_u32 s55, s63, 0
	s_add_i32 s66, s67, s19
	global_load_lds_dwordx4 v[212:213], off
	v_lshl_add_u64 v[232:233], s[54:55], 0, v[112:113]
	s_mov_b32 m0, s66
	v_lshl_add_u64 v[234:235], s[12:13], 0, v[130:131]
	global_load_lds_dwordx4 v[232:233], off
	v_lshl_add_u64 v[232:233], s[54:55], 0, v[130:131]
	s_add_i32 m0, s66, 0x2000
	s_nop 0
	global_load_lds_dwordx4 v[232:233], off
	v_lshl_add_u64 v[232:233], s[12:13], 0, v[112:113]
	s_mov_b32 m0, s20
	s_nop 0
	global_load_lds_dwordx4 v[232:233], off
	s_mov_b32 m0, s21
	s_nop 0
	global_load_lds_dwordx4 v[234:235], off
	s_waitcnt vmcnt(8)
	s_waitcnt lgkmcnt(0)
	s_barrier
; #define PG8_STAGE(bufoff, gbase, voff) do { _Pragma("unroll") for (int _i = 0; _i < 2; ++_i) \
;         __builtin_amdgcn_global_load_lds((const unsigned*)((const char*)(gbase) + (voff)[_i]), (PG8_LAS unsigned*)(lds + (bufoff) + ldsw + _i * 8192), 16, 0, 0); } while (0)
; #define PG8_LDA(dst, b, h) do { _Pragma("unroll") for (int m = 0; m < 4; ++m) _Pragma("unroll") for (int k = 0; k < 2; ++k) dst[m][k] = *(const PG8_LAS bf16x8*)(lds + PG8_SA(b, h) + aoff + m * 2048 + k * 1024); } while (0)
; #define PG8_LDB(dst, b, h) do { _Pragma("unroll") for (int n = 0; n < 2; ++n) _Pragma("unroll") for (int k = 0; k < 2; ++k) dst[n][k] = *(const PG8_LAS bf16x8*)(lds + PG8_SB(b, h) + boff + n * 2048 + k * 1024); } while (0)
; #define PG8_MMA(ai, bj, At, Bt) do { __builtin_amdgcn_s_setprio(1); _Pragma("unroll") for (int m = 0; m < 4; ++m) _Pragma("unroll") for (int n = 0; n < 2; ++n) _Pragma("unroll") for (int k = 0; k < 2; ++k) \
;         acc[ai][bj][m][n] = __builtin_amdgcn_mfma_f32_16x16x32_bf16(Bt[n][k], At[m][k], acc[ai][bj][m][n], 0, 0, 0); __builtin_amdgcn_s_setprio(0); } while (0)
; #define PG8_WAIT_V(n) asm volatile("s_waitcnt vmcnt(" #n ")" ::: "memory")
; #define PG8_WAIT_L(n) asm volatile("s_waitcnt lgkmcnt(" #n ")" ::: "memory")
; #define PG8_BAR __builtin_amdgcn_s_barrier()
; #define PG8_SCHED __builtin_amdgcn_sched_barrier(0)
; template <class Epi, class Sched, bool ALIGN_EPI = false, bool SP2 = false>
; __device__ __forceinline__ void gemm_phase(PG8_LAS unsigned char* lds, const Gemm g, const Sched& S, const Epi& E) {
;     ...
;             PG8_WAIT_V(8); PG8_WAIT_L(0); PG8_BAR; PG8_MMA(1, 0, At, B0); PG8_MMA(1, 1, At, B1); PG8_BAR; PG8_SCHED;
;             PG8_LDB(B0, 1, 0); PG8_LDB(B1, 1, 1); PG8_SCHED; PG8_LDA(At, 1, 0); PG8_STAGE(PG8_SA(0, 1), a2 + hstep, voffA);
;             PG8_WAIT_V(8); PG8_WAIT_L(0); PG8_BAR; PG8_MMA(0, 0, At, B0); PG8_MMA(0, 1, At, B1); PG8_BAR; PG8_SCHED;
	s_setprio 1
	v_mfma_f32_16x16x32_bf16 v[60:63], v[136:139], v[168:171], v[60:63]
	v_mfma_f32_16x16x32_bf16 v[56:59], v[144:147], v[168:171], v[56:59]
	v_mfma_f32_16x16x32_bf16 v[44:47], v[136:139], v[184:187], v[44:47]
	v_mfma_f32_16x16x32_bf16 v[40:43], v[144:147], v[184:187], v[40:43]
	v_mfma_f32_16x16x32_bf16 v[28:31], v[136:139], v[204:207], v[28:31]
	v_mfma_f32_16x16x32_bf16 v[24:27], v[144:147], v[204:207], v[24:27]
	v_mfma_f32_16x16x32_bf16 v[12:15], v[136:139], v[224:227], v[12:15]
	v_mfma_f32_16x16x32_bf16 v[8:11], v[144:147], v[224:227], v[8:11]
	v_mfma_f32_16x16x32_bf16 v[60:63], v[140:143], v[172:175], v[60:63]
	v_mfma_f32_16x16x32_bf16 v[56:59], v[148:151], v[172:175], v[56:59]
	v_mfma_f32_16x16x32_bf16 v[44:47], v[140:143], v[200:203], v[44:47]
	v_mfma_f32_16x16x32_bf16 v[40:43], v[148:151], v[200:203], v[40:43]
	v_mfma_f32_16x16x32_bf16 v[28:31], v[140:143], v[208:211], v[28:31]
	v_mfma_f32_16x16x32_bf16 v[24:27], v[148:151], v[208:211], v[24:27]
	v_mfma_f32_16x16x32_bf16 v[12:15], v[140:143], v[228:231], v[12:15]
	v_mfma_f32_16x16x32_bf16 v[8:11], v[148:151], v[228:231], v[8:11]
	s_setprio 0
	s_setprio 1
	v_mfma_f32_16x16x32_bf16 v[52:55], v[152:155], v[168:171], v[52:55]
	v_mfma_f32_16x16x32_bf16 v[48:51], v[160:163], v[168:171], v[48:51]
	v_mfma_f32_16x16x32_bf16 v[36:39], v[152:155], v[184:187], v[36:39]
	v_mfma_f32_16x16x32_bf16 v[32:35], v[160:163], v[184:187], v[32:35]
	v_mfma_f32_16x16x32_bf16 v[20:23], v[152:155], v[204:207], v[20:23]
	v_mfma_f32_16x16x32_bf16 v[16:19], v[160:163], v[204:207], v[16:19]
	v_mfma_f32_16x16x32_bf16 v[4:7], v[152:155], v[224:227], v[4:7]
	v_mfma_f32_16x16x32_bf16 v[0:3], v[160:163], v[224:227], v[0:3]
	v_mfma_f32_16x16x32_bf16 v[52:55], v[156:159], v[172:175], v[52:55]
	v_mfma_f32_16x16x32_bf16 v[48:51], v[164:167], v[172:175], v[48:51]
	v_mfma_f32_16x16x32_bf16 v[36:39], v[156:159], v[200:203], v[36:39]
	v_mfma_f32_16x16x32_bf16 v[32:35], v[164:167], v[200:203], v[32:35]
	v_mfma_f32_16x16x32_bf16 v[20:23], v[156:159], v[208:211], v[20:23]
	v_mfma_f32_16x16x32_bf16 v[16:19], v[164:167], v[208:211], v[16:19]
	v_mfma_f32_16x16x32_bf16 v[4:7], v[156:159], v[228:231], v[4:7]
	v_mfma_f32_16x16x32_bf16 v[0:3], v[164:167], v[228:231], v[0:3]
	s_setprio 0
	s_barrier
	s_add_i32 s54, 0, 0x18000
	s_add_i32 s55, 0, 0x1c000
	v_add_u32_e32 v148, s54, v179
	v_add_u32_e32 v164, s55, v179
	ds_read_b128 v[136:139], v148
	ds_read_b128 v[140:143], v148 offset:1024
	ds_read_b128 v[144:147], v148 offset:2048
	ds_read_b128 v[148:151], v148 offset:3072
	ds_read_b128 v[152:155], v164
	ds_read_b128 v[156:159], v164 offset:1024
	ds_read_b128 v[160:163], v164 offset:2048
	ds_read_b128 v[164:167], v164 offset:3072
	s_add_u32 s12, s12, 0x100000
	s_addc_u32 s13, s13, 0
	s_mov_b32 m0, s22
	v_lshl_add_u64 v[236:237], s[12:13], 0, v[112:113]
	ds_read_b128 v[168:171], v181 offset:32768
	ds_read_b128 v[172:175], v181 offset:33792
	ds_read_b128 v[184:187], v181 offset:34816
	ds_read_b128 v[200:203], v181 offset:35840
	ds_read_b128 v[204:207], v181 offset:36864
	ds_read_b128 v[208:211], v181 offset:37888
	ds_read_b128 v[224:227], v181 offset:38912
	ds_read_b128 v[228:231], v181 offset:39936
	global_load_lds_dwordx4 v[236:237], off
	v_lshl_add_u64 v[236:237], s[12:13], 0, v[130:131]
	s_mov_b32 m0, s23
	s_nop 0
	global_load_lds_dwordx4 v[236:237], off
	s_waitcnt vmcnt(8)
	s_waitcnt lgkmcnt(0)
	s_barrier
	s_setprio 1
	v_mfma_f32_16x16x32_bf16 v[126:129], v[136:139], v[168:171], v[126:129]
	v_mfma_f32_16x16x32_bf16 v[122:125], v[144:147], v[168:171], v[122:125]
	v_mfma_f32_16x16x32_bf16 v[108:111], v[136:139], v[184:187], v[108:111]
	v_mfma_f32_16x16x32_bf16 v[104:107], v[144:147], v[184:187], v[104:107]
	v_mfma_f32_16x16x32_bf16 v[92:95], v[136:139], v[204:207], v[92:95]
	v_mfma_f32_16x16x32_bf16 v[88:91], v[144:147], v[204:207], v[88:91]
	v_mfma_f32_16x16x32_bf16 v[76:79], v[136:139], v[224:227], v[76:79]
	v_mfma_f32_16x16x32_bf16 v[72:75], v[144:147], v[224:227], v[72:75]
	v_mfma_f32_16x16x32_bf16 v[126:129], v[140:143], v[172:175], v[126:129]
	v_mfma_f32_16x16x32_bf16 v[122:125], v[148:151], v[172:175], v[122:125]
	v_mfma_f32_16x16x32_bf16 v[108:111], v[140:143], v[200:203], v[108:111]
	v_mfma_f32_16x16x32_bf16 v[104:107], v[148:151], v[200:203], v[104:107]
	v_mfma_f32_16x16x32_bf16 v[92:95], v[140:143], v[208:211], v[92:95]
	v_mfma_f32_16x16x32_bf16 v[88:91], v[148:151], v[208:211], v[88:91]
	v_mfma_f32_16x16x32_bf16 v[76:79], v[140:143], v[228:231], v[76:79]
	v_mfma_f32_16x16x32_bf16 v[72:75], v[148:151], v[228:231], v[72:75]
	s_setprio 0
	s_setprio 1
	v_mfma_f32_16x16x32_bf16 v[118:121], v[152:155], v[168:171], v[118:121]
	v_mfma_f32_16x16x32_bf16 v[114:117], v[160:163], v[168:171], v[114:117]
	v_mfma_f32_16x16x32_bf16 v[100:103], v[152:155], v[184:187], v[100:103]
	v_mfma_f32_16x16x32_bf16 v[96:99], v[160:163], v[184:187], v[96:99]
	v_mfma_f32_16x16x32_bf16 v[84:87], v[152:155], v[204:207], v[84:87]
	v_mfma_f32_16x16x32_bf16 v[80:83], v[160:163], v[204:207], v[80:83]
	v_mfma_f32_16x16x32_bf16 v[68:71], v[152:155], v[224:227], v[68:71]
	v_mfma_f32_16x16x32_bf16 v[64:67], v[160:163], v[224:227], v[64:67]
	v_mfma_f32_16x16x32_bf16 v[118:121], v[156:159], v[172:175], v[118:121]
	v_mfma_f32_16x16x32_bf16 v[114:117], v[164:167], v[172:175], v[114:117]
	v_mfma_f32_16x16x32_bf16 v[100:103], v[156:159], v[200:203], v[100:103]
	v_mfma_f32_16x16x32_bf16 v[96:99], v[164:167], v[200:203], v[96:99]
	v_mfma_f32_16x16x32_bf16 v[84:87], v[156:159], v[208:211], v[84:87]
	v_mfma_f32_16x16x32_bf16 v[80:83], v[164:167], v[208:211], v[80:83]
	v_mfma_f32_16x16x32_bf16 v[68:71], v[156:159], v[228:231], v[68:71]
	v_mfma_f32_16x16x32_bf16 v[64:67], v[164:167], v[228:231], v[64:67]
	s_setprio 0
	s_barrier
; #define PG8_STAGE(bufoff, gbase, voff) do { _Pragma("unroll") for (int _i = 0; _i < 2; ++_i) \
;         __builtin_amdgcn_global_load_lds((const unsigned*)((const char*)(gbase) + (voff)[_i]), (PG8_LAS unsigned*)(lds + (bufoff) + ldsw + _i * 8192), 16, 0, 0); } while (0)
; #define PG8_LDA(dst, b, h) do { _Pragma("unroll") for (int m = 0; m < 4; ++m) _Pragma("unroll") for (int k = 0; k < 2; ++k) dst[m][k] = *(const PG8_LAS bf16x8*)(lds + PG8_SA(b, h) + aoff + m * 2048 + k * 1024); } while (0)
; #define PG8_MMA(ai, bj, At, Bt) do { __builtin_amdgcn_s_setprio(1); _Pragma("unroll") for (int m = 0; m < 4; ++m) _Pragma("unroll") for (int n = 0; n < 2; ++n) _Pragma("unroll") for (int k = 0; k < 2; ++k) \
;         acc[ai][bj][m][n] = __builtin_amdgcn_mfma_f32_16x16x32_bf16(Bt[n][k], At[m][k], acc[ai][bj][m][n], 0, 0, 0); __builtin_amdgcn_s_setprio(0); } while (0)
; #define PG8_WAIT_V(n) asm volatile("s_waitcnt vmcnt(" #n ")" ::: "memory")
; #define PG8_WAIT_L(n) asm volatile("s_waitcnt lgkmcnt(" #n ")" ::: "memory")
; #define PG8_BAR __builtin_amdgcn_s_barrier()
; #define PG8_SCHED __builtin_amdgcn_sched_barrier(0)
; template <class Epi, class Sched, bool ALIGN_EPI = false, bool SP2 = false>
; __device__ __forceinline__ void gemm_phase(PG8_LAS unsigned char* lds, const Gemm g, const Sched& S, const Epi& E) {
;     ...
;             PG8_LDA(At, 1, 1); PG8_STAGE(PG8_SB(1, 0), b3, voffB); PG8_STAGE(PG8_SB(1, 1), b3 + hstep, voffB); PG8_STAGE(PG8_SA(1, 0), a3, voffA);
;             PG8_WAIT_V(8); PG8_WAIT_L(0); PG8_BAR; PG8_MMA(1, 0, At, B0); PG8_MMA(1, 1, At, B1); PG8_BAR; PG8_SCHED;
;     ...
;         if constexpr (ALIGN_EPI) { if (wr == 0) PG8_BAR; }
	s_add_i32 s12, s54, s19
	v_lshl_add_u64 v[176:177], v[176:177], 0, s[36:37]
	s_mov_b32 m0, s12
	ds_read_b128 v[168:171], v181 offset:49152
	ds_read_b128 v[172:175], v181 offset:50176
	ds_read_b128 v[184:187], v181 offset:51200
	ds_read_b128 v[200:203], v181 offset:52224
	ds_read_b128 v[204:207], v181 offset:53248
	ds_read_b128 v[208:211], v181 offset:54272
	ds_read_b128 v[224:227], v181 offset:55296
	ds_read_b128 v[228:231], v181 offset:56320
	global_load_lds_dwordx4 v[176:177], off
	s_add_i32 m0, s12, 0x2000
	s_add_u32 s12, s62, 0x100080
	v_lshl_add_u64 v[176:177], v[212:213], 0, s[36:37]
	s_addc_u32 s13, s63, 0
	s_add_i32 s54, s55, s19
	global_load_lds_dwordx4 v[176:177], off
	v_lshl_add_u64 v[176:177], s[12:13], 0, v[112:113]
	s_mov_b32 m0, s54
	s_nop 0
	global_load_lds_dwordx4 v[176:177], off
	v_lshl_add_u64 v[176:177], s[12:13], 0, v[130:131]
	s_add_i32 m0, s54, 0x2000
	s_nop 0
	global_load_lds_dwordx4 v[176:177], off
	v_lshl_add_u64 v[176:177], v[232:233], 0, s[36:37]
	s_mov_b32 m0, s26
	s_nop 0
	global_load_lds_dwordx4 v[176:177], off
	v_lshl_add_u64 v[176:177], v[234:235], 0, s[36:37]
	s_mov_b32 m0, s33
	s_nop 0
	global_load_lds_dwordx4 v[176:177], off
	s_waitcnt vmcnt(8)
	s_waitcnt lgkmcnt(0)
	s_barrier
	s_setprio 1
	v_mfma_f32_16x16x32_bf16 v[60:63], v[136:139], v[168:171], v[60:63]
	v_mfma_f32_16x16x32_bf16 v[56:59], v[144:147], v[168:171], v[56:59]
	v_mfma_f32_16x16x32_bf16 v[44:47], v[136:139], v[184:187], v[44:47]
	v_mfma_f32_16x16x32_bf16 v[40:43], v[144:147], v[184:187], v[40:43]
	v_mfma_f32_16x16x32_bf16 v[28:31], v[136:139], v[204:207], v[28:31]
	v_mfma_f32_16x16x32_bf16 v[24:27], v[144:147], v[204:207], v[24:27]
	v_mfma_f32_16x16x32_bf16 v[12:15], v[136:139], v[224:227], v[12:15]
	v_mfma_f32_16x16x32_bf16 v[8:11], v[144:147], v[224:227], v[8:11]
	v_mfma_f32_16x16x32_bf16 v[60:63], v[140:143], v[172:175], v[60:63]
	v_mfma_f32_16x16x32_bf16 v[56:59], v[148:151], v[172:175], v[56:59]
	v_mfma_f32_16x16x32_bf16 v[44:47], v[140:143], v[200:203], v[44:47]
	v_mfma_f32_16x16x32_bf16 v[40:43], v[148:151], v[200:203], v[40:43]
	v_mfma_f32_16x16x32_bf16 v[28:31], v[140:143], v[208:211], v[28:31]
	v_mfma_f32_16x16x32_bf16 v[24:27], v[148:151], v[208:211], v[24:27]
	v_mfma_f32_16x16x32_bf16 v[12:15], v[140:143], v[228:231], v[12:15]
	v_mfma_f32_16x16x32_bf16 v[8:11], v[148:151], v[228:231], v[8:11]
	s_setprio 0
	s_setprio 1
	v_mfma_f32_16x16x32_bf16 v[52:55], v[152:155], v[168:171], v[52:55]
	v_mfma_f32_16x16x32_bf16 v[48:51], v[160:163], v[168:171], v[48:51]
	v_mfma_f32_16x16x32_bf16 v[36:39], v[152:155], v[184:187], v[36:39]
	v_mfma_f32_16x16x32_bf16 v[32:35], v[160:163], v[184:187], v[32:35]
	v_mfma_f32_16x16x32_bf16 v[20:23], v[152:155], v[204:207], v[20:23]
	v_mfma_f32_16x16x32_bf16 v[16:19], v[160:163], v[204:207], v[16:19]
	v_mfma_f32_16x16x32_bf16 v[4:7], v[152:155], v[224:227], v[4:7]
	v_mfma_f32_16x16x32_bf16 v[0:3], v[160:163], v[224:227], v[0:3]
	v_mfma_f32_16x16x32_bf16 v[52:55], v[156:159], v[172:175], v[52:55]
	v_mfma_f32_16x16x32_bf16 v[48:51], v[164:167], v[172:175], v[48:51]
	v_mfma_f32_16x16x32_bf16 v[36:39], v[156:159], v[200:203], v[36:39]
	v_mfma_f32_16x16x32_bf16 v[32:35], v[164:167], v[200:203], v[32:35]
	v_mfma_f32_16x16x32_bf16 v[20:23], v[156:159], v[208:211], v[20:23]
	v_mfma_f32_16x16x32_bf16 v[16:19], v[164:167], v[208:211], v[16:19]
	v_mfma_f32_16x16x32_bf16 v[4:7], v[156:159], v[228:231], v[4:7]
	v_mfma_f32_16x16x32_bf16 v[0:3], v[164:167], v[228:231], v[0:3]
	s_setprio 0
	s_barrier
	s_add_i32 s60, s60, 2
	s_add_u32 s61, s61, 0x100
	s_addc_u32 s65, s65, 0
	s_cmp_gt_u32 s60, 61
	s_mov_b64 s[54:55], vcc
	s_cbranch_scc0 .LBB0_718
	s_and_b64 vcc, exec, s[46:47]
	s_cbranch_vccz .LBB0_721
	s_barrier

; #define PG8_STAGE(bufoff, gbase, voff) do { _Pragma("unroll") for (int _i = 0; _i < 2; ++_i) \
;         __builtin_amdgcn_global_load_lds((const unsigned*)((const char*)(gbase) + (voff)[_i]), (PG8_LAS unsigned*)(lds + (bufoff) + ldsw + _i * 8192), 16, 0, 0); } while (0)
; #define PG8_LDA(dst, b, h) do { _Pragma("unroll") for (int m = 0; m < 4; ++m) _Pragma("unroll") for (int k = 0; k < 2; ++k) dst[m][k] = *(const PG8_LAS bf16x8*)(lds + PG8_SA(b, h) + aoff + m * 2048 + k * 1024); } while (0)
; #define PG8_LDB(dst, b, h) do { _Pragma("unroll") for (int n = 0; n < 2; ++n) _Pragma("unroll") for (int k = 0; k < 2; ++k) dst[n][k] = *(const PG8_LAS bf16x8*)(lds + PG8_SB(b, h) + boff + n * 2048 + k * 1024); } while (0)
; #define PG8_MMA(ai, bj, At, Bt) do { __builtin_amdgcn_s_setprio(1); _Pragma("unroll") for (int m = 0; m < 4; ++m) _Pragma("unroll") for (int n = 0; n < 2; ++n) _Pragma("unroll") for (int k = 0; k < 2; ++k) \
;         acc[ai][bj][m][n] = __builtin_amdgcn_mfma_f32_16x16x32_bf16(Bt[n][k], At[m][k], acc[ai][bj][m][n], 0, 0, 0); __builtin_amdgcn_s_setprio(0); } while (0)
; #define PG8_WAIT_V(n) asm volatile("s_waitcnt vmcnt(" #n ")" ::: "memory")
; #define PG8_WAIT_L(n) asm volatile("s_waitcnt lgkmcnt(" #n ")" ::: "memory")
; template <class Epi, class Sched, bool ALIGN_EPI = false, bool SP2 = false>
; __device__ __forceinline__ void gemm_phase(PG8_LAS unsigned char* lds, const Gemm g, const Sched& S, const Epi& E) {
;     ...
;             const bool last = (t == nt - 2);
;             const char* a1 = cA + (size_t)(t + 1) * kstep;
;             const char* a2 = last ? nA : cA + (size_t)(t + 2) * kstep; const char* b2 = last ? nB : cB + (size_t)(t + 2) * kstep;
;             const char* a3 = a2 + kstep; const char* b3 = b2 + kstep;
;             if (last && has_next) S.a_ready(nxt);
;             if constexpr (SP2) {
;             PG8_LDB(B0, 0, 0); PG8_LDB(B1, 0, 1); PG8_SCHED; PG8_LDA(At, 0, 0); PG8_STAGE(PG8_SA(1, 1), a1 + hstep, voffA);
;             PG8_WAIT_V(8); PG8_WAIT_L(0); PG8_BAR; PG8_MMA(0, 0, At, B0); PG8_MMA(0, 1, At, B1); PG8_BAR; PG8_SCHED;
;             PG8_LDA(At, 0, 1); PG8_STAGE(PG8_SB(0, 0), b2, voffB); PG8_STAGE(PG8_SB(0, 1), b2 + hstep, voffB); PG8_STAGE(PG8_SA(0, 0), a2, voffA);
;             PG8_WAIT_V(8); PG8_WAIT_L(0); PG8_BAR; PG8_MMA(1, 0, At, B0); PG8_MMA(1, 1, At, B1); PG8_BAR; PG8_SCHED;
.LBB0_760:
	s_add_u32 s12, s54, 0xfff00080
	s_addc_u32 s13, s55, -1
	s_add_i32 s61, 0, 0x10000
	s_cmp_eq_u32 s60, 60
	s_cselect_b32 s13, s47, s13
	s_cselect_b32 s12, s53, s12
	s_cselect_b32 s41, s43, s58
	s_cselect_b32 s40, s56, s57
	s_add_i32 s64, 0, 0x14000
	v_add_u32_e32 v152, s61, v141
	v_add_u32_e32 v168, s64, v141
	ds_read_b128 v[136:139], v152
	ds_read_b128 v[144:147], v152 offset:1024
	ds_read_b128 v[148:151], v152 offset:2048
	ds_read_b128 v[152:155], v152 offset:3072
	ds_read_b128 v[156:159], v168
	ds_read_b128 v[160:163], v168 offset:1024
	ds_read_b128 v[164:167], v168 offset:2048
	ds_read_b128 v[168:171], v168 offset:3072
	v_lshl_add_u64 v[180:181], s[54:55], 0, v[132:133]
	s_add_i32 m0, s21, 0xc000
	ds_read_b128 v[172:175], v143
	ds_read_b128 v[176:179], v143 offset:1024
	ds_read_b128 v[184:187], v143 offset:2048
	ds_read_b128 v[200:203], v143 offset:3072
	ds_read_b128 v[204:207], v143 offset:4096
	ds_read_b128 v[208:211], v143 offset:5120
	ds_read_b128 v[222:225], v143 offset:6144
	ds_read_b128 v[226:229], v143 offset:7168
	global_load_lds_dwordx4 v[180:181], off
	v_lshl_add_u64 v[180:181], s[54:55], 0, v[134:135]
	s_add_i32 m0, s21, 0xe000
	s_nop 0
	global_load_lds_dwordx4 v[180:181], off
	s_waitcnt vmcnt(8)
	s_waitcnt lgkmcnt(0)
	s_barrier
	s_setprio 1
	v_mfma_f32_16x16x32_bf16 v[126:129], v[136:139], v[172:175], v[126:129]
	v_mfma_f32_16x16x32_bf16 v[122:125], v[148:151], v[172:175], v[122:125]
	v_mfma_f32_16x16x32_bf16 v[114:117], v[136:139], v[184:187], v[114:117]
	v_mfma_f32_16x16x32_bf16 v[104:107], v[148:151], v[184:187], v[104:107]
	v_mfma_f32_16x16x32_bf16 v[96:99], v[136:139], v[204:207], v[96:99]
	v_mfma_f32_16x16x32_bf16 v[88:91], v[148:151], v[204:207], v[88:91]
	v_mfma_f32_16x16x32_bf16 v[80:83], v[136:139], v[222:225], v[80:83]
	v_mfma_f32_16x16x32_bf16 v[72:75], v[148:151], v[222:225], v[72:75]
	v_mfma_f32_16x16x32_bf16 v[126:129], v[144:147], v[176:179], v[126:129]
	v_mfma_f32_16x16x32_bf16 v[122:125], v[152:155], v[176:179], v[122:125]
	v_mfma_f32_16x16x32_bf16 v[114:117], v[144:147], v[200:203], v[114:117]
	v_mfma_f32_16x16x32_bf16 v[104:107], v[152:155], v[200:203], v[104:107]
	v_mfma_f32_16x16x32_bf16 v[96:99], v[144:147], v[208:211], v[96:99]
	v_mfma_f32_16x16x32_bf16 v[88:91], v[152:155], v[208:211], v[88:91]
	v_mfma_f32_16x16x32_bf16 v[80:83], v[144:147], v[226:229], v[80:83]
	v_mfma_f32_16x16x32_bf16 v[72:75], v[152:155], v[226:229], v[72:75]
	s_setprio 0
	s_setprio 1
	v_mfma_f32_16x16x32_bf16 v[118:121], v[156:159], v[172:175], v[118:121]
	v_mfma_f32_16x16x32_bf16 v[108:111], v[164:167], v[172:175], v[108:111]
	v_mfma_f32_16x16x32_bf16 v[100:103], v[156:159], v[184:187], v[100:103]
	v_mfma_f32_16x16x32_bf16 v[92:95], v[164:167], v[184:187], v[92:95]
	v_mfma_f32_16x16x32_bf16 v[84:87], v[156:159], v[204:207], v[84:87]
	v_mfma_f32_16x16x32_bf16 v[76:79], v[164:167], v[204:207], v[76:79]
	v_mfma_f32_16x16x32_bf16 v[68:71], v[156:159], v[222:225], v[68:71]
	v_mfma_f32_16x16x32_bf16 v[64:67], v[164:167], v[222:225], v[64:67]
	v_mfma_f32_16x16x32_bf16 v[118:121], v[160:163], v[176:179], v[118:121]
	v_mfma_f32_16x16x32_bf16 v[108:111], v[168:171], v[176:179], v[108:111]
	v_mfma_f32_16x16x32_bf16 v[100:103], v[160:163], v[200:203], v[100:103]
	v_mfma_f32_16x16x32_bf16 v[92:95], v[168:171], v[200:203], v[92:95]
	v_mfma_f32_16x16x32_bf16 v[84:87], v[160:163], v[208:211], v[84:87]
	v_mfma_f32_16x16x32_bf16 v[76:79], v[168:171], v[208:211], v[76:79]
	v_mfma_f32_16x16x32_bf16 v[68:71], v[160:163], v[226:229], v[68:71]
	v_mfma_f32_16x16x32_bf16 v[64:67], v[168:171], v[226:229], v[64:67]
	s_setprio 0
	s_barrier
	s_add_i32 s61, s61, s20
	v_lshl_add_u64 v[180:181], s[40:41], 0, v[112:113]
	s_mov_b32 m0, s61
	ds_read_b128 v[172:175], v143 offset:16384
	ds_read_b128 v[176:179], v143 offset:17408
	ds_read_b128 v[184:187], v143 offset:18432
	ds_read_b128 v[200:203], v143 offset:19456
	ds_read_b128 v[204:207], v143 offset:20480
	ds_read_b128 v[208:211], v143 offset:21504
	ds_read_b128 v[222:225], v143 offset:22528
	ds_read_b128 v[226:229], v143 offset:23552
	global_load_lds_dwordx4 v[180:181], off
	s_add_i32 m0, s61, 0x2000
	s_add_u32 s62, s40, 0x100000
	v_lshl_add_u64 v[212:213], s[40:41], 0, v[130:131]
	s_addc_u32 s63, s41, 0
	s_add_i32 s61, s64, s20
	global_load_lds_dwordx4 v[212:213], off
	v_lshl_add_u64 v[230:231], s[62:63], 0, v[112:113]
	s_mov_b32 m0, s61
	v_lshl_add_u64 v[232:233], s[12:13], 0, v[130:131]
	global_load_lds_dwordx4 v[230:231], off
	v_lshl_add_u64 v[230:231], s[62:63], 0, v[130:131]
	s_add_i32 m0, s61, 0x2000
	s_nop 0
	global_load_lds_dwordx4 v[230:231], off
	v_lshl_add_u64 v[230:231], s[12:13], 0, v[112:113]
	s_mov_b32 m0, s21
	s_nop 0
	global_load_lds_dwordx4 v[230:231], off
	s_mov_b32 m0, s22
	s_nop 0
	global_load_lds_dwordx4 v[232:233], off
	s_waitcnt vmcnt(8)
	s_waitcnt lgkmcnt(0)
	s_barrier
; #define PG8_STAGE(bufoff, gbase, voff) do { _Pragma("unroll") for (int _i = 0; _i < 2; ++_i) \
;         __builtin_amdgcn_global_load_lds((const unsigned*)((const char*)(gbase) + (voff)[_i]), (PG8_LAS unsigned*)(lds + (bufoff) + ldsw + _i * 8192), 16, 0, 0); } while (0)
; #define PG8_LDA(dst, b, h) do { _Pragma("unroll") for (int m = 0; m < 4; ++m) _Pragma("unroll") for (int k = 0; k < 2; ++k) dst[m][k] = *(const PG8_LAS bf16x8*)(lds + PG8_SA(b, h) + aoff + m * 2048 + k * 1024); } while (0)
; #define PG8_LDB(dst, b, h) do { _Pragma("unroll") for (int n = 0; n < 2; ++n) _Pragma("unroll") for (int k = 0; k < 2; ++k) dst[n][k] = *(const PG8_LAS bf16x8*)(lds + PG8_SB(b, h) + boff + n * 2048 + k * 1024); } while (0)
; #define PG8_MMA(ai, bj, At, Bt) do { __builtin_amdgcn_s_setprio(1); _Pragma("unroll") for (int m = 0; m < 4; ++m) _Pragma("unroll") for (int n = 0; n < 2; ++n) _Pragma("unroll") for (int k = 0; k < 2; ++k) \
;         acc[ai][bj][m][n] = __builtin_amdgcn_mfma_f32_16x16x32_bf16(Bt[n][k], At[m][k], acc[ai][bj][m][n], 0, 0, 0); __builtin_amdgcn_s_setprio(0); } while (0)
; #define PG8_WAIT_V(n) asm volatile("s_waitcnt vmcnt(" #n ")" ::: "memory")
; #define PG8_WAIT_L(n) asm volatile("s_waitcnt lgkmcnt(" #n ")" ::: "memory")
; #define PG8_BAR __builtin_amdgcn_s_barrier()
; #define PG8_SCHED __builtin_amdgcn_sched_barrier(0)
; template <class Epi, class Sched, bool ALIGN_EPI = false, bool SP2 = false>
; __device__ __forceinline__ void gemm_phase(PG8_LAS unsigned char* lds, const Gemm g, const Sched& S, const Epi& E) {
;     ...
;             PG8_WAIT_V(8); PG8_WAIT_L(0); PG8_BAR; PG8_MMA(1, 0, At, B0); PG8_MMA(1, 1, At, B1); PG8_BAR; PG8_SCHED;
;             PG8_LDB(B0, 1, 0); PG8_LDB(B1, 1, 1); PG8_SCHED; PG8_LDA(At, 1, 0); PG8_STAGE(PG8_SA(0, 1), a2 + hstep, voffA);
;             PG8_WAIT_V(8); PG8_WAIT_L(0); PG8_BAR; PG8_MMA(0, 0, At, B0); PG8_MMA(0, 1, At, B1); PG8_BAR; PG8_SCHED;
	s_setprio 1
	v_mfma_f32_16x16x32_bf16 v[60:63], v[136:139], v[172:175], v[60:63]
	v_mfma_f32_16x16x32_bf16 v[56:59], v[148:151], v[172:175], v[56:59]
	v_mfma_f32_16x16x32_bf16 v[48:51], v[136:139], v[184:187], v[48:51]
	v_mfma_f32_16x16x32_bf16 v[40:43], v[148:151], v[184:187], v[40:43]
	v_mfma_f32_16x16x32_bf16 v[32:35], v[136:139], v[204:207], v[32:35]
	v_mfma_f32_16x16x32_bf16 v[24:27], v[148:151], v[204:207], v[24:27]
	v_mfma_f32_16x16x32_bf16 v[16:19], v[136:139], v[222:225], v[16:19]
	v_mfma_f32_16x16x32_bf16 v[8:11], v[148:151], v[222:225], v[8:11]
	v_mfma_f32_16x16x32_bf16 v[60:63], v[144:147], v[176:179], v[60:63]
	v_mfma_f32_16x16x32_bf16 v[56:59], v[152:155], v[176:179], v[56:59]
	v_mfma_f32_16x16x32_bf16 v[48:51], v[144:147], v[200:203], v[48:51]
	v_mfma_f32_16x16x32_bf16 v[40:43], v[152:155], v[200:203], v[40:43]
	v_mfma_f32_16x16x32_bf16 v[32:35], v[144:147], v[208:211], v[32:35]
	v_mfma_f32_16x16x32_bf16 v[24:27], v[152:155], v[208:211], v[24:27]
	v_mfma_f32_16x16x32_bf16 v[16:19], v[144:147], v[226:229], v[16:19]
	v_mfma_f32_16x16x32_bf16 v[8:11], v[152:155], v[226:229], v[8:11]
	s_setprio 0
	s_setprio 1
	v_mfma_f32_16x16x32_bf16 v[52:55], v[156:159], v[172:175], v[52:55]
	v_mfma_f32_16x16x32_bf16 v[44:47], v[164:167], v[172:175], v[44:47]
	v_mfma_f32_16x16x32_bf16 v[36:39], v[156:159], v[184:187], v[36:39]
	v_mfma_f32_16x16x32_bf16 v[28:31], v[164:167], v[184:187], v[28:31]
	v_mfma_f32_16x16x32_bf16 v[20:23], v[156:159], v[204:207], v[20:23]
	v_mfma_f32_16x16x32_bf16 v[12:15], v[164:167], v[204:207], v[12:15]
	v_mfma_f32_16x16x32_bf16 v[4:7], v[156:159], v[222:225], v[4:7]
	v_mfma_f32_16x16x32_bf16 v[0:3], v[164:167], v[222:225], v[0:3]
	v_mfma_f32_16x16x32_bf16 v[52:55], v[160:163], v[176:179], v[52:55]
	v_mfma_f32_16x16x32_bf16 v[44:47], v[168:171], v[176:179], v[44:47]
	v_mfma_f32_16x16x32_bf16 v[36:39], v[160:163], v[200:203], v[36:39]
	v_mfma_f32_16x16x32_bf16 v[28:31], v[168:171], v[200:203], v[28:31]
	v_mfma_f32_16x16x32_bf16 v[20:23], v[160:163], v[208:211], v[20:23]
	v_mfma_f32_16x16x32_bf16 v[12:15], v[168:171], v[208:211], v[12:15]
	v_mfma_f32_16x16x32_bf16 v[4:7], v[160:163], v[226:229], v[4:7]
	v_mfma_f32_16x16x32_bf16 v[0:3], v[168:171], v[226:229], v[0:3]
	s_setprio 0
	s_barrier
	s_add_i32 s61, 0, 0x18000
	s_add_i32 s62, 0, 0x1c000
	v_add_u32_e32 v152, s61, v141
	v_add_u32_e32 v168, s62, v141
	ds_read_b128 v[136:139], v152
	ds_read_b128 v[144:147], v152 offset:1024
	ds_read_b128 v[148:151], v152 offset:2048
	ds_read_b128 v[152:155], v152 offset:3072
	ds_read_b128 v[156:159], v168
	ds_read_b128 v[160:163], v168 offset:1024
	ds_read_b128 v[164:167], v168 offset:2048
	ds_read_b128 v[168:171], v168 offset:3072
	s_add_u32 s12, s12, 0x100000
	s_addc_u32 s13, s13, 0
	s_mov_b32 m0, s23
	v_lshl_add_u64 v[234:235], s[12:13], 0, v[112:113]
	ds_read_b128 v[172:175], v143 offset:32768
	ds_read_b128 v[176:179], v143 offset:33792
	ds_read_b128 v[184:187], v143 offset:34816
	ds_read_b128 v[200:203], v143 offset:35840
	ds_read_b128 v[204:207], v143 offset:36864
	ds_read_b128 v[208:211], v143 offset:37888
	ds_read_b128 v[222:225], v143 offset:38912
	ds_read_b128 v[226:229], v143 offset:39936
	global_load_lds_dwordx4 v[234:235], off
	v_lshl_add_u64 v[234:235], s[12:13], 0, v[130:131]
	s_mov_b32 m0, s24
	s_nop 0
	global_load_lds_dwordx4 v[234:235], off
	s_waitcnt vmcnt(8)
	s_waitcnt lgkmcnt(0)
	s_barrier
	s_setprio 1
	v_mfma_f32_16x16x32_bf16 v[126:129], v[136:139], v[172:175], v[126:129]
	v_mfma_f32_16x16x32_bf16 v[122:125], v[148:151], v[172:175], v[122:125]
	v_mfma_f32_16x16x32_bf16 v[114:117], v[136:139], v[184:187], v[114:117]
	v_mfma_f32_16x16x32_bf16 v[104:107], v[148:151], v[184:187], v[104:107]
	v_mfma_f32_16x16x32_bf16 v[96:99], v[136:139], v[204:207], v[96:99]
	v_mfma_f32_16x16x32_bf16 v[88:91], v[148:151], v[204:207], v[88:91]
	v_mfma_f32_16x16x32_bf16 v[80:83], v[136:139], v[222:225], v[80:83]
	v_mfma_f32_16x16x32_bf16 v[72:75], v[148:151], v[222:225], v[72:75]
	v_mfma_f32_16x16x32_bf16 v[126:129], v[144:147], v[176:179], v[126:129]
	v_mfma_f32_16x16x32_bf16 v[122:125], v[152:155], v[176:179], v[122:125]
	v_mfma_f32_16x16x32_bf16 v[114:117], v[144:147], v[200:203], v[114:117]
	v_mfma_f32_16x16x32_bf16 v[104:107], v[152:155], v[200:203], v[104:107]
	v_mfma_f32_16x16x32_bf16 v[96:99], v[144:147], v[208:211], v[96:99]
	v_mfma_f32_16x16x32_bf16 v[88:91], v[152:155], v[208:211], v[88:91]
	v_mfma_f32_16x16x32_bf16 v[80:83], v[144:147], v[226:229], v[80:83]
	v_mfma_f32_16x16x32_bf16 v[72:75], v[152:155], v[226:229], v[72:75]
	s_setprio 0
	s_setprio 1
	v_mfma_f32_16x16x32_bf16 v[118:121], v[156:159], v[172:175], v[118:121]
	v_mfma_f32_16x16x32_bf16 v[108:111], v[164:167], v[172:175], v[108:111]
	v_mfma_f32_16x16x32_bf16 v[100:103], v[156:159], v[184:187], v[100:103]
	v_mfma_f32_16x16x32_bf16 v[92:95], v[164:167], v[184:187], v[92:95]
	v_mfma_f32_16x16x32_bf16 v[84:87], v[156:159], v[204:207], v[84:87]
	v_mfma_f32_16x16x32_bf16 v[76:79], v[164:167], v[204:207], v[76:79]
	v_mfma_f32_16x16x32_bf16 v[68:71], v[156:159], v[222:225], v[68:71]
	v_mfma_f32_16x16x32_bf16 v[64:67], v[164:167], v[222:225], v[64:67]
	v_mfma_f32_16x16x32_bf16 v[118:121], v[160:163], v[176:179], v[118:121]
	v_mfma_f32_16x16x32_bf16 v[108:111], v[168:171], v[176:179], v[108:111]
	v_mfma_f32_16x16x32_bf16 v[100:103], v[160:163], v[200:203], v[100:103]
	v_mfma_f32_16x16x32_bf16 v[92:95], v[168:171], v[200:203], v[92:95]
	v_mfma_f32_16x16x32_bf16 v[84:87], v[160:163], v[208:211], v[84:87]
	v_mfma_f32_16x16x32_bf16 v[76:79], v[168:171], v[208:211], v[76:79]
	v_mfma_f32_16x16x32_bf16 v[68:71], v[160:163], v[226:229], v[68:71]
	v_mfma_f32_16x16x32_bf16 v[64:67], v[168:171], v[226:229], v[64:67]
	s_setprio 0
	s_barrier
; #define PG8_STAGE(bufoff, gbase, voff) do { _Pragma("unroll") for (int _i = 0; _i < 2; ++_i) \
;         __builtin_amdgcn_global_load_lds((const unsigned*)((const char*)(gbase) + (voff)[_i]), (PG8_LAS unsigned*)(lds + (bufoff) + ldsw + _i * 8192), 16, 0, 0); } while (0)
; #define PG8_LDA(dst, b, h) do { _Pragma("unroll") for (int m = 0; m < 4; ++m) _Pragma("unroll") for (int k = 0; k < 2; ++k) dst[m][k] = *(const PG8_LAS bf16x8*)(lds + PG8_SA(b, h) + aoff + m * 2048 + k * 1024); } while (0)
; #define PG8_MMA(ai, bj, At, Bt) do { __builtin_amdgcn_s_setprio(1); _Pragma("unroll") for (int m = 0; m < 4; ++m) _Pragma("unroll") for (int n = 0; n < 2; ++n) _Pragma("unroll") for (int k = 0; k < 2; ++k) \
;         acc[ai][bj][m][n] = __builtin_amdgcn_mfma_f32_16x16x32_bf16(Bt[n][k], At[m][k], acc[ai][bj][m][n], 0, 0, 0); __builtin_amdgcn_s_setprio(0); } while (0)
; #define PG8_WAIT_V(n) asm volatile("s_waitcnt vmcnt(" #n ")" ::: "memory")
; #define PG8_WAIT_L(n) asm volatile("s_waitcnt lgkmcnt(" #n ")" ::: "memory")
; #define PG8_BAR __builtin_amdgcn_s_barrier()
; #define PG8_SCHED __builtin_amdgcn_sched_barrier(0)
; template <class Epi, class Sched, bool ALIGN_EPI = false, bool SP2 = false>
; __device__ __forceinline__ void gemm_phase(PG8_LAS unsigned char* lds, const Gemm g, const Sched& S, const Epi& E) {
;     ...
;             PG8_LDA(At, 1, 1); PG8_STAGE(PG8_SB(1, 0), b3, voffB); PG8_STAGE(PG8_SB(1, 1), b3 + hstep, voffB); PG8_STAGE(PG8_SA(1, 0), a3, voffA);
;             PG8_WAIT_V(8); PG8_WAIT_L(0); PG8_BAR; PG8_MMA(1, 0, At, B0); PG8_MMA(1, 1, At, B1); PG8_BAR; PG8_SCHED;
;     ...
;         if constexpr (ALIGN_EPI) { if (wr == 0) PG8_BAR; }
	s_add_i32 s12, s61, s20
	v_lshl_add_u64 v[180:181], v[180:181], 0, s[36:37]
	s_mov_b32 m0, s12
	ds_read_b128 v[172:175], v143 offset:49152
	ds_read_b128 v[176:179], v143 offset:50176
	ds_read_b128 v[184:187], v143 offset:51200
	ds_read_b128 v[200:203], v143 offset:52224
	ds_read_b128 v[204:207], v143 offset:53248
	ds_read_b128 v[208:211], v143 offset:54272
	ds_read_b128 v[222:225], v143 offset:55296
	ds_read_b128 v[226:229], v143 offset:56320
	global_load_lds_dwordx4 v[180:181], off
	s_add_i32 m0, s12, 0x2000
	s_add_u32 s12, s40, 0x100080
	v_lshl_add_u64 v[180:181], v[212:213], 0, s[36:37]
	s_addc_u32 s13, s41, 0
	s_add_i32 s40, s62, s20
	global_load_lds_dwordx4 v[180:181], off
	v_lshl_add_u64 v[180:181], s[12:13], 0, v[112:113]
	s_mov_b32 m0, s40
	s_nop 0
	global_load_lds_dwordx4 v[180:181], off
	v_lshl_add_u64 v[180:181], s[12:13], 0, v[130:131]
	s_add_i32 m0, s40, 0x2000
	s_nop 0
	global_load_lds_dwordx4 v[180:181], off
	v_lshl_add_u64 v[180:181], v[230:231], 0, s[36:37]
	s_mov_b32 m0, s26
	s_nop 0
	global_load_lds_dwordx4 v[180:181], off
	v_lshl_add_u64 v[180:181], v[232:233], 0, s[36:37]
	s_mov_b32 m0, s33
	s_nop 0
	global_load_lds_dwordx4 v[180:181], off
	s_waitcnt vmcnt(8)
	s_waitcnt lgkmcnt(0)
	s_barrier
	s_setprio 1
	v_mfma_f32_16x16x32_bf16 v[60:63], v[136:139], v[172:175], v[60:63]
	v_mfma_f32_16x16x32_bf16 v[56:59], v[148:151], v[172:175], v[56:59]
	v_mfma_f32_16x16x32_bf16 v[48:51], v[136:139], v[184:187], v[48:51]
	v_mfma_f32_16x16x32_bf16 v[40:43], v[148:151], v[184:187], v[40:43]
	v_mfma_f32_16x16x32_bf16 v[32:35], v[136:139], v[204:207], v[32:35]
	v_mfma_f32_16x16x32_bf16 v[24:27], v[148:151], v[204:207], v[24:27]
	v_mfma_f32_16x16x32_bf16 v[16:19], v[136:139], v[222:225], v[16:19]
	v_mfma_f32_16x16x32_bf16 v[8:11], v[148:151], v[222:225], v[8:11]
	v_mfma_f32_16x16x32_bf16 v[60:63], v[144:147], v[176:179], v[60:63]
	v_mfma_f32_16x16x32_bf16 v[56:59], v[152:155], v[176:179], v[56:59]
	v_mfma_f32_16x16x32_bf16 v[48:51], v[144:147], v[200:203], v[48:51]
	v_mfma_f32_16x16x32_bf16 v[40:43], v[152:155], v[200:203], v[40:43]
	v_mfma_f32_16x16x32_bf16 v[32:35], v[144:147], v[208:211], v[32:35]
	v_mfma_f32_16x16x32_bf16 v[24:27], v[152:155], v[208:211], v[24:27]
	v_mfma_f32_16x16x32_bf16 v[16:19], v[144:147], v[226:229], v[16:19]
	v_mfma_f32_16x16x32_bf16 v[8:11], v[152:155], v[226:229], v[8:11]
	s_setprio 0
	s_setprio 1
	v_mfma_f32_16x16x32_bf16 v[52:55], v[156:159], v[172:175], v[52:55]
	v_mfma_f32_16x16x32_bf16 v[44:47], v[164:167], v[172:175], v[44:47]
	v_mfma_f32_16x16x32_bf16 v[36:39], v[156:159], v[184:187], v[36:39]
	v_mfma_f32_16x16x32_bf16 v[28:31], v[164:167], v[184:187], v[28:31]
	v_mfma_f32_16x16x32_bf16 v[20:23], v[156:159], v[204:207], v[20:23]
	v_mfma_f32_16x16x32_bf16 v[12:15], v[164:167], v[204:207], v[12:15]
	v_mfma_f32_16x16x32_bf16 v[4:7], v[156:159], v[222:225], v[4:7]
	v_mfma_f32_16x16x32_bf16 v[0:3], v[164:167], v[222:225], v[0:3]
	v_mfma_f32_16x16x32_bf16 v[52:55], v[160:163], v[176:179], v[52:55]
	v_mfma_f32_16x16x32_bf16 v[44:47], v[168:171], v[176:179], v[44:47]
	v_mfma_f32_16x16x32_bf16 v[36:39], v[160:163], v[200:203], v[36:39]
	v_mfma_f32_16x16x32_bf16 v[28:31], v[168:171], v[200:203], v[28:31]
	v_mfma_f32_16x16x32_bf16 v[20:23], v[160:163], v[208:211], v[20:23]
	v_mfma_f32_16x16x32_bf16 v[12:15], v[168:171], v[208:211], v[12:15]
	v_mfma_f32_16x16x32_bf16 v[4:7], v[160:163], v[226:229], v[4:7]
	v_mfma_f32_16x16x32_bf16 v[0:3], v[168:171], v[226:229], v[0:3]
	s_setprio 0
	s_barrier
	s_add_i32 s60, s60, 2
	s_add_u32 s54, s54, 0x100
	s_addc_u32 s55, s55, 0
	s_add_u32 s57, s57, 0x100
	s_addc_u32 s58, s58, 0
	s_cmp_gt_u32 s60, 61
	s_cbranch_scc0 .LBB0_760
	s_and_b64 vcc, exec, s[38:39]
	s_cbranch_vccz .LBB0_763
	s_barrier
